# v40 + residual epilogue vmcnt waits relaxed by one (each region issues exactly 8 unconditional stores, compiler assumed 7)
# speedup vs baseline: 1.0051x; 1.0051x over previous
; #define LAS __attribute__((address_space(3)))
; #define ERN_EOFF(q, m) (eb + (unsigned)((((q) & 1) * HALF + (m) * 16) * DM + ERN_COL((q) >> 1)))
;     __device__ __forceinline__ void operator()(const f32x4 (&acc)[2][2][4][2], const Unit& u, int wr, int wc, int fr, int fq) const {
;     ...
;         for (int g = 0; g < 8; ++g) { const int ai = g >> 2, m = g & 3;
;             if (g + 1 < 8) ERN_LOADX(g + 1);
;             float sq0 = 0.f, sq1 = 0.f; u32x2 hw[2][2];
; #pragma unroll
;             for (int bj = 0; bj < 2; ++bj) {
;                 *(LAS f32x4*)(st + wr_off) = acc[ai][bj][m][0]; *(LAS f32x4*)(st + wr_off + 64) = acc[ai][bj][m][1];
;                 const f32x4 a0 = *(const LAS f32x4*)(st + rd_off), a1 = *(const LAS f32x4*)(st + rd_off + 8 * 144);
;                 { const f32x4 xv = xb[g & 1][bj][0] + gv[bj] * a0; __builtin_nontemporal_store(xv, (f32x4*)((char*)xo + 4u * ERN_EOFF(g, bj, 0)));
;                   sq0 += (xv.x * xv.x + xv.y * xv.y) + (xv.z * xv.z + xv.w * xv.w);
;                   const f32x4 hv = xv * gsn[bj]; hw[bj][0].x = cvt_pk_bf16(hv.x, hv.y); hw[bj][0].y = cvt_pk_bf16(hv.z, hv.w); }
;                 { const f32x4 xv = xb[g & 1][bj][1] + gv[bj] * a1; __builtin_nontemporal_store(xv, (f32x4*)((char*)xo + 4u * ERN_EOFF(g, bj, 1)));
;                   sq1 += (xv.x * xv.x + xv.y * xv.y) + (xv.z * xv.z + xv.w * xv.w);
;                   const f32x4 hv = xv * gsn[bj]; hw[bj][1].x = cvt_pk_bf16(hv.x, hv.y); hw[bj][1].y = cvt_pk_bf16(hv.z, hv.w); }
;             }
;             if (!NOH && !PLAIN) {
; #pragma unroll
;                 for (int rh = 0; rh < 2; ++rh) { u32x2 rv; rv.x = __shfl_xor(hw[1][rh].x, 8); rv.y = __shfl_xor(hw[1][rh].y, 8);
;                     const unsigned e0 = ERN_EOFF(g, 0, rh);
;                     const unsigned ee = odd ? (e0 - DM + 32) : e0, eo2 = odd ? e0 : (e0 + DM + 32);
;                     *(u32x2*)((char*)ho + 2u * ee) = odd ? rv : hw[0][rh];
;                     *(u32x2*)((char*)ho + 2u * eo2) = odd ? hw[0][rh] : rv; }
;             }
;             if (!PLAIN) { sq0 += __shfl_xor(sq0, 1); sq0 += __shfl_xor(sq0, 2); sq0 += __shfl_xor(sq0, 4);
;             sq1 += __shfl_xor(sq1, 1); sq1 += __shfl_xor(sq1, 2); sq1 += __shfl_xor(sq1, 4); }
;             if (!PLAIN && pc == 0) { sst[g * 16 + rr] = sq0; sst[g * 16 + 8 + rr] = sq1; }
.LBB0_340:
	s_or_b64 exec, exec, s[16:17]
	v_add_u32_e32 v98, 0x60000, v207
	v_add_u32_e32 v154, 0x70000, v207
	v_add_u32_e32 v132, 0x60080, v207
	global_load_dwordx4 v[106:109], v154, s[58:59]
	global_load_dwordx4 v[102:105], v132, s[58:59]
	v_add_u32_e32 v130, 0x70080, v207
	global_load_dwordx4 v[110:113], v98, s[58:59]
	s_waitcnt lgkmcnt(0)
	global_load_dwordx4 v[98:101], v130, s[58:59]
	ds_write_b128 v200, v[94:97]
	ds_write_b128 v200, v[90:93] offset:64
	ds_read_b128 v[90:93], v201
	ds_read_b128 v[94:97], v201 offset:1152
	v_mov_b32_e32 v191, v155
	v_mov_b32_e32 v189, v155
	v_mov_b32_e32 v187, v155
	s_waitcnt vmcnt(12) lgkmcnt(1)
	v_pk_fma_f32 v[92:93], v[178:179], v[92:93], v[128:129]
	v_add_u32_e32 v128, 0x10000, v202
	v_pk_fma_f32 v[90:91], v[180:181], v[90:91], v[126:127]
	v_lshlrev_b32_e32 v126, 2, v128
	global_store_dwordx4 v126, v[90:93], s[56:57] nt
	v_pk_mul_f32 v[126:127], v[176:177], v[90:91]
	s_waitcnt lgkmcnt(0)
	v_pk_fma_f32 v[96:97], v[178:179], v[96:97], v[124:125]
	v_pk_fma_f32 v[94:95], v[180:181], v[94:95], v[122:123]
	v_lshl_add_u64 v[122:123], s[56:57], 0, v[190:191]
	v_pk_mul_f32 v[134:135], v[174:175], v[92:93]
	v_cvt_pk_bf16_f32 v126, v126, v127
	v_pk_mul_f32 v[124:125], v[174:175], v[96:97]
	v_cvt_pk_bf16_f32 v127, v134, v135
	global_store_dwordx4 v[122:123], v[94:97], off nt
	v_pk_mul_f32 v[122:123], v[176:177], v[94:95]
	s_nop 0
	v_cvt_pk_bf16_f32 v122, v122, v123
	v_cvt_pk_bf16_f32 v123, v124, v125
	ds_write_b128 v200, v[86:89]
	ds_write_b128 v200, v[82:85] offset:64
	ds_read_b128 v[82:85], v201
	ds_read_b128 v[86:89], v201 offset:1152
	s_waitcnt lgkmcnt(1)
	v_pk_fma_f32 v[82:83], v[168:169], v[82:83], v[118:119]
	v_pk_fma_f32 v[84:85], v[166:167], v[84:85], v[120:121]
	v_lshl_add_u64 v[118:119], s[56:57], 0, v[188:189]
	v_pk_mul_f32 v[120:121], v[172:173], v[82:83]
	s_waitcnt vmcnt(13) lgkmcnt(0)
	v_pk_fma_f32 v[88:89], v[166:167], v[88:89], v[116:117]
	v_pk_fma_f32 v[86:87], v[168:169], v[86:87], v[114:115]
	v_lshl_add_u64 v[114:115], s[56:57], 0, v[186:187]
	global_store_dwordx4 v[118:119], v[82:85], off nt
	v_pk_mul_f32 v[118:119], v[170:171], v[84:85]
	v_cvt_pk_bf16_f32 v120, v120, v121
	v_pk_mul_f32 v[116:117], v[172:173], v[86:87]
	v_cvt_pk_bf16_f32 v121, v118, v119
	global_store_dwordx4 v[114:115], v[86:89], off nt
	ds_bpermute_b32 v114, v203, v120
	ds_bpermute_b32 v115, v203, v121
	v_pk_mul_f32 v[118:119], v[170:171], v[88:89]
	v_cvt_pk_bf16_f32 v116, v116, v117
	s_nop 0
	v_cvt_pk_bf16_f32 v117, v118, v119
	v_lshlrev_b32_e32 v118, 1, v128
	s_waitcnt lgkmcnt(0)
	v_add_u32_e32 v250, 0xfffff040, v118
	v_cndmask_b32_e64 v250, v118, v250, s[40:41]
	v_cndmask_b32_e64 v248, v126, v114, s[40:41]
	v_cndmask_b32_e64 v249, v127, v115, s[40:41]
	global_store_dwordx2 v250, v[248:249], s[54:55]
	v_cndmask_b32_e64 v246, v114, v126, s[40:41]
	v_cndmask_b32_e64 v247, v115, v127, s[40:41]
	s_waitcnt lgkmcnt(1)
	v_add_u32_e32 v114, 0x1040, v118
	v_cndmask_b32_e64 v114, v118, v114, s[38:39]
	global_store_dwordx2 v114, v[246:247], s[54:55]
	ds_bpermute_b32 v114, v203, v116
	s_waitcnt lgkmcnt(1)
	ds_bpermute_b32 v115, v203, v117
	v_add_u32_e32 v117, 0x14000, v202
	v_lshlrev_b32_e32 v116, 1, v117
	s_waitcnt lgkmcnt(0)
	v_add_u32_e32 v250, 0xfffff040, v116
	v_cndmask_b32_e64 v250, v116, v250, s[40:41]
	v_cndmask_b32_e64 v248, v122, v114, s[40:41]
	v_cndmask_b32_e64 v249, v123, v115, s[40:41]
	global_store_dwordx2 v250, v[248:249], s[54:55]
	v_cndmask_b32_e64 v246, v114, v122, s[40:41]
	v_cndmask_b32_e64 v247, v115, v123, s[40:41]
	v_mul_f32_e32 v83, v83, v83
	v_fmac_f32_e32 v83, v82, v82
	v_mul_f32_e32 v82, v85, v85
	v_mul_f32_e32 v93, v93, v93
	v_fmac_f32_e32 v82, v84, v84
	v_mul_f32_e32 v91, v91, v91
	v_fmac_f32_e32 v93, v92, v92
	v_mul_f32_e32 v92, v95, v95
	v_mul_f32_e32 v95, v97, v97
	v_add_f32_e32 v82, v83, v82
	v_mul_f32_e32 v83, v87, v87
	v_mul_f32_e32 v84, v89, v89
	v_fmac_f32_e32 v95, v96, v96
	v_fmac_f32_e32 v83, v86, v86
	v_fmac_f32_e32 v84, v88, v88
	v_fmac_f32_e32 v91, v90, v90
	v_fmac_f32_e32 v92, v94, v94
	v_add_f32_e32 v83, v83, v84
	v_add_f32_e32 v84, v91, v93
	v_add_f32_e32 v85, v92, v95
	v_add_f32_e32 v82, v84, v82
	v_add_f32_e32 v83, v85, v83
	ds_bpermute_b32 v84, v204, v82
	ds_bpermute_b32 v85, v204, v83
	s_waitcnt lgkmcnt(1)
	v_add_f32_e32 v82, v82, v84
	s_waitcnt lgkmcnt(0)
	v_add_f32_e32 v85, v83, v85
	ds_bpermute_b32 v84, v205, v82
	ds_bpermute_b32 v86, v205, v85
	s_waitcnt lgkmcnt(1)
	v_add_f32_e32 v82, v82, v84
	s_waitcnt lgkmcnt(0)
	v_add_f32_e32 v84, v85, v86
	ds_bpermute_b32 v83, v206, v82
	ds_bpermute_b32 v85, v206, v84
	v_add_u32_e32 v86, 0x1040, v116
	v_cndmask_b32_e64 v86, v116, v86, s[38:39]
	global_store_dwordx2 v86, v[246:247], s[54:55]
	s_and_saveexec_b64 s[16:17], s[42:43]
	s_cbranch_execz .LBB0_350
	s_waitcnt lgkmcnt(1)
	v_add_f32_e32 v82, v82, v83
	s_waitcnt lgkmcnt(0)
	v_add_f32_e32 v83, v84, v85
	ds_write2_b32 v194, v82, v83 offset0:32 offset1:40
; #define LAS __attribute__((address_space(3)))
; #define ERN_EOFF(q, m) (eb + (unsigned)((((q) & 1) * HALF + (m) * 16) * DM + ERN_COL((q) >> 1)))
;     __device__ __forceinline__ void operator()(const f32x4 (&acc)[2][2][4][2], const Unit& u, int wr, int wc, int fr, int fq) const {
;     ...
;         for (int g = 0; g < 8; ++g) { const int ai = g >> 2, m = g & 3;
;             if (g + 1 < 8) ERN_LOADX(g + 1);
;             float sq0 = 0.f, sq1 = 0.f; u32x2 hw[2][2];
; #pragma unroll
;             for (int bj = 0; bj < 2; ++bj) {
;                 *(LAS f32x4*)(st + wr_off) = acc[ai][bj][m][0]; *(LAS f32x4*)(st + wr_off + 64) = acc[ai][bj][m][1];
;                 const f32x4 a0 = *(const LAS f32x4*)(st + rd_off), a1 = *(const LAS f32x4*)(st + rd_off + 8 * 144);
;                 { const f32x4 xv = xb[g & 1][bj][0] + gv[bj] * a0; __builtin_nontemporal_store(xv, (f32x4*)((char*)xo + 4u * ERN_EOFF(g, bj, 0)));
;                   sq0 += (xv.x * xv.x + xv.y * xv.y) + (xv.z * xv.z + xv.w * xv.w);
;                   const f32x4 hv = xv * gsn[bj]; hw[bj][0].x = cvt_pk_bf16(hv.x, hv.y); hw[bj][0].y = cvt_pk_bf16(hv.z, hv.w); }
;                 { const f32x4 xv = xb[g & 1][bj][1] + gv[bj] * a1; __builtin_nontemporal_store(xv, (f32x4*)((char*)xo + 4u * ERN_EOFF(g, bj, 1)));
;                   sq1 += (xv.x * xv.x + xv.y * xv.y) + (xv.z * xv.z + xv.w * xv.w);
;                   const f32x4 hv = xv * gsn[bj]; hw[bj][1].x = cvt_pk_bf16(hv.x, hv.y); hw[bj][1].y = cvt_pk_bf16(hv.z, hv.w); }
;             }
;             if (!NOH && !PLAIN) {
; #pragma unroll
;                 for (int rh = 0; rh < 2; ++rh) { u32x2 rv; rv.x = __shfl_xor(hw[1][rh].x, 8); rv.y = __shfl_xor(hw[1][rh].y, 8);
;                     const unsigned e0 = ERN_EOFF(g, 0, rh);
;                     const unsigned ee = odd ? (e0 - DM + 32) : e0, eo2 = odd ? e0 : (e0 + DM + 32);
;                     *(u32x2*)((char*)ho + 2u * ee) = odd ? rv : hw[0][rh];
;                     *(u32x2*)((char*)ho + 2u * eo2) = odd ? hw[0][rh] : rv; }
;             }
;             if (!PLAIN) { sq0 += __shfl_xor(sq0, 1); sq0 += __shfl_xor(sq0, 2); sq0 += __shfl_xor(sq0, 4);
;             sq1 += __shfl_xor(sq1, 1); sq1 += __shfl_xor(sq1, 2); sq1 += __shfl_xor(sq1, 4); }
;             if (!PLAIN && pc == 0) { sst[g * 16 + rr] = sq0; sst[g * 16 + 8 + rr] = sq1; }
.LBB0_350:
	s_or_b64 exec, exec, s[16:17]
	v_add_u32_e32 v82, 0x100000, v207
	s_waitcnt lgkmcnt(1)
	v_add_u32_e32 v83, 0x110000, v207
	v_add_u32_e32 v116, 0x100080, v207
	global_load_dwordx4 v[94:97], v82, s[58:59]
	global_load_dwordx4 v[90:93], v83, s[58:59]
	v_add_u32_e32 v114, 0x110080, v207
	global_load_dwordx4 v[86:89], v116, s[58:59]
	s_waitcnt lgkmcnt(0)
	global_load_dwordx4 v[82:85], v114, s[58:59]
	ds_write_b128 v200, v[78:81]
	ds_write_b128 v200, v[74:77] offset:64
	ds_read_b128 v[74:77], v201
	ds_read_b128 v[78:81], v201 offset:1152
	v_mov_b32_e32 v133, v155
	v_mov_b32_e32 v131, v155
	s_waitcnt vmcnt(12) lgkmcnt(1)
	v_pk_fma_f32 v[76:77], v[178:179], v[76:77], v[112:113]
	v_add_u32_e32 v112, 0x18000, v202
	v_pk_fma_f32 v[74:75], v[180:181], v[74:75], v[110:111]
	v_lshlrev_b32_e32 v110, 2, v112
	global_store_dwordx4 v110, v[74:77], s[56:57] nt
	v_pk_mul_f32 v[110:111], v[176:177], v[74:75]
	s_waitcnt lgkmcnt(0)
	v_pk_fma_f32 v[80:81], v[178:179], v[80:81], v[108:109]
	v_pk_fma_f32 v[78:79], v[180:181], v[78:79], v[106:107]
	v_lshl_add_u64 v[106:107], s[56:57], 0, v[154:155]
	v_pk_mul_f32 v[118:119], v[174:175], v[76:77]
	v_cvt_pk_bf16_f32 v110, v110, v111
	v_pk_mul_f32 v[108:109], v[174:175], v[80:81]
	v_cvt_pk_bf16_f32 v111, v118, v119
	global_store_dwordx4 v[106:107], v[78:81], off nt
	v_pk_mul_f32 v[106:107], v[176:177], v[78:79]
	s_nop 0
	v_cvt_pk_bf16_f32 v106, v106, v107
	v_cvt_pk_bf16_f32 v107, v108, v109
	ds_write_b128 v200, v[70:73]
	ds_write_b128 v200, v[66:69] offset:64
	ds_read_b128 v[66:69], v201
	ds_read_b128 v[70:73], v201 offset:1152
	s_waitcnt lgkmcnt(1)
	v_pk_fma_f32 v[66:67], v[168:169], v[66:67], v[102:103]
	v_pk_fma_f32 v[68:69], v[166:167], v[68:69], v[104:105]
	v_lshl_add_u64 v[102:103], s[56:57], 0, v[132:133]
	v_pk_mul_f32 v[104:105], v[172:173], v[66:67]
	s_waitcnt vmcnt(13) lgkmcnt(0)
	v_pk_fma_f32 v[72:73], v[166:167], v[72:73], v[100:101]
	v_pk_fma_f32 v[70:71], v[168:169], v[70:71], v[98:99]
	v_lshl_add_u64 v[98:99], s[56:57], 0, v[130:131]
	global_store_dwordx4 v[102:103], v[66:69], off nt
	v_pk_mul_f32 v[102:103], v[170:171], v[68:69]
	v_cvt_pk_bf16_f32 v104, v104, v105
	v_pk_mul_f32 v[100:101], v[172:173], v[70:71]
	v_cvt_pk_bf16_f32 v105, v102, v103
	global_store_dwordx4 v[98:99], v[70:73], off nt
	ds_bpermute_b32 v98, v203, v104
	ds_bpermute_b32 v99, v203, v105
	v_pk_mul_f32 v[102:103], v[170:171], v[72:73]
	v_cvt_pk_bf16_f32 v100, v100, v101
	s_nop 0
	v_cvt_pk_bf16_f32 v101, v102, v103
	v_lshlrev_b32_e32 v102, 1, v112
	s_waitcnt lgkmcnt(0)
	v_add_u32_e32 v250, 0xfffff040, v102
	v_cndmask_b32_e64 v250, v102, v250, s[40:41]
	v_cndmask_b32_e64 v248, v110, v98, s[40:41]
	v_cndmask_b32_e64 v249, v111, v99, s[40:41]
	global_store_dwordx2 v250, v[248:249], s[54:55]
	v_cndmask_b32_e64 v246, v98, v110, s[40:41]
	v_cndmask_b32_e64 v247, v99, v111, s[40:41]
	s_waitcnt lgkmcnt(1)
	v_add_u32_e32 v98, 0x1040, v102
	v_cndmask_b32_e64 v98, v102, v98, s[38:39]
	global_store_dwordx2 v98, v[246:247], s[54:55]
	ds_bpermute_b32 v98, v203, v100
	s_waitcnt lgkmcnt(1)
	ds_bpermute_b32 v99, v203, v101
	v_add_u32_e32 v101, 0x1c000, v202
	v_lshlrev_b32_e32 v100, 1, v101
	s_waitcnt lgkmcnt(0)
	v_add_u32_e32 v250, 0xfffff040, v100
	v_cndmask_b32_e64 v250, v100, v250, s[40:41]
	v_cndmask_b32_e64 v248, v106, v98, s[40:41]
	v_cndmask_b32_e64 v249, v107, v99, s[40:41]
	global_store_dwordx2 v250, v[248:249], s[54:55]
	v_cndmask_b32_e64 v246, v98, v106, s[40:41]
	v_cndmask_b32_e64 v247, v99, v107, s[40:41]
	v_mul_f32_e32 v67, v67, v67
	v_fmac_f32_e32 v67, v66, v66
	v_mul_f32_e32 v66, v69, v69
	v_mul_f32_e32 v77, v77, v77
	v_fmac_f32_e32 v66, v68, v68
	v_mul_f32_e32 v75, v75, v75
	v_fmac_f32_e32 v77, v76, v76
	v_mul_f32_e32 v76, v79, v79
	v_mul_f32_e32 v79, v81, v81
	v_add_f32_e32 v66, v67, v66
	v_mul_f32_e32 v67, v71, v71
	v_mul_f32_e32 v68, v73, v73
	v_fmac_f32_e32 v79, v80, v80
	v_fmac_f32_e32 v67, v70, v70
	v_fmac_f32_e32 v68, v72, v72
	v_fmac_f32_e32 v75, v74, v74
	v_fmac_f32_e32 v76, v78, v78
	v_add_f32_e32 v67, v67, v68
	v_add_f32_e32 v68, v75, v77
	v_add_f32_e32 v69, v76, v79
	v_add_f32_e32 v66, v68, v66
	v_add_f32_e32 v67, v69, v67
	ds_bpermute_b32 v68, v204, v66
	ds_bpermute_b32 v69, v204, v67
	s_waitcnt lgkmcnt(1)
	v_add_f32_e32 v66, v66, v68
	s_waitcnt lgkmcnt(0)
	v_add_f32_e32 v69, v67, v69
	ds_bpermute_b32 v68, v205, v66
	ds_bpermute_b32 v70, v205, v69
	s_waitcnt lgkmcnt(1)
	v_add_f32_e32 v66, v66, v68
	s_waitcnt lgkmcnt(0)
	v_add_f32_e32 v68, v69, v70
	ds_bpermute_b32 v67, v206, v66
	ds_bpermute_b32 v69, v206, v68
	v_add_u32_e32 v70, 0x1040, v100
	v_cndmask_b32_e64 v70, v100, v70, s[38:39]
	global_store_dwordx2 v70, v[246:247], s[54:55]
	s_and_saveexec_b64 s[16:17], s[42:43]
	s_cbranch_execz .LBB0_360
	s_waitcnt lgkmcnt(1)
	v_add_f32_e32 v66, v66, v67
	s_waitcnt lgkmcnt(0)
	v_add_f32_e32 v67, v68, v69
	ds_write2_b32 v194, v66, v67 offset0:48 offset1:56
; #define LAS __attribute__((address_space(3)))
; #define ERN_EOFF(q, m) (eb + (unsigned)((((q) & 1) * HALF + (m) * 16) * DM + ERN_COL((q) >> 1)))
;     __device__ __forceinline__ void operator()(const f32x4 (&acc)[2][2][4][2], const Unit& u, int wr, int wc, int fr, int fq) const {
;     ...
;         for (int g = 0; g < 8; ++g) { const int ai = g >> 2, m = g & 3;
;             if (g + 1 < 8) ERN_LOADX(g + 1);
;             float sq0 = 0.f, sq1 = 0.f; u32x2 hw[2][2];
; #pragma unroll
;             for (int bj = 0; bj < 2; ++bj) {
;                 *(LAS f32x4*)(st + wr_off) = acc[ai][bj][m][0]; *(LAS f32x4*)(st + wr_off + 64) = acc[ai][bj][m][1];
;                 const f32x4 a0 = *(const LAS f32x4*)(st + rd_off), a1 = *(const LAS f32x4*)(st + rd_off + 8 * 144);
;                 { const f32x4 xv = xb[g & 1][bj][0] + gv[bj] * a0; __builtin_nontemporal_store(xv, (f32x4*)((char*)xo + 4u * ERN_EOFF(g, bj, 0)));
;                   sq0 += (xv.x * xv.x + xv.y * xv.y) + (xv.z * xv.z + xv.w * xv.w);
;                   const f32x4 hv = xv * gsn[bj]; hw[bj][0].x = cvt_pk_bf16(hv.x, hv.y); hw[bj][0].y = cvt_pk_bf16(hv.z, hv.w); }
;                 { const f32x4 xv = xb[g & 1][bj][1] + gv[bj] * a1; __builtin_nontemporal_store(xv, (f32x4*)((char*)xo + 4u * ERN_EOFF(g, bj, 1)));
;                   sq1 += (xv.x * xv.x + xv.y * xv.y) + (xv.z * xv.z + xv.w * xv.w);
;                   const f32x4 hv = xv * gsn[bj]; hw[bj][1].x = cvt_pk_bf16(hv.x, hv.y); hw[bj][1].y = cvt_pk_bf16(hv.z, hv.w); }
;             }
;             if (!NOH && !PLAIN) {
; #pragma unroll
;                 for (int rh = 0; rh < 2; ++rh) { u32x2 rv; rv.x = __shfl_xor(hw[1][rh].x, 8); rv.y = __shfl_xor(hw[1][rh].y, 8);
;                     const unsigned e0 = ERN_EOFF(g, 0, rh);
;                     const unsigned ee = odd ? (e0 - DM + 32) : e0, eo2 = odd ? e0 : (e0 + DM + 32);
;                     *(u32x2*)((char*)ho + 2u * ee) = odd ? rv : hw[0][rh];
;                     *(u32x2*)((char*)ho + 2u * eo2) = odd ? hw[0][rh] : rv; }
;             }
;             if (!PLAIN) { sq0 += __shfl_xor(sq0, 1); sq0 += __shfl_xor(sq0, 2); sq0 += __shfl_xor(sq0, 4);
;             sq1 += __shfl_xor(sq1, 1); sq1 += __shfl_xor(sq1, 2); sq1 += __shfl_xor(sq1, 4); }
;             if (!PLAIN && pc == 0) { sst[g * 16 + rr] = sq0; sst[g * 16 + 8 + rr] = sq1; }
.LBB0_360:
	s_or_b64 exec, exec, s[16:17]
	v_add_u32_e32 v154, 0x120000, v207
	v_add_u32_e32 v100, 0x120080, v207
	v_add_u32_e32 v102, 0x130000, v207
	global_load_dwordx4 v[78:81], v154, s[58:59]
	global_load_dwordx4 v[74:77], v102, s[58:59]
	v_add_u32_e32 v98, 0x130080, v207
	global_load_dwordx4 v[70:73], v100, s[58:59]
	s_waitcnt lgkmcnt(0)
	global_load_dwordx4 v[66:69], v98, s[58:59]
	ds_write_b128 v200, v[62:65]
	ds_write_b128 v200, v[58:61] offset:64
	ds_read_b128 v[58:61], v201
	ds_read_b128 v[62:65], v201 offset:1152
	v_mov_b32_e32 v117, v155
	v_mov_b32_e32 v115, v155
	s_waitcnt vmcnt(14) lgkmcnt(1)
	v_pk_fma_f32 v[60:61], v[178:179], v[60:61], v[96:97]
	v_add_u32_e32 v96, 0x40000, v202
	v_pk_fma_f32 v[58:59], v[180:181], v[58:59], v[94:95]
	v_lshlrev_b32_e32 v94, 2, v96
	s_waitcnt vmcnt(13) lgkmcnt(0)
	v_pk_fma_f32 v[64:65], v[178:179], v[64:65], v[92:93]
	v_add_u32_e32 v92, 0x44000, v202
	global_store_dwordx4 v94, v[58:61], s[56:57] nt
	v_pk_mul_f32 v[94:95], v[176:177], v[58:59]
	v_pk_fma_f32 v[62:63], v[180:181], v[62:63], v[90:91]
	v_lshlrev_b32_e32 v90, 2, v92
	v_pk_mul_f32 v[104:105], v[174:175], v[60:61]
	v_cvt_pk_bf16_f32 v94, v94, v95
	s_nop 0
	v_cvt_pk_bf16_f32 v95, v104, v105
	global_store_dwordx4 v90, v[62:65], s[56:57] nt
	v_pk_mul_f32 v[90:91], v[176:177], v[62:63]
	v_pk_mul_f32 v[104:105], v[174:175], v[64:65]
	v_cvt_pk_bf16_f32 v90, v90, v91
	s_nop 0
	v_cvt_pk_bf16_f32 v91, v104, v105
	ds_write_b128 v200, v[54:57]
	ds_write_b128 v200, v[50:53] offset:64
	ds_read_b128 v[50:53], v201
	ds_read_b128 v[54:57], v201 offset:1152
	s_waitcnt vmcnt(14) lgkmcnt(1)
	v_pk_fma_f32 v[50:51], v[168:169], v[50:51], v[86:87]
	v_pk_fma_f32 v[52:53], v[166:167], v[52:53], v[88:89]
	v_lshl_add_u64 v[86:87], s[56:57], 0, v[116:117]
	v_pk_mul_f32 v[88:89], v[172:173], v[50:51]
	s_waitcnt vmcnt(13) lgkmcnt(0)
	v_pk_fma_f32 v[56:57], v[166:167], v[56:57], v[84:85]
	v_pk_fma_f32 v[54:55], v[168:169], v[54:55], v[82:83]
	v_lshl_add_u64 v[82:83], s[56:57], 0, v[114:115]
	global_store_dwordx4 v[86:87], v[50:53], off nt
	v_pk_mul_f32 v[86:87], v[170:171], v[52:53]
	v_cvt_pk_bf16_f32 v88, v88, v89
	v_pk_mul_f32 v[84:85], v[172:173], v[54:55]
	v_cvt_pk_bf16_f32 v89, v86, v87
	global_store_dwordx4 v[82:83], v[54:57], off nt
	ds_bpermute_b32 v82, v203, v88
	ds_bpermute_b32 v83, v203, v89
	v_pk_mul_f32 v[86:87], v[170:171], v[56:57]
	v_cvt_pk_bf16_f32 v84, v84, v85
	s_nop 0
	v_cvt_pk_bf16_f32 v85, v86, v87
	v_lshlrev_b32_e32 v86, 1, v96
	s_waitcnt lgkmcnt(0)
	v_add_u32_e32 v250, 0xfffff040, v86
	v_cndmask_b32_e64 v250, v86, v250, s[40:41]
	v_cndmask_b32_e64 v248, v94, v82, s[40:41]
	v_cndmask_b32_e64 v249, v95, v83, s[40:41]
	global_store_dwordx2 v250, v[248:249], s[54:55]
	v_cndmask_b32_e64 v246, v82, v94, s[40:41]
	v_cndmask_b32_e64 v247, v83, v95, s[40:41]
	s_waitcnt lgkmcnt(1)
	v_add_u32_e32 v82, 0x1040, v86
	v_cndmask_b32_e64 v82, v86, v82, s[38:39]
	global_store_dwordx2 v82, v[246:247], s[54:55]
	ds_bpermute_b32 v82, v203, v84
	s_waitcnt lgkmcnt(1)
	ds_bpermute_b32 v83, v203, v85
	v_lshlrev_b32_e32 v84, 1, v92
	s_waitcnt lgkmcnt(0)
	v_add_u32_e32 v250, 0xfffff040, v84
	v_cndmask_b32_e64 v250, v84, v250, s[40:41]
	v_cndmask_b32_e64 v248, v90, v82, s[40:41]
	v_cndmask_b32_e64 v249, v91, v83, s[40:41]
	global_store_dwordx2 v250, v[248:249], s[54:55]
	v_cndmask_b32_e64 v246, v82, v90, s[40:41]
	v_cndmask_b32_e64 v247, v83, v91, s[40:41]
	v_mul_f32_e32 v51, v51, v51
	v_fmac_f32_e32 v51, v50, v50
	v_mul_f32_e32 v50, v53, v53
	v_mul_f32_e32 v61, v61, v61
	v_fmac_f32_e32 v50, v52, v52
	v_mul_f32_e32 v59, v59, v59
	v_fmac_f32_e32 v61, v60, v60
	v_mul_f32_e32 v60, v63, v63
	v_mul_f32_e32 v63, v65, v65
	v_add_f32_e32 v50, v51, v50
	v_mul_f32_e32 v51, v55, v55
	v_mul_f32_e32 v52, v57, v57
	v_fmac_f32_e32 v63, v64, v64
	v_fmac_f32_e32 v51, v54, v54
	v_fmac_f32_e32 v52, v56, v56
	v_fmac_f32_e32 v59, v58, v58
	v_fmac_f32_e32 v60, v62, v62
	v_add_f32_e32 v51, v51, v52
	v_add_f32_e32 v52, v59, v61
	v_add_f32_e32 v53, v60, v63
	v_add_f32_e32 v50, v52, v50
	v_add_f32_e32 v51, v53, v51
	ds_bpermute_b32 v52, v204, v50
	ds_bpermute_b32 v53, v204, v51
	s_waitcnt lgkmcnt(1)
	v_add_f32_e32 v50, v50, v52
	s_waitcnt lgkmcnt(0)
	v_add_f32_e32 v53, v51, v53
	ds_bpermute_b32 v52, v205, v50
	ds_bpermute_b32 v54, v205, v53
	s_waitcnt lgkmcnt(1)
	v_add_f32_e32 v50, v50, v52
	s_waitcnt lgkmcnt(0)
	v_add_f32_e32 v52, v53, v54
	ds_bpermute_b32 v51, v206, v50
	ds_bpermute_b32 v53, v206, v52
	v_add_u32_e32 v54, 0x1040, v84
	v_cndmask_b32_e64 v54, v84, v54, s[38:39]
	global_store_dwordx2 v54, v[246:247], s[54:55]
	s_and_saveexec_b64 s[16:17], s[42:43]
	s_cbranch_execz .LBB0_370
	s_waitcnt lgkmcnt(1)
	v_add_f32_e32 v50, v50, v51
	s_waitcnt lgkmcnt(0)
	v_add_f32_e32 v51, v52, v53
	ds_write2_b32 v194, v50, v51 offset0:64 offset1:72
; #define LAS __attribute__((address_space(3)))
; #define ERN_EOFF(q, m) (eb + (unsigned)((((q) & 1) * HALF + (m) * 16) * DM + ERN_COL((q) >> 1)))
;     __device__ __forceinline__ void operator()(const f32x4 (&acc)[2][2][4][2], const Unit& u, int wr, int wc, int fr, int fq) const {
;     ...
;         for (int g = 0; g < 8; ++g) { const int ai = g >> 2, m = g & 3;
;             if (g + 1 < 8) ERN_LOADX(g + 1);
;             float sq0 = 0.f, sq1 = 0.f; u32x2 hw[2][2];
; #pragma unroll
;             for (int bj = 0; bj < 2; ++bj) {
;                 *(LAS f32x4*)(st + wr_off) = acc[ai][bj][m][0]; *(LAS f32x4*)(st + wr_off + 64) = acc[ai][bj][m][1];
;                 const f32x4 a0 = *(const LAS f32x4*)(st + rd_off), a1 = *(const LAS f32x4*)(st + rd_off + 8 * 144);
;                 { const f32x4 xv = xb[g & 1][bj][0] + gv[bj] * a0; __builtin_nontemporal_store(xv, (f32x4*)((char*)xo + 4u * ERN_EOFF(g, bj, 0)));
;                   sq0 += (xv.x * xv.x + xv.y * xv.y) + (xv.z * xv.z + xv.w * xv.w);
;                   const f32x4 hv = xv * gsn[bj]; hw[bj][0].x = cvt_pk_bf16(hv.x, hv.y); hw[bj][0].y = cvt_pk_bf16(hv.z, hv.w); }
;                 { const f32x4 xv = xb[g & 1][bj][1] + gv[bj] * a1; __builtin_nontemporal_store(xv, (f32x4*)((char*)xo + 4u * ERN_EOFF(g, bj, 1)));
;                   sq1 += (xv.x * xv.x + xv.y * xv.y) + (xv.z * xv.z + xv.w * xv.w);
;                   const f32x4 hv = xv * gsn[bj]; hw[bj][1].x = cvt_pk_bf16(hv.x, hv.y); hw[bj][1].y = cvt_pk_bf16(hv.z, hv.w); }
;             }
;             if (!NOH && !PLAIN) {
; #pragma unroll
;                 for (int rh = 0; rh < 2; ++rh) { u32x2 rv; rv.x = __shfl_xor(hw[1][rh].x, 8); rv.y = __shfl_xor(hw[1][rh].y, 8);
;                     const unsigned e0 = ERN_EOFF(g, 0, rh);
;                     const unsigned ee = odd ? (e0 - DM + 32) : e0, eo2 = odd ? e0 : (e0 + DM + 32);
;                     *(u32x2*)((char*)ho + 2u * ee) = odd ? rv : hw[0][rh];
;                     *(u32x2*)((char*)ho + 2u * eo2) = odd ? hw[0][rh] : rv; }
;             }
;             if (!PLAIN) { sq0 += __shfl_xor(sq0, 1); sq0 += __shfl_xor(sq0, 2); sq0 += __shfl_xor(sq0, 4);
;             sq1 += __shfl_xor(sq1, 1); sq1 += __shfl_xor(sq1, 2); sq1 += __shfl_xor(sq1, 4); }
;             if (!PLAIN && pc == 0) { sst[g * 16 + rr] = sq0; sst[g * 16 + 8 + rr] = sq1; }
.LBB0_370:
	s_or_b64 exec, exec, s[16:17]
	v_add_u32_e32 v88, 0x140000, v207
	v_add_u32_e32 v84, 0x140080, v207
	v_add_u32_e32 v86, 0x150000, v207
	global_load_dwordx4 v[62:65], v88, s[58:59]
	global_load_dwordx4 v[58:61], v86, s[58:59]
	v_add_u32_e32 v82, 0x150080, v207
	global_load_dwordx4 v[54:57], v84, s[58:59]
	s_waitcnt lgkmcnt(0)
	global_load_dwordx4 v[50:53], v82, s[58:59]
	ds_write_b128 v200, v[46:49]
	ds_write_b128 v200, v[42:45] offset:64
	ds_read_b128 v[42:45], v201
	ds_read_b128 v[46:49], v201 offset:1152
	v_mov_b32_e32 v103, v155
	v_mov_b32_e32 v101, v155
	v_mov_b32_e32 v99, v155
	s_waitcnt vmcnt(14) lgkmcnt(1)
	v_pk_fma_f32 v[44:45], v[178:179], v[44:45], v[80:81]
	v_pk_fma_f32 v[42:43], v[180:181], v[42:43], v[78:79]
	v_lshl_add_u64 v[78:79], s[56:57], 0, v[154:155]
	global_store_dwordx4 v[78:79], v[42:45], off nt
	v_pk_mul_f32 v[78:79], v[176:177], v[42:43]
	s_waitcnt vmcnt(14) lgkmcnt(0)
	v_pk_fma_f32 v[48:49], v[178:179], v[48:49], v[76:77]
	v_pk_fma_f32 v[46:47], v[180:181], v[46:47], v[74:75]
	v_lshl_add_u64 v[74:75], s[56:57], 0, v[102:103]
	v_pk_mul_f32 v[80:81], v[174:175], v[44:45]
	v_cvt_pk_bf16_f32 v78, v78, v79
	v_pk_mul_f32 v[76:77], v[174:175], v[48:49]
	v_cvt_pk_bf16_f32 v79, v80, v81
	global_store_dwordx4 v[74:75], v[46:49], off nt
	v_pk_mul_f32 v[74:75], v[176:177], v[46:47]
	s_nop 0
	v_cvt_pk_bf16_f32 v74, v74, v75
	v_cvt_pk_bf16_f32 v75, v76, v77
	ds_write_b128 v200, v[38:41]
	ds_write_b128 v200, v[34:37] offset:64
	ds_read_b128 v[34:37], v201
	ds_read_b128 v[38:41], v201 offset:1152
	s_waitcnt vmcnt(14) lgkmcnt(1)
	v_pk_fma_f32 v[34:35], v[168:169], v[34:35], v[70:71]
	v_pk_fma_f32 v[36:37], v[166:167], v[36:37], v[72:73]
	v_lshl_add_u64 v[70:71], s[56:57], 0, v[100:101]
	v_pk_mul_f32 v[72:73], v[172:173], v[34:35]
	s_waitcnt vmcnt(13) lgkmcnt(0)
	v_pk_fma_f32 v[40:41], v[166:167], v[40:41], v[68:69]
	v_pk_fma_f32 v[38:39], v[168:169], v[38:39], v[66:67]
	v_lshl_add_u64 v[66:67], s[56:57], 0, v[98:99]
	global_store_dwordx4 v[70:71], v[34:37], off nt
	v_pk_mul_f32 v[70:71], v[170:171], v[36:37]
	v_cvt_pk_bf16_f32 v72, v72, v73
	v_pk_mul_f32 v[68:69], v[172:173], v[38:39]
	v_cvt_pk_bf16_f32 v73, v70, v71
	global_store_dwordx4 v[66:67], v[38:41], off nt
	ds_bpermute_b32 v66, v203, v72
	ds_bpermute_b32 v67, v203, v73
	v_pk_mul_f32 v[70:71], v[170:171], v[40:41]
	v_cvt_pk_bf16_f32 v68, v68, v69
	s_nop 0
	v_cvt_pk_bf16_f32 v69, v70, v71
	v_add_u32_e32 v71, 0x48000, v202
	v_lshlrev_b32_e32 v70, 1, v71
	s_waitcnt lgkmcnt(0)
	v_add_u32_e32 v250, 0xfffff040, v70
	v_cndmask_b32_e64 v250, v70, v250, s[40:41]
	v_cndmask_b32_e64 v248, v78, v66, s[40:41]
	v_cndmask_b32_e64 v249, v79, v67, s[40:41]
	global_store_dwordx2 v250, v[248:249], s[54:55]
	v_cndmask_b32_e64 v246, v66, v78, s[40:41]
	v_cndmask_b32_e64 v247, v67, v79, s[40:41]
	s_waitcnt lgkmcnt(1)
	v_add_u32_e32 v66, 0x1040, v70
	v_cndmask_b32_e64 v66, v70, v66, s[38:39]
	global_store_dwordx2 v66, v[246:247], s[54:55]
	ds_bpermute_b32 v66, v203, v68
	s_waitcnt lgkmcnt(1)
	ds_bpermute_b32 v67, v203, v69
	v_add_u32_e32 v69, 0x4c000, v202
	v_lshlrev_b32_e32 v68, 1, v69
	s_waitcnt lgkmcnt(0)
	v_add_u32_e32 v250, 0xfffff040, v68
	v_cndmask_b32_e64 v250, v68, v250, s[40:41]
	v_cndmask_b32_e64 v248, v74, v66, s[40:41]
	v_cndmask_b32_e64 v249, v75, v67, s[40:41]
	global_store_dwordx2 v250, v[248:249], s[54:55]
	v_cndmask_b32_e64 v246, v66, v74, s[40:41]
	v_cndmask_b32_e64 v247, v67, v75, s[40:41]
	v_mul_f32_e32 v35, v35, v35
	v_fmac_f32_e32 v35, v34, v34
	v_mul_f32_e32 v34, v37, v37
	v_mul_f32_e32 v45, v45, v45
	v_fmac_f32_e32 v34, v36, v36
	v_mul_f32_e32 v43, v43, v43
	v_fmac_f32_e32 v45, v44, v44
	v_mul_f32_e32 v44, v47, v47
	v_mul_f32_e32 v47, v49, v49
	v_add_f32_e32 v34, v35, v34
	v_mul_f32_e32 v35, v39, v39
	v_mul_f32_e32 v36, v41, v41
	v_fmac_f32_e32 v47, v48, v48
	v_fmac_f32_e32 v35, v38, v38
	v_fmac_f32_e32 v36, v40, v40
	v_fmac_f32_e32 v43, v42, v42
	v_fmac_f32_e32 v44, v46, v46
	v_add_f32_e32 v35, v35, v36
	v_add_f32_e32 v36, v43, v45
	v_add_f32_e32 v37, v44, v47
	v_add_f32_e32 v34, v36, v34
	v_add_f32_e32 v35, v37, v35
	ds_bpermute_b32 v36, v204, v34
	ds_bpermute_b32 v37, v204, v35
	s_waitcnt lgkmcnt(1)
	v_add_f32_e32 v34, v34, v36
	s_waitcnt lgkmcnt(0)
	v_add_f32_e32 v37, v35, v37
	ds_bpermute_b32 v36, v205, v34
	ds_bpermute_b32 v38, v205, v37
	s_waitcnt lgkmcnt(1)
	v_add_f32_e32 v34, v34, v36
	s_waitcnt lgkmcnt(0)
	v_add_f32_e32 v36, v37, v38
	ds_bpermute_b32 v35, v206, v34
	ds_bpermute_b32 v37, v206, v36
	v_add_u32_e32 v38, 0x1040, v68
	v_cndmask_b32_e64 v38, v68, v38, s[38:39]
	global_store_dwordx2 v38, v[246:247], s[54:55]
	s_and_saveexec_b64 s[16:17], s[42:43]
	s_cbranch_execz .LBB0_380
	s_waitcnt lgkmcnt(1)
	v_add_f32_e32 v34, v34, v35
	s_waitcnt lgkmcnt(0)
	v_add_f32_e32 v35, v36, v37
	ds_write2_b32 v194, v34, v35 offset0:80 offset1:88
; #define LAS __attribute__((address_space(3)))
; #define ERN_EOFF(q, m) (eb + (unsigned)((((q) & 1) * HALF + (m) * 16) * DM + ERN_COL((q) >> 1)))
;     __device__ __forceinline__ void operator()(const f32x4 (&acc)[2][2][4][2], const Unit& u, int wr, int wc, int fr, int fq) const {
;     ...
;         for (int g = 0; g < 8; ++g) { const int ai = g >> 2, m = g & 3;
;             if (g + 1 < 8) ERN_LOADX(g + 1);
;             float sq0 = 0.f, sq1 = 0.f; u32x2 hw[2][2];
; #pragma unroll
;             for (int bj = 0; bj < 2; ++bj) {
;                 *(LAS f32x4*)(st + wr_off) = acc[ai][bj][m][0]; *(LAS f32x4*)(st + wr_off + 64) = acc[ai][bj][m][1];
;                 const f32x4 a0 = *(const LAS f32x4*)(st + rd_off), a1 = *(const LAS f32x4*)(st + rd_off + 8 * 144);
;                 { const f32x4 xv = xb[g & 1][bj][0] + gv[bj] * a0; __builtin_nontemporal_store(xv, (f32x4*)((char*)xo + 4u * ERN_EOFF(g, bj, 0)));
;                   sq0 += (xv.x * xv.x + xv.y * xv.y) + (xv.z * xv.z + xv.w * xv.w);
;                   const f32x4 hv = xv * gsn[bj]; hw[bj][0].x = cvt_pk_bf16(hv.x, hv.y); hw[bj][0].y = cvt_pk_bf16(hv.z, hv.w); }
;                 { const f32x4 xv = xb[g & 1][bj][1] + gv[bj] * a1; __builtin_nontemporal_store(xv, (f32x4*)((char*)xo + 4u * ERN_EOFF(g, bj, 1)));
;                   sq1 += (xv.x * xv.x + xv.y * xv.y) + (xv.z * xv.z + xv.w * xv.w);
;                   const f32x4 hv = xv * gsn[bj]; hw[bj][1].x = cvt_pk_bf16(hv.x, hv.y); hw[bj][1].y = cvt_pk_bf16(hv.z, hv.w); }
;             }
;             if (!NOH && !PLAIN) {
; #pragma unroll
;                 for (int rh = 0; rh < 2; ++rh) { u32x2 rv; rv.x = __shfl_xor(hw[1][rh].x, 8); rv.y = __shfl_xor(hw[1][rh].y, 8);
;                     const unsigned e0 = ERN_EOFF(g, 0, rh);
;                     const unsigned ee = odd ? (e0 - DM + 32) : e0, eo2 = odd ? e0 : (e0 + DM + 32);
;                     *(u32x2*)((char*)ho + 2u * ee) = odd ? rv : hw[0][rh];
;                     *(u32x2*)((char*)ho + 2u * eo2) = odd ? hw[0][rh] : rv; }
;             }
;             if (!PLAIN) { sq0 += __shfl_xor(sq0, 1); sq0 += __shfl_xor(sq0, 2); sq0 += __shfl_xor(sq0, 4);
;             sq1 += __shfl_xor(sq1, 1); sq1 += __shfl_xor(sq1, 2); sq1 += __shfl_xor(sq1, 4); }
;             if (!PLAIN && pc == 0) { sst[g * 16 + rr] = sq0; sst[g * 16 + 8 + rr] = sq1; }
.LBB0_380:
	s_or_b64 exec, exec, s[16:17]
	v_add_u32_e32 v154, 0x160000, v207
	v_add_u32_e32 v68, 0x160080, v207
	v_add_u32_e32 v70, 0x170000, v207
	global_load_dwordx4 v[46:49], v154, s[58:59]
	global_load_dwordx4 v[42:45], v70, s[58:59]
	v_add_u32_e32 v66, 0x170080, v207
	global_load_dwordx4 v[38:41], v68, s[58:59]
	s_waitcnt lgkmcnt(0)
	global_load_dwordx4 v[34:37], v66, s[58:59]
	ds_write_b128 v200, v[30:33]
	ds_write_b128 v200, v[26:29] offset:64
	ds_read_b128 v[26:29], v201
	ds_read_b128 v[30:33], v201 offset:1152
	v_mov_b32_e32 v89, v155
	v_mov_b32_e32 v87, v155
	v_mov_b32_e32 v85, v155
	s_waitcnt vmcnt(14) lgkmcnt(1)
	v_pk_fma_f32 v[28:29], v[178:179], v[28:29], v[64:65]
	v_pk_fma_f32 v[26:27], v[180:181], v[26:27], v[62:63]
	v_lshl_add_u64 v[62:63], s[56:57], 0, v[88:89]
	global_store_dwordx4 v[62:63], v[26:29], off nt
	v_pk_mul_f32 v[62:63], v[176:177], v[26:27]
	s_waitcnt vmcnt(14) lgkmcnt(0)
	v_pk_fma_f32 v[32:33], v[178:179], v[32:33], v[60:61]
	v_pk_fma_f32 v[30:31], v[180:181], v[30:31], v[58:59]
	v_lshl_add_u64 v[58:59], s[56:57], 0, v[86:87]
	v_pk_mul_f32 v[64:65], v[174:175], v[28:29]
	v_cvt_pk_bf16_f32 v62, v62, v63
	v_pk_mul_f32 v[60:61], v[174:175], v[32:33]
	v_cvt_pk_bf16_f32 v63, v64, v65
	global_store_dwordx4 v[58:59], v[30:33], off nt
	v_pk_mul_f32 v[58:59], v[176:177], v[30:31]
	v_mov_b32_e32 v83, v155
	v_cvt_pk_bf16_f32 v58, v58, v59
	v_cvt_pk_bf16_f32 v59, v60, v61
	ds_write_b128 v200, v[22:25]
	ds_write_b128 v200, v[18:21] offset:64
	ds_read_b128 v[18:21], v201
	ds_read_b128 v[22:25], v201 offset:1152
	s_waitcnt vmcnt(14) lgkmcnt(1)
	v_pk_fma_f32 v[18:19], v[168:169], v[18:19], v[54:55]
	v_pk_fma_f32 v[20:21], v[166:167], v[20:21], v[56:57]
	v_lshl_add_u64 v[54:55], s[56:57], 0, v[84:85]
	v_pk_mul_f32 v[56:57], v[172:173], v[18:19]
	s_waitcnt vmcnt(13) lgkmcnt(0)
	v_pk_fma_f32 v[24:25], v[166:167], v[24:25], v[52:53]
	v_pk_fma_f32 v[22:23], v[168:169], v[22:23], v[50:51]
	v_lshl_add_u64 v[50:51], s[56:57], 0, v[82:83]
	global_store_dwordx4 v[54:55], v[18:21], off nt
	v_pk_mul_f32 v[54:55], v[170:171], v[20:21]
	v_cvt_pk_bf16_f32 v56, v56, v57
	v_pk_mul_f32 v[52:53], v[172:173], v[22:23]
	v_cvt_pk_bf16_f32 v57, v54, v55
	global_store_dwordx4 v[50:51], v[22:25], off nt
	ds_bpermute_b32 v50, v203, v56
	ds_bpermute_b32 v51, v203, v57
	v_pk_mul_f32 v[54:55], v[170:171], v[24:25]
	v_cvt_pk_bf16_f32 v52, v52, v53
	s_nop 0
	v_cvt_pk_bf16_f32 v53, v54, v55
	v_add_u32_e32 v55, 0x50000, v202
	v_lshlrev_b32_e32 v54, 1, v55
	s_waitcnt lgkmcnt(0)
	v_add_u32_e32 v250, 0xfffff040, v54
	v_cndmask_b32_e64 v250, v54, v250, s[40:41]
	v_cndmask_b32_e64 v248, v62, v50, s[40:41]
	v_cndmask_b32_e64 v249, v63, v51, s[40:41]
	global_store_dwordx2 v250, v[248:249], s[54:55]
	v_cndmask_b32_e64 v246, v50, v62, s[40:41]
	v_cndmask_b32_e64 v247, v51, v63, s[40:41]
	s_waitcnt lgkmcnt(1)
	v_add_u32_e32 v50, 0x1040, v54
	v_cndmask_b32_e64 v50, v54, v50, s[38:39]
	global_store_dwordx2 v50, v[246:247], s[54:55]
	ds_bpermute_b32 v50, v203, v52
	s_waitcnt lgkmcnt(1)
	ds_bpermute_b32 v51, v203, v53
	v_add_u32_e32 v53, 0x54000, v202
	v_lshlrev_b32_e32 v52, 1, v53
	s_waitcnt lgkmcnt(0)
	v_add_u32_e32 v250, 0xfffff040, v52
	v_cndmask_b32_e64 v250, v52, v250, s[40:41]
	v_cndmask_b32_e64 v248, v58, v50, s[40:41]
	v_cndmask_b32_e64 v249, v59, v51, s[40:41]
	global_store_dwordx2 v250, v[248:249], s[54:55]
	v_cndmask_b32_e64 v246, v50, v58, s[40:41]
	v_cndmask_b32_e64 v247, v51, v59, s[40:41]
	v_mul_f32_e32 v19, v19, v19
	v_fmac_f32_e32 v19, v18, v18
	v_mul_f32_e32 v18, v21, v21
	v_mul_f32_e32 v29, v29, v29
	v_fmac_f32_e32 v18, v20, v20
	v_mul_f32_e32 v27, v27, v27
	v_fmac_f32_e32 v29, v28, v28
	v_mul_f32_e32 v28, v31, v31
	v_mul_f32_e32 v31, v33, v33
	v_add_f32_e32 v18, v19, v18
	v_mul_f32_e32 v19, v23, v23
	v_mul_f32_e32 v20, v25, v25
	v_fmac_f32_e32 v31, v32, v32
	v_fmac_f32_e32 v19, v22, v22
	v_fmac_f32_e32 v20, v24, v24
	v_fmac_f32_e32 v27, v26, v26
	v_fmac_f32_e32 v28, v30, v30
	v_add_f32_e32 v19, v19, v20
	v_add_f32_e32 v20, v27, v29
	v_add_f32_e32 v21, v28, v31
	v_add_f32_e32 v18, v20, v18
	v_add_f32_e32 v19, v21, v19
	ds_bpermute_b32 v20, v204, v18
	ds_bpermute_b32 v21, v204, v19
	s_waitcnt lgkmcnt(1)
	v_add_f32_e32 v18, v18, v20
	s_waitcnt lgkmcnt(0)
	v_add_f32_e32 v21, v19, v21
	ds_bpermute_b32 v20, v205, v18
	ds_bpermute_b32 v22, v205, v21
	s_waitcnt lgkmcnt(1)
	v_add_f32_e32 v18, v18, v20
	s_waitcnt lgkmcnt(0)
	v_add_f32_e32 v20, v21, v22
	ds_bpermute_b32 v19, v206, v18
	ds_bpermute_b32 v21, v206, v20
	v_add_u32_e32 v22, 0x1040, v52
	v_cndmask_b32_e64 v22, v52, v22, s[38:39]
	global_store_dwordx2 v22, v[246:247], s[54:55]
	s_and_saveexec_b64 s[16:17], s[42:43]
	s_cbranch_execz .LBB0_390
	s_waitcnt lgkmcnt(1)
	v_add_f32_e32 v18, v18, v19
	s_waitcnt lgkmcnt(0)
	v_add_f32_e32 v19, v20, v21
	ds_write2_b32 v194, v18, v19 offset0:96 offset1:104
; #define LAS __attribute__((address_space(3)))
; #define ERN_EOFF(q, m) (eb + (unsigned)((((q) & 1) * HALF + (m) * 16) * DM + ERN_COL((q) >> 1)))
;     __device__ __forceinline__ void operator()(const f32x4 (&acc)[2][2][4][2], const Unit& u, int wr, int wc, int fr, int fq) const {
;     ...
;         for (int g = 0; g < 8; ++g) { const int ai = g >> 2, m = g & 3;
;             if (g + 1 < 8) ERN_LOADX(g + 1);
;             float sq0 = 0.f, sq1 = 0.f; u32x2 hw[2][2];
; #pragma unroll
;             for (int bj = 0; bj < 2; ++bj) {
;                 *(LAS f32x4*)(st + wr_off) = acc[ai][bj][m][0]; *(LAS f32x4*)(st + wr_off + 64) = acc[ai][bj][m][1];
;                 const f32x4 a0 = *(const LAS f32x4*)(st + rd_off), a1 = *(const LAS f32x4*)(st + rd_off + 8 * 144);
;                 { const f32x4 xv = xb[g & 1][bj][0] + gv[bj] * a0; __builtin_nontemporal_store(xv, (f32x4*)((char*)xo + 4u * ERN_EOFF(g, bj, 0)));
;                   sq0 += (xv.x * xv.x + xv.y * xv.y) + (xv.z * xv.z + xv.w * xv.w);
;                   const f32x4 hv = xv * gsn[bj]; hw[bj][0].x = cvt_pk_bf16(hv.x, hv.y); hw[bj][0].y = cvt_pk_bf16(hv.z, hv.w); }
;                 { const f32x4 xv = xb[g & 1][bj][1] + gv[bj] * a1; __builtin_nontemporal_store(xv, (f32x4*)((char*)xo + 4u * ERN_EOFF(g, bj, 1)));
;                   sq1 += (xv.x * xv.x + xv.y * xv.y) + (xv.z * xv.z + xv.w * xv.w);
;                   const f32x4 hv = xv * gsn[bj]; hw[bj][1].x = cvt_pk_bf16(hv.x, hv.y); hw[bj][1].y = cvt_pk_bf16(hv.z, hv.w); }
;             }
;             if (!NOH && !PLAIN) {
; #pragma unroll
;                 for (int rh = 0; rh < 2; ++rh) { u32x2 rv; rv.x = __shfl_xor(hw[1][rh].x, 8); rv.y = __shfl_xor(hw[1][rh].y, 8);
;                     const unsigned e0 = ERN_EOFF(g, 0, rh);
;                     const unsigned ee = odd ? (e0 - DM + 32) : e0, eo2 = odd ? e0 : (e0 + DM + 32);
;                     *(u32x2*)((char*)ho + 2u * ee) = odd ? rv : hw[0][rh];
;                     *(u32x2*)((char*)ho + 2u * eo2) = odd ? hw[0][rh] : rv; }
;             }
;             if (!PLAIN) { sq0 += __shfl_xor(sq0, 1); sq0 += __shfl_xor(sq0, 2); sq0 += __shfl_xor(sq0, 4);
;             sq1 += __shfl_xor(sq1, 1); sq1 += __shfl_xor(sq1, 2); sq1 += __shfl_xor(sq1, 4); }
;             if (!PLAIN && pc == 0) { sst[g * 16 + rr] = sq0; sst[g * 16 + 8 + rr] = sq1; }
.LBB0_390:
	s_or_b64 exec, exec, s[16:17]
	ds_write_b128 v200, v[14:17]
	ds_write_b128 v200, v[10:13] offset:64
	ds_read_b128 v[10:13], v201
	ds_read_b128 v[14:17], v201 offset:1152
	s_waitcnt lgkmcnt(5)
	v_lshl_add_u64 v[18:19], s[56:57], 0, v[154:155]
	v_mov_b32_e32 v71, v155
	v_mov_b32_e32 v69, v155
	s_waitcnt vmcnt(10) lgkmcnt(1)
	v_pk_fma_f32 v[12:13], v[178:179], v[12:13], v[48:49]
	v_pk_fma_f32 v[10:11], v[180:181], v[10:11], v[46:47]
	global_store_dwordx4 v[18:19], v[10:13], off nt
	v_pk_mul_f32 v[18:19], v[174:175], v[12:13]
	v_pk_mul_f32 v[20:21], v[176:177], v[10:11]
	s_waitcnt vmcnt(10) lgkmcnt(0)
	v_pk_fma_f32 v[16:17], v[178:179], v[16:17], v[44:45]
	v_cvt_pk_bf16_f32 v20, v20, v21
	v_cvt_pk_bf16_f32 v21, v18, v19
	v_pk_fma_f32 v[14:15], v[180:181], v[14:15], v[42:43]
	v_lshl_add_u64 v[18:19], s[56:57], 0, v[70:71]
	global_store_dwordx4 v[18:19], v[14:17], off nt
	v_pk_mul_f32 v[18:19], v[176:177], v[14:15]
	v_pk_mul_f32 v[22:23], v[174:175], v[16:17]
	v_cvt_pk_bf16_f32 v18, v18, v19
	v_mov_b32_e32 v67, v155
	v_cvt_pk_bf16_f32 v19, v22, v23
	ds_write_b128 v200, v[6:9]
	ds_write_b128 v200, v[2:5] offset:64
	ds_read_b128 v[2:5], v201
	ds_read_b128 v[6:9], v201 offset:1152
	v_lshl_add_u64 v[22:23], s[56:57], 0, v[68:69]
	s_waitcnt vmcnt(10) lgkmcnt(1)
	v_pk_fma_f32 v[4:5], v[166:167], v[4:5], v[40:41]
	v_pk_fma_f32 v[2:3], v[168:169], v[2:3], v[38:39]
	global_store_dwordx4 v[22:23], v[2:5], off nt
	v_pk_mul_f32 v[22:23], v[170:171], v[4:5]
	v_pk_mul_f32 v[24:25], v[172:173], v[2:3]
	s_waitcnt vmcnt(10) lgkmcnt(0)
	v_pk_fma_f32 v[8:9], v[166:167], v[8:9], v[36:37]
	v_cvt_pk_bf16_f32 v28, v24, v25
	v_cvt_pk_bf16_f32 v29, v22, v23
	v_pk_fma_f32 v[6:7], v[168:169], v[6:7], v[34:35]
	v_lshl_add_u64 v[22:23], s[56:57], 0, v[66:67]
	global_store_dwordx4 v[22:23], v[6:9], off nt
	ds_bpermute_b32 v22, v203, v28
	ds_bpermute_b32 v23, v203, v29
	v_pk_mul_f32 v[26:27], v[170:171], v[8:9]
	v_pk_mul_f32 v[24:25], v[172:173], v[6:7]
	s_nop 0
	v_cvt_pk_bf16_f32 v24, v24, v25
	v_cvt_pk_bf16_f32 v25, v26, v27
	v_add_u32_e32 v27, 0x58000, v202
	v_lshlrev_b32_e32 v26, 1, v27
	s_waitcnt lgkmcnt(0)
	v_add_u32_e32 v250, 0xfffff040, v26
	v_cndmask_b32_e64 v250, v26, v250, s[40:41]
	v_cndmask_b32_e64 v248, v20, v22, s[40:41]
	v_cndmask_b32_e64 v249, v21, v23, s[40:41]
	global_store_dwordx2 v250, v[248:249], s[54:55]
	v_cndmask_b32_e64 v246, v22, v20, s[40:41]
	v_cndmask_b32_e64 v247, v23, v21, s[40:41]
	s_waitcnt lgkmcnt(1)
	v_add_u32_e32 v22, 0x1040, v26
	v_cndmask_b32_e64 v22, v26, v22, s[38:39]
	global_store_dwordx2 v22, v[246:247], s[54:55]
	ds_bpermute_b32 v20, v203, v24
	ds_bpermute_b32 v21, v203, v25
	s_waitcnt lgkmcnt(2)
	v_add_u32_e32 v23, 0x5c000, v202
	v_lshlrev_b32_e32 v22, 1, v23
	s_waitcnt lgkmcnt(0)
	v_add_u32_e32 v250, 0xfffff040, v22
	v_cndmask_b32_e64 v250, v22, v250, s[40:41]
	v_cndmask_b32_e64 v248, v18, v20, s[40:41]
	v_cndmask_b32_e64 v249, v19, v21, s[40:41]
	global_store_dwordx2 v250, v[248:249], s[54:55]
	v_cndmask_b32_e64 v246, v20, v18, s[40:41]
	v_cndmask_b32_e64 v247, v21, v19, s[40:41]
	v_mul_f32_e32 v3, v3, v3
	v_fmac_f32_e32 v3, v2, v2
	v_mul_f32_e32 v2, v5, v5
	v_mul_f32_e32 v13, v13, v13
	v_fmac_f32_e32 v2, v4, v4
	v_mul_f32_e32 v11, v11, v11
	v_fmac_f32_e32 v13, v12, v12
	v_mul_f32_e32 v12, v15, v15
	v_mul_f32_e32 v15, v17, v17
	v_add_f32_e32 v2, v3, v2
	v_mul_f32_e32 v3, v7, v7
	v_mul_f32_e32 v4, v9, v9
	v_fmac_f32_e32 v15, v16, v16
	v_fmac_f32_e32 v3, v6, v6
	v_fmac_f32_e32 v4, v8, v8
	v_fmac_f32_e32 v11, v10, v10
	v_fmac_f32_e32 v12, v14, v14
	v_add_f32_e32 v3, v3, v4
	v_add_f32_e32 v4, v11, v13
	v_add_f32_e32 v5, v12, v15
	v_add_f32_e32 v2, v4, v2
	v_add_f32_e32 v3, v5, v3
	ds_bpermute_b32 v4, v204, v2
	ds_bpermute_b32 v5, v204, v3
	s_waitcnt lgkmcnt(1)
	v_add_f32_e32 v2, v2, v4
	s_waitcnt lgkmcnt(0)
	v_add_f32_e32 v5, v3, v5
	ds_bpermute_b32 v4, v205, v2
	ds_bpermute_b32 v6, v205, v5
	s_waitcnt lgkmcnt(1)
	v_add_f32_e32 v2, v2, v4
	s_waitcnt lgkmcnt(0)
	v_add_f32_e32 v4, v5, v6
	ds_bpermute_b32 v3, v206, v2
	ds_bpermute_b32 v5, v206, v4
	v_add_u32_e32 v6, 0x1040, v22
	v_cndmask_b32_e64 v6, v22, v6, s[38:39]
	global_store_dwordx2 v6, v[246:247], s[54:55]
	s_and_saveexec_b64 s[16:17], s[42:43]
	s_cbranch_execz .LBB0_400
	s_waitcnt lgkmcnt(1)
	v_add_f32_e32 v2, v2, v3
	s_waitcnt lgkmcnt(0)
	v_add_f32_e32 v3, v4, v5
	ds_write2_b32 v194, v2, v3 offset0:112 offset1:120

; #define LAS __attribute__((address_space(3)))
; #define ERN_EOFF(q, m) (eb + (unsigned)((((q) & 1) * HALF + (m) * 16) * DM + ERN_COL((q) >> 1)))
;     __device__ __forceinline__ void operator()(const f32x4 (&acc)[2][2][4][2], const Unit& u, int wr, int wc, int fr, int fq) const {
;     ...
;         for (int g = 0; g < 8; ++g) { const int ai = g >> 2, m = g & 3;
;             if (g + 1 < 8) ERN_LOADX(g + 1);
;             float sq0 = 0.f, sq1 = 0.f; u32x2 hw[2][2];
; #pragma unroll
;             for (int bj = 0; bj < 2; ++bj) {
;                 *(LAS f32x4*)(st + wr_off) = acc[ai][bj][m][0]; *(LAS f32x4*)(st + wr_off + 64) = acc[ai][bj][m][1];
;                 const f32x4 a0 = *(const LAS f32x4*)(st + rd_off), a1 = *(const LAS f32x4*)(st + rd_off + 8 * 144);
;                 { const f32x4 xv = xb[g & 1][bj][0] + gv[bj] * a0; __builtin_nontemporal_store(xv, (f32x4*)((char*)xo + 4u * ERN_EOFF(g, bj, 0)));
;                   sq0 += (xv.x * xv.x + xv.y * xv.y) + (xv.z * xv.z + xv.w * xv.w);
;                   const f32x4 hv = xv * gsn[bj]; hw[bj][0].x = cvt_pk_bf16(hv.x, hv.y); hw[bj][0].y = cvt_pk_bf16(hv.z, hv.w); }
;                 { const f32x4 xv = xb[g & 1][bj][1] + gv[bj] * a1; __builtin_nontemporal_store(xv, (f32x4*)((char*)xo + 4u * ERN_EOFF(g, bj, 1)));
;                   sq1 += (xv.x * xv.x + xv.y * xv.y) + (xv.z * xv.z + xv.w * xv.w);
;                   const f32x4 hv = xv * gsn[bj]; hw[bj][1].x = cvt_pk_bf16(hv.x, hv.y); hw[bj][1].y = cvt_pk_bf16(hv.z, hv.w); }
;             }
;             if (!NOH && !PLAIN) {
; #pragma unroll
;                 for (int rh = 0; rh < 2; ++rh) { u32x2 rv; rv.x = __shfl_xor(hw[1][rh].x, 8); rv.y = __shfl_xor(hw[1][rh].y, 8);
;                     const unsigned e0 = ERN_EOFF(g, 0, rh);
;                     const unsigned ee = odd ? (e0 - DM + 32) : e0, eo2 = odd ? e0 : (e0 + DM + 32);
;                     *(u32x2*)((char*)ho + 2u * ee) = odd ? rv : hw[0][rh];
;                     *(u32x2*)((char*)ho + 2u * eo2) = odd ? hw[0][rh] : rv; }
;             }
;             if (!PLAIN) { sq0 += __shfl_xor(sq0, 1); sq0 += __shfl_xor(sq0, 2); sq0 += __shfl_xor(sq0, 4);
;             sq1 += __shfl_xor(sq1, 1); sq1 += __shfl_xor(sq1, 2); sq1 += __shfl_xor(sq1, 4); }
;             if (!PLAIN && pc == 0) { sst[g * 16 + rr] = sq0; sst[g * 16 + 8 + rr] = sq1; }
.LBB0_1273:
	s_or_b64 exec, exec, s[16:17]
	v_lshl_add_u64 v[142:143], s[48:49], 0, v[162:163]
	v_add_u32_e32 v106, 0x60000, v205
	v_add_u32_e32 v162, 0x70000, v205
	v_add_u32_e32 v138, 0x60080, v205
	global_load_dwordx4 v[114:117], v162, s[48:49]
	global_load_dwordx4 v[110:113], v138, s[48:49]
	v_add_u32_e32 v140, 0x70080, v205
	global_load_dwordx4 v[118:121], v106, s[48:49]
	s_waitcnt lgkmcnt(0)
	global_load_dwordx4 v[106:109], v140, s[48:49]
	ds_write_b128 v200, v[102:105]
	ds_write_b128 v200, v[98:101] offset:64
	ds_read_b128 v[98:101], v201
	ds_read_b128 v[102:105], v201 offset:1152
	v_mov_b32_e32 v187, v163
	v_mov_b32_e32 v189, v163
	s_waitcnt vmcnt(12) lgkmcnt(1)
	v_pk_fma_f32 v[100:101], v[56:57], v[100:101], v[136:137]
	v_add_u32_e32 v136, 0x10000, v202
	v_pk_fma_f32 v[98:99], v[54:55], v[98:99], v[134:135]
	v_lshlrev_b32_e32 v134, 2, v136
	s_waitcnt lgkmcnt(0)
	v_pk_fma_f32 v[102:103], v[54:55], v[102:103], v[130:131]
	global_store_dwordx4 v134, v[98:101], s[48:49] nt
	v_pk_mul_f32 v[134:135], v[180:181], v[98:99]
	v_pk_fma_f32 v[104:105], v[56:57], v[104:105], v[132:133]
	v_pk_mul_f32 v[130:131], v[180:181], v[102:103]
	v_pk_mul_f32 v[144:145], v[178:179], v[100:101]
	v_cvt_pk_bf16_f32 v134, v134, v135
	v_pk_mul_f32 v[132:133], v[178:179], v[104:105]
	v_cvt_pk_bf16_f32 v135, v144, v145
	global_store_dwordx4 v[142:143], v[102:105], off nt
	v_cvt_pk_bf16_f32 v130, v130, v131
	v_cvt_pk_bf16_f32 v131, v132, v133
	ds_write_b128 v200, v[94:97]
	ds_write_b128 v200, v[90:93] offset:64
	ds_read_b128 v[90:93], v201
	ds_read_b128 v[94:97], v201 offset:1152
	v_lshl_add_u64 v[132:133], s[48:49], 0, v[186:187]
	v_lshl_add_u64 v[142:143], s[48:49], 0, v[188:189]
	s_waitcnt lgkmcnt(1)
	v_pk_fma_f32 v[90:91], v[50:51], v[90:91], v[126:127]
	v_pk_fma_f32 v[92:93], v[52:53], v[92:93], v[128:129]
	v_pk_mul_f32 v[128:129], v[176:177], v[90:91]
	global_store_dwordx4 v[132:133], v[90:93], off nt
	v_pk_mul_f32 v[126:127], v[174:175], v[92:93]
	v_cvt_pk_bf16_f32 v128, v128, v129
	s_waitcnt vmcnt(14) lgkmcnt(0)
	v_pk_fma_f32 v[94:95], v[50:51], v[94:95], v[122:123]
	v_cvt_pk_bf16_f32 v129, v126, v127
	ds_bpermute_b32 v122, v203, v128
	ds_bpermute_b32 v123, v203, v129
	v_pk_fma_f32 v[96:97], v[52:53], v[96:97], v[124:125]
	v_pk_mul_f32 v[124:125], v[176:177], v[94:95]
	v_pk_mul_f32 v[126:127], v[174:175], v[96:97]
	global_store_dwordx4 v[142:143], v[94:97], off nt
	v_cvt_pk_bf16_f32 v124, v124, v125
	v_cvt_pk_bf16_f32 v125, v126, v127
	v_lshlrev_b32_e32 v126, 1, v136
	s_waitcnt lgkmcnt(0)
	v_add_u32_e32 v250, 0xfffff040, v126
	v_cndmask_b32_e64 v250, v126, v250, s[40:41]
	v_cndmask_b32_e64 v248, v134, v122, s[40:41]
	v_cndmask_b32_e64 v249, v135, v123, s[40:41]
	global_store_dwordx2 v250, v[248:249], s[46:47]
	v_cndmask_b32_e64 v246, v122, v134, s[40:41]
	v_cndmask_b32_e64 v247, v123, v135, s[40:41]
	s_waitcnt lgkmcnt(1)
	v_add_u32_e32 v122, 0x1040, v126
	v_cndmask_b32_e64 v122, v126, v122, s[38:39]
	global_store_dwordx2 v122, v[246:247], s[46:47]
	ds_bpermute_b32 v122, v203, v124
	s_waitcnt lgkmcnt(1)
	ds_bpermute_b32 v123, v203, v125
	v_add_u32_e32 v125, 0x14000, v202
	v_lshlrev_b32_e32 v124, 1, v125
	s_waitcnt lgkmcnt(0)
	v_add_u32_e32 v250, 0xfffff040, v124
	v_cndmask_b32_e64 v250, v124, v250, s[40:41]
	v_cndmask_b32_e64 v248, v130, v122, s[40:41]
	v_cndmask_b32_e64 v249, v131, v123, s[40:41]
	global_store_dwordx2 v250, v[248:249], s[46:47]
	v_cndmask_b32_e64 v246, v122, v130, s[40:41]
	v_cndmask_b32_e64 v247, v123, v131, s[40:41]
	v_mul_f32_e32 v91, v91, v91
	v_fmac_f32_e32 v91, v90, v90
	v_mul_f32_e32 v90, v93, v93
	v_mul_f32_e32 v101, v101, v101
	v_fmac_f32_e32 v90, v92, v92
	v_mul_f32_e32 v99, v99, v99
	v_fmac_f32_e32 v101, v100, v100
	v_mul_f32_e32 v100, v103, v103
	v_mul_f32_e32 v103, v105, v105
	v_add_f32_e32 v90, v91, v90
	v_mul_f32_e32 v91, v95, v95
	v_mul_f32_e32 v92, v97, v97
	v_fmac_f32_e32 v103, v104, v104
	v_fmac_f32_e32 v91, v94, v94
	v_fmac_f32_e32 v92, v96, v96
	v_fmac_f32_e32 v99, v98, v98
	v_fmac_f32_e32 v100, v102, v102
	v_add_f32_e32 v91, v91, v92
	v_add_f32_e32 v92, v99, v101
	v_add_f32_e32 v93, v100, v103
	v_add_f32_e32 v90, v92, v90
	v_add_f32_e32 v91, v93, v91
	ds_bpermute_b32 v92, v190, v90
	ds_bpermute_b32 v93, v190, v91
	s_waitcnt lgkmcnt(1)
	v_add_f32_e32 v90, v90, v92
	s_waitcnt lgkmcnt(0)
	v_add_f32_e32 v93, v91, v93
	ds_bpermute_b32 v92, v191, v90
	ds_bpermute_b32 v94, v191, v93
	s_waitcnt lgkmcnt(1)
	v_add_f32_e32 v90, v90, v92
	s_waitcnt lgkmcnt(0)
	v_add_f32_e32 v92, v93, v94
	ds_bpermute_b32 v91, v204, v90
	ds_bpermute_b32 v93, v204, v92
	v_add_u32_e32 v94, 0x1040, v124
	v_cndmask_b32_e64 v94, v124, v94, s[38:39]
	global_store_dwordx2 v94, v[246:247], s[46:47]
	s_and_saveexec_b64 s[16:17], s[42:43]
	s_cbranch_execz .LBB0_1283
	s_waitcnt lgkmcnt(1)
	v_add_f32_e32 v90, v90, v91
	s_waitcnt lgkmcnt(0)
	v_add_f32_e32 v91, v92, v93
	ds_write2_b32 v194, v90, v91 offset0:32 offset1:40
; #define LAS __attribute__((address_space(3)))
; #define ERN_EOFF(q, m) (eb + (unsigned)((((q) & 1) * HALF + (m) * 16) * DM + ERN_COL((q) >> 1)))
;     __device__ __forceinline__ void operator()(const f32x4 (&acc)[2][2][4][2], const Unit& u, int wr, int wc, int fr, int fq) const {
;     ...
;         for (int g = 0; g < 8; ++g) { const int ai = g >> 2, m = g & 3;
;             if (g + 1 < 8) ERN_LOADX(g + 1);
;             float sq0 = 0.f, sq1 = 0.f; u32x2 hw[2][2];
; #pragma unroll
;             for (int bj = 0; bj < 2; ++bj) {
;                 *(LAS f32x4*)(st + wr_off) = acc[ai][bj][m][0]; *(LAS f32x4*)(st + wr_off + 64) = acc[ai][bj][m][1];
;                 const f32x4 a0 = *(const LAS f32x4*)(st + rd_off), a1 = *(const LAS f32x4*)(st + rd_off + 8 * 144);
;                 { const f32x4 xv = xb[g & 1][bj][0] + gv[bj] * a0; __builtin_nontemporal_store(xv, (f32x4*)((char*)xo + 4u * ERN_EOFF(g, bj, 0)));
;                   sq0 += (xv.x * xv.x + xv.y * xv.y) + (xv.z * xv.z + xv.w * xv.w);
;                   const f32x4 hv = xv * gsn[bj]; hw[bj][0].x = cvt_pk_bf16(hv.x, hv.y); hw[bj][0].y = cvt_pk_bf16(hv.z, hv.w); }
;                 { const f32x4 xv = xb[g & 1][bj][1] + gv[bj] * a1; __builtin_nontemporal_store(xv, (f32x4*)((char*)xo + 4u * ERN_EOFF(g, bj, 1)));
;                   sq1 += (xv.x * xv.x + xv.y * xv.y) + (xv.z * xv.z + xv.w * xv.w);
;                   const f32x4 hv = xv * gsn[bj]; hw[bj][1].x = cvt_pk_bf16(hv.x, hv.y); hw[bj][1].y = cvt_pk_bf16(hv.z, hv.w); }
;             }
;             if (!NOH && !PLAIN) {
; #pragma unroll
;                 for (int rh = 0; rh < 2; ++rh) { u32x2 rv; rv.x = __shfl_xor(hw[1][rh].x, 8); rv.y = __shfl_xor(hw[1][rh].y, 8);
;                     const unsigned e0 = ERN_EOFF(g, 0, rh);
;                     const unsigned ee = odd ? (e0 - DM + 32) : e0, eo2 = odd ? e0 : (e0 + DM + 32);
;                     *(u32x2*)((char*)ho + 2u * ee) = odd ? rv : hw[0][rh];
;                     *(u32x2*)((char*)ho + 2u * eo2) = odd ? hw[0][rh] : rv; }
;             }
;             if (!PLAIN) { sq0 += __shfl_xor(sq0, 1); sq0 += __shfl_xor(sq0, 2); sq0 += __shfl_xor(sq0, 4);
;             sq1 += __shfl_xor(sq1, 1); sq1 += __shfl_xor(sq1, 2); sq1 += __shfl_xor(sq1, 4); }
;             if (!PLAIN && pc == 0) { sst[g * 16 + rr] = sq0; sst[g * 16 + 8 + rr] = sq1; }
.LBB0_1283:
	s_or_b64 exec, exec, s[16:17]
	v_lshl_add_u64 v[124:125], s[48:49], 0, v[162:163]
	v_add_u32_e32 v90, 0x100000, v205
	s_waitcnt lgkmcnt(1)
	v_add_u32_e32 v91, 0x110000, v205
	v_add_u32_e32 v162, 0x100080, v205
	global_load_dwordx4 v[102:105], v90, s[48:49]
	global_load_dwordx4 v[98:101], v91, s[48:49]
	v_add_u32_e32 v122, 0x110080, v205
	global_load_dwordx4 v[94:97], v162, s[48:49]
	s_waitcnt lgkmcnt(0)
	global_load_dwordx4 v[90:93], v122, s[48:49]
	ds_write_b128 v200, v[86:89]
	ds_write_b128 v200, v[82:85] offset:64
	ds_read_b128 v[82:85], v201
	ds_read_b128 v[86:89], v201 offset:1152
	v_mov_b32_e32 v139, v163
	v_mov_b32_e32 v141, v163
	s_waitcnt vmcnt(12) lgkmcnt(1)
	v_pk_fma_f32 v[84:85], v[56:57], v[84:85], v[120:121]
	v_add_u32_e32 v120, 0x18000, v202
	v_pk_fma_f32 v[82:83], v[54:55], v[82:83], v[118:119]
	v_lshlrev_b32_e32 v118, 2, v120
	s_waitcnt lgkmcnt(0)
	v_pk_fma_f32 v[86:87], v[54:55], v[86:87], v[114:115]
	global_store_dwordx4 v118, v[82:85], s[48:49] nt
	v_pk_mul_f32 v[118:119], v[180:181], v[82:83]
	v_pk_fma_f32 v[88:89], v[56:57], v[88:89], v[116:117]
	v_pk_mul_f32 v[114:115], v[180:181], v[86:87]
	v_pk_mul_f32 v[126:127], v[178:179], v[84:85]
	v_cvt_pk_bf16_f32 v118, v118, v119
	v_pk_mul_f32 v[116:117], v[178:179], v[88:89]
	v_cvt_pk_bf16_f32 v119, v126, v127
	global_store_dwordx4 v[124:125], v[86:89], off nt
	v_cvt_pk_bf16_f32 v114, v114, v115
	v_cvt_pk_bf16_f32 v115, v116, v117
	ds_write_b128 v200, v[78:81]
	ds_write_b128 v200, v[74:77] offset:64
	ds_read_b128 v[74:77], v201
	ds_read_b128 v[78:81], v201 offset:1152
	v_lshl_add_u64 v[116:117], s[48:49], 0, v[138:139]
	v_lshl_add_u64 v[124:125], s[48:49], 0, v[140:141]
	s_waitcnt lgkmcnt(1)
	v_pk_fma_f32 v[74:75], v[50:51], v[74:75], v[110:111]
	v_pk_fma_f32 v[76:77], v[52:53], v[76:77], v[112:113]
	v_pk_mul_f32 v[112:113], v[176:177], v[74:75]
	global_store_dwordx4 v[116:117], v[74:77], off nt
	v_pk_mul_f32 v[110:111], v[174:175], v[76:77]
	v_cvt_pk_bf16_f32 v112, v112, v113
	s_waitcnt vmcnt(14) lgkmcnt(0)
	v_pk_fma_f32 v[78:79], v[50:51], v[78:79], v[106:107]
	v_cvt_pk_bf16_f32 v113, v110, v111
	ds_bpermute_b32 v106, v203, v112
	ds_bpermute_b32 v107, v203, v113
	v_pk_fma_f32 v[80:81], v[52:53], v[80:81], v[108:109]
	v_pk_mul_f32 v[108:109], v[176:177], v[78:79]
	v_pk_mul_f32 v[110:111], v[174:175], v[80:81]
	global_store_dwordx4 v[124:125], v[78:81], off nt
	v_cvt_pk_bf16_f32 v108, v108, v109
	v_cvt_pk_bf16_f32 v109, v110, v111
	v_lshlrev_b32_e32 v110, 1, v120
	s_waitcnt lgkmcnt(0)
	v_add_u32_e32 v250, 0xfffff040, v110
	v_cndmask_b32_e64 v250, v110, v250, s[40:41]
	v_cndmask_b32_e64 v248, v118, v106, s[40:41]
	v_cndmask_b32_e64 v249, v119, v107, s[40:41]
	global_store_dwordx2 v250, v[248:249], s[46:47]
	v_cndmask_b32_e64 v246, v106, v118, s[40:41]
	v_cndmask_b32_e64 v247, v107, v119, s[40:41]
	s_waitcnt lgkmcnt(1)
	v_add_u32_e32 v106, 0x1040, v110
	v_cndmask_b32_e64 v106, v110, v106, s[38:39]
	global_store_dwordx2 v106, v[246:247], s[46:47]
	ds_bpermute_b32 v106, v203, v108
	s_waitcnt lgkmcnt(1)
	ds_bpermute_b32 v107, v203, v109
	v_add_u32_e32 v109, 0x1c000, v202
	v_lshlrev_b32_e32 v108, 1, v109
	s_waitcnt lgkmcnt(0)
	v_add_u32_e32 v250, 0xfffff040, v108
	v_cndmask_b32_e64 v250, v108, v250, s[40:41]
	v_cndmask_b32_e64 v248, v114, v106, s[40:41]
	v_cndmask_b32_e64 v249, v115, v107, s[40:41]
	global_store_dwordx2 v250, v[248:249], s[46:47]
	v_cndmask_b32_e64 v246, v106, v114, s[40:41]
	v_cndmask_b32_e64 v247, v107, v115, s[40:41]
	v_mul_f32_e32 v75, v75, v75
	v_fmac_f32_e32 v75, v74, v74
	v_mul_f32_e32 v74, v77, v77
	v_mul_f32_e32 v85, v85, v85
	v_fmac_f32_e32 v74, v76, v76
	v_mul_f32_e32 v83, v83, v83
	v_fmac_f32_e32 v85, v84, v84
	v_mul_f32_e32 v84, v87, v87
	v_mul_f32_e32 v87, v89, v89
	v_add_f32_e32 v74, v75, v74
	v_mul_f32_e32 v75, v79, v79
	v_mul_f32_e32 v76, v81, v81
	v_fmac_f32_e32 v87, v88, v88
	v_fmac_f32_e32 v75, v78, v78
	v_fmac_f32_e32 v76, v80, v80
	v_fmac_f32_e32 v83, v82, v82
	v_fmac_f32_e32 v84, v86, v86
	v_add_f32_e32 v75, v75, v76
	v_add_f32_e32 v76, v83, v85
	v_add_f32_e32 v77, v84, v87
	v_add_f32_e32 v74, v76, v74
	v_add_f32_e32 v75, v77, v75
	ds_bpermute_b32 v76, v190, v74
	ds_bpermute_b32 v77, v190, v75
	s_waitcnt lgkmcnt(1)
	v_add_f32_e32 v74, v74, v76
	s_waitcnt lgkmcnt(0)
	v_add_f32_e32 v77, v75, v77
	ds_bpermute_b32 v76, v191, v74
	ds_bpermute_b32 v78, v191, v77
	s_waitcnt lgkmcnt(1)
	v_add_f32_e32 v74, v74, v76
	s_waitcnt lgkmcnt(0)
	v_add_f32_e32 v76, v77, v78
	ds_bpermute_b32 v75, v204, v74
	ds_bpermute_b32 v77, v204, v76
	v_add_u32_e32 v78, 0x1040, v108
	v_cndmask_b32_e64 v78, v108, v78, s[38:39]
	global_store_dwordx2 v78, v[246:247], s[46:47]
	s_and_saveexec_b64 s[16:17], s[42:43]
	s_cbranch_execz .LBB0_1293
	s_waitcnt lgkmcnt(1)
	v_add_f32_e32 v74, v74, v75
	s_waitcnt lgkmcnt(0)
	v_add_f32_e32 v75, v76, v77
	ds_write2_b32 v194, v74, v75 offset0:48 offset1:56
; #define LAS __attribute__((address_space(3)))
; #define ERN_EOFF(q, m) (eb + (unsigned)((((q) & 1) * HALF + (m) * 16) * DM + ERN_COL((q) >> 1)))
;     __device__ __forceinline__ void operator()(const f32x4 (&acc)[2][2][4][2], const Unit& u, int wr, int wc, int fr, int fq) const {
;     ...
;         for (int g = 0; g < 8; ++g) { const int ai = g >> 2, m = g & 3;
;             if (g + 1 < 8) ERN_LOADX(g + 1);
;             float sq0 = 0.f, sq1 = 0.f; u32x2 hw[2][2];
; #pragma unroll
;             for (int bj = 0; bj < 2; ++bj) {
;                 *(LAS f32x4*)(st + wr_off) = acc[ai][bj][m][0]; *(LAS f32x4*)(st + wr_off + 64) = acc[ai][bj][m][1];
;                 const f32x4 a0 = *(const LAS f32x4*)(st + rd_off), a1 = *(const LAS f32x4*)(st + rd_off + 8 * 144);
;                 { const f32x4 xv = xb[g & 1][bj][0] + gv[bj] * a0; __builtin_nontemporal_store(xv, (f32x4*)((char*)xo + 4u * ERN_EOFF(g, bj, 0)));
;                   sq0 += (xv.x * xv.x + xv.y * xv.y) + (xv.z * xv.z + xv.w * xv.w);
;                   const f32x4 hv = xv * gsn[bj]; hw[bj][0].x = cvt_pk_bf16(hv.x, hv.y); hw[bj][0].y = cvt_pk_bf16(hv.z, hv.w); }
;                 { const f32x4 xv = xb[g & 1][bj][1] + gv[bj] * a1; __builtin_nontemporal_store(xv, (f32x4*)((char*)xo + 4u * ERN_EOFF(g, bj, 1)));
;                   sq1 += (xv.x * xv.x + xv.y * xv.y) + (xv.z * xv.z + xv.w * xv.w);
;                   const f32x4 hv = xv * gsn[bj]; hw[bj][1].x = cvt_pk_bf16(hv.x, hv.y); hw[bj][1].y = cvt_pk_bf16(hv.z, hv.w); }
;             }
;             if (!NOH && !PLAIN) {
; #pragma unroll
;                 for (int rh = 0; rh < 2; ++rh) { u32x2 rv; rv.x = __shfl_xor(hw[1][rh].x, 8); rv.y = __shfl_xor(hw[1][rh].y, 8);
;                     const unsigned e0 = ERN_EOFF(g, 0, rh);
;                     const unsigned ee = odd ? (e0 - DM + 32) : e0, eo2 = odd ? e0 : (e0 + DM + 32);
;                     *(u32x2*)((char*)ho + 2u * ee) = odd ? rv : hw[0][rh];
;                     *(u32x2*)((char*)ho + 2u * eo2) = odd ? hw[0][rh] : rv; }
;             }
;             if (!PLAIN) { sq0 += __shfl_xor(sq0, 1); sq0 += __shfl_xor(sq0, 2); sq0 += __shfl_xor(sq0, 4);
;             sq1 += __shfl_xor(sq1, 1); sq1 += __shfl_xor(sq1, 2); sq1 += __shfl_xor(sq1, 4); }
;             if (!PLAIN && pc == 0) { sst[g * 16 + rr] = sq0; sst[g * 16 + 8 + rr] = sq1; }
.LBB0_1293:
	s_or_b64 exec, exec, s[16:17]
	v_lshl_add_u64 v[112:113], s[48:49], 0, v[162:163]
	v_add_u32_e32 v162, 0x120000, v205
	v_add_u32_e32 v108, 0x120080, v205
	v_add_u32_e32 v110, 0x130000, v205
	global_load_dwordx4 v[86:89], v162, s[48:49]
	global_load_dwordx4 v[82:85], v110, s[48:49]
	v_add_u32_e32 v106, 0x130080, v205
	global_load_dwordx4 v[78:81], v108, s[48:49]
	s_waitcnt lgkmcnt(0)
	global_load_dwordx4 v[74:77], v106, s[48:49]
	ds_write_b128 v200, v[70:73]
	ds_write_b128 v200, v[66:69] offset:64
	ds_read_b128 v[66:69], v201
	ds_read_b128 v[70:73], v201 offset:1152
	v_mov_b32_e32 v123, v163
	s_waitcnt vmcnt(14) lgkmcnt(1)
	v_pk_fma_f32 v[68:69], v[56:57], v[68:69], v[104:105]
	v_add_u32_e32 v104, 0x40000, v202
	v_pk_fma_f32 v[66:67], v[54:55], v[66:67], v[102:103]
	v_lshlrev_b32_e32 v102, 2, v104
	s_waitcnt vmcnt(13) lgkmcnt(0)
	v_pk_fma_f32 v[72:73], v[56:57], v[72:73], v[100:101]
	v_add_u32_e32 v100, 0x44000, v202
	global_store_dwordx4 v102, v[66:69], s[48:49] nt
	v_pk_mul_f32 v[102:103], v[180:181], v[66:67]
	v_pk_fma_f32 v[70:71], v[54:55], v[70:71], v[98:99]
	v_lshlrev_b32_e32 v98, 2, v100
	v_pk_mul_f32 v[114:115], v[178:179], v[68:69]
	v_cvt_pk_bf16_f32 v102, v102, v103
	s_nop 0
	v_cvt_pk_bf16_f32 v103, v114, v115
	global_store_dwordx4 v98, v[70:73], s[48:49] nt
	v_pk_mul_f32 v[98:99], v[180:181], v[70:71]
	v_pk_mul_f32 v[114:115], v[178:179], v[72:73]
	v_cvt_pk_bf16_f32 v98, v98, v99
	s_nop 0
	v_cvt_pk_bf16_f32 v99, v114, v115
	ds_write_b128 v200, v[62:65]
	ds_write_b128 v200, v[58:61] offset:64
	ds_read_b128 v[58:61], v201
	ds_read_b128 v[62:65], v201 offset:1152
	v_lshl_add_u64 v[114:115], s[48:49], 0, v[122:123]
	s_waitcnt vmcnt(14) lgkmcnt(1)
	v_pk_fma_f32 v[58:59], v[50:51], v[58:59], v[94:95]
	v_pk_fma_f32 v[60:61], v[52:53], v[60:61], v[96:97]
	v_pk_mul_f32 v[96:97], v[176:177], v[58:59]
	global_store_dwordx4 v[112:113], v[58:61], off nt
	v_pk_mul_f32 v[94:95], v[174:175], v[60:61]
	v_cvt_pk_bf16_f32 v96, v96, v97
	s_waitcnt vmcnt(14) lgkmcnt(0)
	v_pk_fma_f32 v[62:63], v[50:51], v[62:63], v[90:91]
	v_cvt_pk_bf16_f32 v97, v94, v95
	ds_bpermute_b32 v90, v203, v96
	ds_bpermute_b32 v91, v203, v97
	v_pk_fma_f32 v[64:65], v[52:53], v[64:65], v[92:93]
	v_pk_mul_f32 v[92:93], v[176:177], v[62:63]
	v_pk_mul_f32 v[94:95], v[174:175], v[64:65]
	global_store_dwordx4 v[114:115], v[62:65], off nt
	v_cvt_pk_bf16_f32 v92, v92, v93
	v_cvt_pk_bf16_f32 v93, v94, v95
	v_lshlrev_b32_e32 v94, 1, v104
	s_waitcnt lgkmcnt(0)
	v_add_u32_e32 v250, 0xfffff040, v94
	v_cndmask_b32_e64 v250, v94, v250, s[40:41]
	v_cndmask_b32_e64 v248, v102, v90, s[40:41]
	v_cndmask_b32_e64 v249, v103, v91, s[40:41]
	global_store_dwordx2 v250, v[248:249], s[46:47]
	v_cndmask_b32_e64 v246, v90, v102, s[40:41]
	v_cndmask_b32_e64 v247, v91, v103, s[40:41]
	s_waitcnt lgkmcnt(1)
	v_add_u32_e32 v90, 0x1040, v94
	v_cndmask_b32_e64 v90, v94, v90, s[38:39]
	global_store_dwordx2 v90, v[246:247], s[46:47]
	ds_bpermute_b32 v90, v203, v92
	s_waitcnt lgkmcnt(1)
	ds_bpermute_b32 v91, v203, v93
	v_lshlrev_b32_e32 v92, 1, v100
	s_waitcnt lgkmcnt(0)
	v_add_u32_e32 v250, 0xfffff040, v92
	v_cndmask_b32_e64 v250, v92, v250, s[40:41]
	v_cndmask_b32_e64 v248, v98, v90, s[40:41]
	v_cndmask_b32_e64 v249, v99, v91, s[40:41]
	global_store_dwordx2 v250, v[248:249], s[46:47]
	v_cndmask_b32_e64 v246, v90, v98, s[40:41]
	v_cndmask_b32_e64 v247, v91, v99, s[40:41]
	v_mul_f32_e32 v59, v59, v59
	v_fmac_f32_e32 v59, v58, v58
	v_mul_f32_e32 v58, v61, v61
	v_mul_f32_e32 v69, v69, v69
	v_fmac_f32_e32 v58, v60, v60
	v_mul_f32_e32 v67, v67, v67
	v_fmac_f32_e32 v69, v68, v68
	v_mul_f32_e32 v68, v71, v71
	v_mul_f32_e32 v71, v73, v73
	v_add_f32_e32 v58, v59, v58
	v_mul_f32_e32 v59, v63, v63
	v_mul_f32_e32 v60, v65, v65
	v_fmac_f32_e32 v71, v72, v72
	v_fmac_f32_e32 v59, v62, v62
	v_fmac_f32_e32 v60, v64, v64
	v_fmac_f32_e32 v67, v66, v66
	v_fmac_f32_e32 v68, v70, v70
	v_add_f32_e32 v59, v59, v60
	v_add_f32_e32 v60, v67, v69
	v_add_f32_e32 v61, v68, v71
	v_add_f32_e32 v58, v60, v58
	v_add_f32_e32 v59, v61, v59
	ds_bpermute_b32 v60, v190, v58
	ds_bpermute_b32 v61, v190, v59
	s_waitcnt lgkmcnt(1)
	v_add_f32_e32 v58, v58, v60
	s_waitcnt lgkmcnt(0)
	v_add_f32_e32 v61, v59, v61
	ds_bpermute_b32 v60, v191, v58
	ds_bpermute_b32 v62, v191, v61
	s_waitcnt lgkmcnt(1)
	v_add_f32_e32 v58, v58, v60
	s_waitcnt lgkmcnt(0)
	v_add_f32_e32 v60, v61, v62
	ds_bpermute_b32 v59, v204, v58
	ds_bpermute_b32 v61, v204, v60
	v_add_u32_e32 v62, 0x1040, v92
	v_cndmask_b32_e64 v62, v92, v62, s[38:39]
	global_store_dwordx2 v62, v[246:247], s[46:47]
	s_and_saveexec_b64 s[16:17], s[42:43]
	s_cbranch_execz .LBB0_1303
	s_waitcnt lgkmcnt(1)
	v_add_f32_e32 v58, v58, v59
	s_waitcnt lgkmcnt(0)
	v_add_f32_e32 v59, v60, v61
	ds_write2_b32 v194, v58, v59 offset0:64 offset1:72
; #define LAS __attribute__((address_space(3)))
; #define ERN_EOFF(q, m) (eb + (unsigned)((((q) & 1) * HALF + (m) * 16) * DM + ERN_COL((q) >> 1)))
;     __device__ __forceinline__ void operator()(const f32x4 (&acc)[2][2][4][2], const Unit& u, int wr, int wc, int fr, int fq) const {
;     ...
;         for (int g = 0; g < 8; ++g) { const int ai = g >> 2, m = g & 3;
;             if (g + 1 < 8) ERN_LOADX(g + 1);
;             float sq0 = 0.f, sq1 = 0.f; u32x2 hw[2][2];
; #pragma unroll
;             for (int bj = 0; bj < 2; ++bj) {
;                 *(LAS f32x4*)(st + wr_off) = acc[ai][bj][m][0]; *(LAS f32x4*)(st + wr_off + 64) = acc[ai][bj][m][1];
;                 const f32x4 a0 = *(const LAS f32x4*)(st + rd_off), a1 = *(const LAS f32x4*)(st + rd_off + 8 * 144);
;                 { const f32x4 xv = xb[g & 1][bj][0] + gv[bj] * a0; __builtin_nontemporal_store(xv, (f32x4*)((char*)xo + 4u * ERN_EOFF(g, bj, 0)));
;                   sq0 += (xv.x * xv.x + xv.y * xv.y) + (xv.z * xv.z + xv.w * xv.w);
;                   const f32x4 hv = xv * gsn[bj]; hw[bj][0].x = cvt_pk_bf16(hv.x, hv.y); hw[bj][0].y = cvt_pk_bf16(hv.z, hv.w); }
;                 { const f32x4 xv = xb[g & 1][bj][1] + gv[bj] * a1; __builtin_nontemporal_store(xv, (f32x4*)((char*)xo + 4u * ERN_EOFF(g, bj, 1)));
;                   sq1 += (xv.x * xv.x + xv.y * xv.y) + (xv.z * xv.z + xv.w * xv.w);
;                   const f32x4 hv = xv * gsn[bj]; hw[bj][1].x = cvt_pk_bf16(hv.x, hv.y); hw[bj][1].y = cvt_pk_bf16(hv.z, hv.w); }
;             }
;             if (!NOH && !PLAIN) {
; #pragma unroll
;                 for (int rh = 0; rh < 2; ++rh) { u32x2 rv; rv.x = __shfl_xor(hw[1][rh].x, 8); rv.y = __shfl_xor(hw[1][rh].y, 8);
;                     const unsigned e0 = ERN_EOFF(g, 0, rh);
;                     const unsigned ee = odd ? (e0 - DM + 32) : e0, eo2 = odd ? e0 : (e0 + DM + 32);
;                     *(u32x2*)((char*)ho + 2u * ee) = odd ? rv : hw[0][rh];
;                     *(u32x2*)((char*)ho + 2u * eo2) = odd ? hw[0][rh] : rv; }
;             }
;             if (!PLAIN) { sq0 += __shfl_xor(sq0, 1); sq0 += __shfl_xor(sq0, 2); sq0 += __shfl_xor(sq0, 4);
;             sq1 += __shfl_xor(sq1, 1); sq1 += __shfl_xor(sq1, 2); sq1 += __shfl_xor(sq1, 4); }
;             if (!PLAIN && pc == 0) { sst[g * 16 + rr] = sq0; sst[g * 16 + 8 + rr] = sq1; }
.LBB0_1303:
	s_or_b64 exec, exec, s[16:17]
	v_lshl_add_u64 v[96:97], s[48:49], 0, v[162:163]
	v_add_u32_e32 v162, 0x140000, v205
	v_add_u32_e32 v92, 0x140080, v205
	v_add_u32_e32 v94, 0x150000, v205
	global_load_dwordx4 v[70:73], v162, s[48:49]
	global_load_dwordx4 v[66:69], v94, s[48:49]
	v_add_u32_e32 v90, 0x150080, v205
	global_load_dwordx4 v[62:65], v92, s[48:49]
	s_waitcnt lgkmcnt(0)
	global_load_dwordx4 v[58:61], v90, s[48:49]
	ds_write_b128 v200, v[46:49]
	ds_write_b128 v200, v[42:45] offset:64
	ds_read_b128 v[42:45], v201
	ds_read_b128 v[46:49], v201 offset:1152
	v_mov_b32_e32 v111, v163
	v_lshl_add_u64 v[98:99], s[48:49], 0, v[110:111]
	v_mov_b32_e32 v109, v163
	s_waitcnt vmcnt(14) lgkmcnt(1)
	v_pk_fma_f32 v[42:43], v[54:55], v[42:43], v[86:87]
	s_waitcnt vmcnt(13) lgkmcnt(0)
	v_pk_fma_f32 v[46:47], v[54:55], v[46:47], v[82:83]
	v_pk_fma_f32 v[44:45], v[56:57], v[44:45], v[88:89]
	v_pk_mul_f32 v[86:87], v[180:181], v[42:43]
	v_pk_fma_f32 v[48:49], v[56:57], v[48:49], v[84:85]
	v_pk_mul_f32 v[82:83], v[180:181], v[46:47]
	global_store_dwordx4 v[96:97], v[42:45], off nt
	v_pk_mul_f32 v[88:89], v[178:179], v[44:45]
	v_cvt_pk_bf16_f32 v86, v86, v87
	v_pk_mul_f32 v[84:85], v[178:179], v[48:49]
	v_cvt_pk_bf16_f32 v87, v88, v89
	global_store_dwordx4 v[98:99], v[46:49], off nt
	v_cvt_pk_bf16_f32 v82, v82, v83
	v_cvt_pk_bf16_f32 v83, v84, v85
	ds_write_b128 v200, v[38:41]
	ds_write_b128 v200, v[34:37] offset:64
	ds_read_b128 v[34:37], v201
	ds_read_b128 v[38:41], v201 offset:1152
	v_lshl_add_u64 v[84:85], s[48:49], 0, v[108:109]
	v_mov_b32_e32 v107, v163
	v_lshl_add_u64 v[88:89], s[48:49], 0, v[106:107]
	s_waitcnt vmcnt(14) lgkmcnt(1)
	v_pk_fma_f32 v[34:35], v[50:51], v[34:35], v[78:79]
	v_pk_fma_f32 v[36:37], v[52:53], v[36:37], v[80:81]
	v_pk_mul_f32 v[80:81], v[176:177], v[34:35]
	global_store_dwordx4 v[84:85], v[34:37], off nt
	v_pk_mul_f32 v[78:79], v[174:175], v[36:37]
	v_cvt_pk_bf16_f32 v80, v80, v81
	s_waitcnt vmcnt(14) lgkmcnt(0)
	v_pk_fma_f32 v[38:39], v[50:51], v[38:39], v[74:75]
	v_cvt_pk_bf16_f32 v81, v78, v79
	ds_bpermute_b32 v74, v203, v80
	ds_bpermute_b32 v75, v203, v81
	v_pk_fma_f32 v[40:41], v[52:53], v[40:41], v[76:77]
	v_pk_mul_f32 v[76:77], v[176:177], v[38:39]
	v_pk_mul_f32 v[78:79], v[174:175], v[40:41]
	global_store_dwordx4 v[88:89], v[38:41], off nt
	v_cvt_pk_bf16_f32 v76, v76, v77
	v_cvt_pk_bf16_f32 v77, v78, v79
	v_add_u32_e32 v79, 0x48000, v202
	v_lshlrev_b32_e32 v78, 1, v79
	s_waitcnt lgkmcnt(0)
	v_add_u32_e32 v250, 0xfffff040, v78
	v_cndmask_b32_e64 v250, v78, v250, s[40:41]
	v_cndmask_b32_e64 v248, v86, v74, s[40:41]
	v_cndmask_b32_e64 v249, v87, v75, s[40:41]
	global_store_dwordx2 v250, v[248:249], s[46:47]
	v_cndmask_b32_e64 v246, v74, v86, s[40:41]
	v_cndmask_b32_e64 v247, v75, v87, s[40:41]
	s_waitcnt lgkmcnt(1)
	v_add_u32_e32 v74, 0x1040, v78
	v_cndmask_b32_e64 v74, v78, v74, s[38:39]
	global_store_dwordx2 v74, v[246:247], s[46:47]
	ds_bpermute_b32 v74, v203, v76
	s_waitcnt lgkmcnt(1)
	ds_bpermute_b32 v75, v203, v77
	v_add_u32_e32 v77, 0x4c000, v202
	v_lshlrev_b32_e32 v76, 1, v77
	s_waitcnt lgkmcnt(0)
	v_add_u32_e32 v250, 0xfffff040, v76
	v_cndmask_b32_e64 v250, v76, v250, s[40:41]
	v_cndmask_b32_e64 v248, v82, v74, s[40:41]
	v_cndmask_b32_e64 v249, v83, v75, s[40:41]
	global_store_dwordx2 v250, v[248:249], s[46:47]
	v_cndmask_b32_e64 v246, v74, v82, s[40:41]
	v_cndmask_b32_e64 v247, v75, v83, s[40:41]
	v_mul_f32_e32 v35, v35, v35
	v_fmac_f32_e32 v35, v34, v34
	v_mul_f32_e32 v34, v37, v37
	v_mul_f32_e32 v45, v45, v45
	v_fmac_f32_e32 v34, v36, v36
	v_mul_f32_e32 v43, v43, v43
	v_fmac_f32_e32 v45, v44, v44
	v_mul_f32_e32 v44, v47, v47
	v_mul_f32_e32 v47, v49, v49
	v_add_f32_e32 v34, v35, v34
	v_mul_f32_e32 v35, v39, v39
	v_mul_f32_e32 v36, v41, v41
	v_fmac_f32_e32 v47, v48, v48
	v_fmac_f32_e32 v35, v38, v38
	v_fmac_f32_e32 v36, v40, v40
	v_fmac_f32_e32 v43, v42, v42
	v_fmac_f32_e32 v44, v46, v46
	v_add_f32_e32 v35, v35, v36
	v_add_f32_e32 v36, v43, v45
	v_add_f32_e32 v37, v44, v47
	v_add_f32_e32 v34, v36, v34
	v_add_f32_e32 v35, v37, v35
	ds_bpermute_b32 v36, v190, v34
	ds_bpermute_b32 v37, v190, v35
	s_waitcnt lgkmcnt(1)
	v_add_f32_e32 v34, v34, v36
	s_waitcnt lgkmcnt(0)
	v_add_f32_e32 v37, v35, v37
	ds_bpermute_b32 v36, v191, v34
	ds_bpermute_b32 v38, v191, v37
	s_waitcnt lgkmcnt(1)
	v_add_f32_e32 v34, v34, v36
	s_waitcnt lgkmcnt(0)
	v_add_f32_e32 v36, v37, v38
	ds_bpermute_b32 v35, v204, v34
	ds_bpermute_b32 v37, v204, v36
	v_add_u32_e32 v38, 0x1040, v76
	v_cndmask_b32_e64 v38, v76, v38, s[38:39]
	global_store_dwordx2 v38, v[246:247], s[46:47]
	s_and_saveexec_b64 s[16:17], s[42:43]
	s_cbranch_execz .LBB0_1313
	s_waitcnt lgkmcnt(1)
	v_add_f32_e32 v34, v34, v35
	s_waitcnt lgkmcnt(0)
	v_add_f32_e32 v35, v36, v37
	ds_write2_b32 v194, v34, v35 offset0:80 offset1:88
; #define LAS __attribute__((address_space(3)))
; #define ERN_EOFF(q, m) (eb + (unsigned)((((q) & 1) * HALF + (m) * 16) * DM + ERN_COL((q) >> 1)))
;     __device__ __forceinline__ void operator()(const f32x4 (&acc)[2][2][4][2], const Unit& u, int wr, int wc, int fr, int fq) const {
;     ...
;         for (int g = 0; g < 8; ++g) { const int ai = g >> 2, m = g & 3;
;             if (g + 1 < 8) ERN_LOADX(g + 1);
;             float sq0 = 0.f, sq1 = 0.f; u32x2 hw[2][2];
; #pragma unroll
;             for (int bj = 0; bj < 2; ++bj) {
;                 *(LAS f32x4*)(st + wr_off) = acc[ai][bj][m][0]; *(LAS f32x4*)(st + wr_off + 64) = acc[ai][bj][m][1];
;                 const f32x4 a0 = *(const LAS f32x4*)(st + rd_off), a1 = *(const LAS f32x4*)(st + rd_off + 8 * 144);
;                 { const f32x4 xv = xb[g & 1][bj][0] + gv[bj] * a0; __builtin_nontemporal_store(xv, (f32x4*)((char*)xo + 4u * ERN_EOFF(g, bj, 0)));
;                   sq0 += (xv.x * xv.x + xv.y * xv.y) + (xv.z * xv.z + xv.w * xv.w);
;                   const f32x4 hv = xv * gsn[bj]; hw[bj][0].x = cvt_pk_bf16(hv.x, hv.y); hw[bj][0].y = cvt_pk_bf16(hv.z, hv.w); }
;                 { const f32x4 xv = xb[g & 1][bj][1] + gv[bj] * a1; __builtin_nontemporal_store(xv, (f32x4*)((char*)xo + 4u * ERN_EOFF(g, bj, 1)));
;                   sq1 += (xv.x * xv.x + xv.y * xv.y) + (xv.z * xv.z + xv.w * xv.w);
;                   const f32x4 hv = xv * gsn[bj]; hw[bj][1].x = cvt_pk_bf16(hv.x, hv.y); hw[bj][1].y = cvt_pk_bf16(hv.z, hv.w); }
;             }
;             if (!NOH && !PLAIN) {
; #pragma unroll
;                 for (int rh = 0; rh < 2; ++rh) { u32x2 rv; rv.x = __shfl_xor(hw[1][rh].x, 8); rv.y = __shfl_xor(hw[1][rh].y, 8);
;                     const unsigned e0 = ERN_EOFF(g, 0, rh);
;                     const unsigned ee = odd ? (e0 - DM + 32) : e0, eo2 = odd ? e0 : (e0 + DM + 32);
;                     *(u32x2*)((char*)ho + 2u * ee) = odd ? rv : hw[0][rh];
;                     *(u32x2*)((char*)ho + 2u * eo2) = odd ? hw[0][rh] : rv; }
;             }
;             if (!PLAIN) { sq0 += __shfl_xor(sq0, 1); sq0 += __shfl_xor(sq0, 2); sq0 += __shfl_xor(sq0, 4);
;             sq1 += __shfl_xor(sq1, 1); sq1 += __shfl_xor(sq1, 2); sq1 += __shfl_xor(sq1, 4); }
;             if (!PLAIN && pc == 0) { sst[g * 16 + rr] = sq0; sst[g * 16 + 8 + rr] = sq1; }
.LBB0_1313:
	s_or_b64 exec, exec, s[16:17]
	v_lshl_add_u64 v[80:81], s[48:49], 0, v[162:163]
	v_add_u32_e32 v162, 0x160000, v205
	v_add_u32_e32 v76, 0x160080, v205
	v_add_u32_e32 v78, 0x170000, v205
	global_load_dwordx4 v[46:49], v162, s[48:49]
	global_load_dwordx4 v[42:45], v78, s[48:49]
	v_add_u32_e32 v74, 0x170080, v205
	global_load_dwordx4 v[38:41], v76, s[48:49]
	s_waitcnt lgkmcnt(0)
	global_load_dwordx4 v[34:37], v74, s[48:49]
	ds_write_b128 v200, v[30:33]
	ds_write_b128 v200, v[26:29] offset:64
	ds_read_b128 v[26:29], v201
	ds_read_b128 v[30:33], v201 offset:1152
	v_mov_b32_e32 v95, v163
	v_lshl_add_u64 v[82:83], s[48:49], 0, v[94:95]
	v_mov_b32_e32 v93, v163
	s_waitcnt vmcnt(14) lgkmcnt(1)
	v_pk_fma_f32 v[26:27], v[54:55], v[26:27], v[70:71]
	s_waitcnt vmcnt(13) lgkmcnt(0)
	v_pk_fma_f32 v[30:31], v[54:55], v[30:31], v[66:67]
	v_pk_fma_f32 v[28:29], v[56:57], v[28:29], v[72:73]
	v_pk_mul_f32 v[70:71], v[180:181], v[26:27]
	v_pk_fma_f32 v[32:33], v[56:57], v[32:33], v[68:69]
	v_pk_mul_f32 v[66:67], v[180:181], v[30:31]
	global_store_dwordx4 v[80:81], v[26:29], off nt
	v_pk_mul_f32 v[72:73], v[178:179], v[28:29]
	v_cvt_pk_bf16_f32 v70, v70, v71
	v_pk_mul_f32 v[68:69], v[178:179], v[32:33]
	v_cvt_pk_bf16_f32 v71, v72, v73
	global_store_dwordx4 v[82:83], v[30:33], off nt
	v_cvt_pk_bf16_f32 v66, v66, v67
	v_cvt_pk_bf16_f32 v67, v68, v69
	ds_write_b128 v200, v[22:25]
	ds_write_b128 v200, v[18:21] offset:64
	ds_read_b128 v[18:21], v201
	ds_read_b128 v[22:25], v201 offset:1152
	v_lshl_add_u64 v[68:69], s[48:49], 0, v[92:93]
	v_mov_b32_e32 v91, v163
	v_lshl_add_u64 v[72:73], s[48:49], 0, v[90:91]
	s_waitcnt vmcnt(14) lgkmcnt(1)
	v_pk_fma_f32 v[18:19], v[50:51], v[18:19], v[62:63]
	v_pk_fma_f32 v[20:21], v[52:53], v[20:21], v[64:65]
	v_pk_mul_f32 v[64:65], v[176:177], v[18:19]
	global_store_dwordx4 v[68:69], v[18:21], off nt
	v_pk_mul_f32 v[62:63], v[174:175], v[20:21]
	v_cvt_pk_bf16_f32 v64, v64, v65
	s_waitcnt vmcnt(14) lgkmcnt(0)
	v_pk_fma_f32 v[22:23], v[50:51], v[22:23], v[58:59]
	v_cvt_pk_bf16_f32 v65, v62, v63
	ds_bpermute_b32 v58, v203, v64
	ds_bpermute_b32 v59, v203, v65
	v_pk_fma_f32 v[24:25], v[52:53], v[24:25], v[60:61]
	v_pk_mul_f32 v[60:61], v[176:177], v[22:23]
	v_pk_mul_f32 v[62:63], v[174:175], v[24:25]
	global_store_dwordx4 v[72:73], v[22:25], off nt
	v_cvt_pk_bf16_f32 v60, v60, v61
	v_cvt_pk_bf16_f32 v61, v62, v63
	v_add_u32_e32 v63, 0x50000, v202
	v_lshlrev_b32_e32 v62, 1, v63
	s_waitcnt lgkmcnt(0)
	v_add_u32_e32 v250, 0xfffff040, v62
	v_cndmask_b32_e64 v250, v62, v250, s[40:41]
	v_cndmask_b32_e64 v248, v70, v58, s[40:41]
	v_cndmask_b32_e64 v249, v71, v59, s[40:41]
	global_store_dwordx2 v250, v[248:249], s[46:47]
	v_cndmask_b32_e64 v246, v58, v70, s[40:41]
	v_cndmask_b32_e64 v247, v59, v71, s[40:41]
	s_waitcnt lgkmcnt(1)
	v_add_u32_e32 v58, 0x1040, v62
	v_cndmask_b32_e64 v58, v62, v58, s[38:39]
	global_store_dwordx2 v58, v[246:247], s[46:47]
	ds_bpermute_b32 v58, v203, v60
	s_waitcnt lgkmcnt(1)
	ds_bpermute_b32 v59, v203, v61
	v_add_u32_e32 v61, 0x54000, v202
	v_lshlrev_b32_e32 v60, 1, v61
	s_waitcnt lgkmcnt(0)
	v_add_u32_e32 v250, 0xfffff040, v60
	v_cndmask_b32_e64 v250, v60, v250, s[40:41]
	v_cndmask_b32_e64 v248, v66, v58, s[40:41]
	v_cndmask_b32_e64 v249, v67, v59, s[40:41]
	global_store_dwordx2 v250, v[248:249], s[46:47]
	v_cndmask_b32_e64 v246, v58, v66, s[40:41]
	v_cndmask_b32_e64 v247, v59, v67, s[40:41]
	v_mul_f32_e32 v19, v19, v19
	v_fmac_f32_e32 v19, v18, v18
	v_mul_f32_e32 v18, v21, v21
	v_mul_f32_e32 v29, v29, v29
	v_fmac_f32_e32 v18, v20, v20
	v_mul_f32_e32 v27, v27, v27
	v_fmac_f32_e32 v29, v28, v28
	v_mul_f32_e32 v28, v31, v31
	v_mul_f32_e32 v31, v33, v33
	v_add_f32_e32 v18, v19, v18
	v_mul_f32_e32 v19, v23, v23
	v_mul_f32_e32 v20, v25, v25
	v_fmac_f32_e32 v31, v32, v32
	v_fmac_f32_e32 v19, v22, v22
	v_fmac_f32_e32 v20, v24, v24
	v_fmac_f32_e32 v27, v26, v26
	v_fmac_f32_e32 v28, v30, v30
	v_add_f32_e32 v19, v19, v20
	v_add_f32_e32 v20, v27, v29
	v_add_f32_e32 v21, v28, v31
	v_add_f32_e32 v18, v20, v18
	v_add_f32_e32 v19, v21, v19
	ds_bpermute_b32 v20, v190, v18
	ds_bpermute_b32 v21, v190, v19
	s_waitcnt lgkmcnt(1)
	v_add_f32_e32 v18, v18, v20
	s_waitcnt lgkmcnt(0)
	v_add_f32_e32 v21, v19, v21
	ds_bpermute_b32 v20, v191, v18
	ds_bpermute_b32 v22, v191, v21
	s_waitcnt lgkmcnt(1)
	v_add_f32_e32 v18, v18, v20
	s_waitcnt lgkmcnt(0)
	v_add_f32_e32 v20, v21, v22
	ds_bpermute_b32 v19, v204, v18
	ds_bpermute_b32 v21, v204, v20
	v_add_u32_e32 v22, 0x1040, v60
	v_cndmask_b32_e64 v22, v60, v22, s[38:39]
	global_store_dwordx2 v22, v[246:247], s[46:47]
	s_and_saveexec_b64 s[16:17], s[42:43]
	s_cbranch_execz .LBB0_1323
	s_waitcnt lgkmcnt(1)
	v_add_f32_e32 v18, v18, v19
	s_waitcnt lgkmcnt(0)
	v_add_f32_e32 v19, v20, v21
	ds_write2_b32 v194, v18, v19 offset0:96 offset1:104
; #define LAS __attribute__((address_space(3)))
; #define ERN_EOFF(q, m) (eb + (unsigned)((((q) & 1) * HALF + (m) * 16) * DM + ERN_COL((q) >> 1)))
;     __device__ __forceinline__ void operator()(const f32x4 (&acc)[2][2][4][2], const Unit& u, int wr, int wc, int fr, int fq) const {
;     ...
;         for (int g = 0; g < 8; ++g) { const int ai = g >> 2, m = g & 3;
;             if (g + 1 < 8) ERN_LOADX(g + 1);
;             float sq0 = 0.f, sq1 = 0.f; u32x2 hw[2][2];
; #pragma unroll
;             for (int bj = 0; bj < 2; ++bj) {
;                 *(LAS f32x4*)(st + wr_off) = acc[ai][bj][m][0]; *(LAS f32x4*)(st + wr_off + 64) = acc[ai][bj][m][1];
;                 const f32x4 a0 = *(const LAS f32x4*)(st + rd_off), a1 = *(const LAS f32x4*)(st + rd_off + 8 * 144);
;                 { const f32x4 xv = xb[g & 1][bj][0] + gv[bj] * a0; __builtin_nontemporal_store(xv, (f32x4*)((char*)xo + 4u * ERN_EOFF(g, bj, 0)));
;                   sq0 += (xv.x * xv.x + xv.y * xv.y) + (xv.z * xv.z + xv.w * xv.w);
;                   const f32x4 hv = xv * gsn[bj]; hw[bj][0].x = cvt_pk_bf16(hv.x, hv.y); hw[bj][0].y = cvt_pk_bf16(hv.z, hv.w); }
;                 { const f32x4 xv = xb[g & 1][bj][1] + gv[bj] * a1; __builtin_nontemporal_store(xv, (f32x4*)((char*)xo + 4u * ERN_EOFF(g, bj, 1)));
;                   sq1 += (xv.x * xv.x + xv.y * xv.y) + (xv.z * xv.z + xv.w * xv.w);
;                   const f32x4 hv = xv * gsn[bj]; hw[bj][1].x = cvt_pk_bf16(hv.x, hv.y); hw[bj][1].y = cvt_pk_bf16(hv.z, hv.w); }
;             }
;             if (!NOH && !PLAIN) {
; #pragma unroll
;                 for (int rh = 0; rh < 2; ++rh) { u32x2 rv; rv.x = __shfl_xor(hw[1][rh].x, 8); rv.y = __shfl_xor(hw[1][rh].y, 8);
;                     const unsigned e0 = ERN_EOFF(g, 0, rh);
;                     const unsigned ee = odd ? (e0 - DM + 32) : e0, eo2 = odd ? e0 : (e0 + DM + 32);
;                     *(u32x2*)((char*)ho + 2u * ee) = odd ? rv : hw[0][rh];
;                     *(u32x2*)((char*)ho + 2u * eo2) = odd ? hw[0][rh] : rv; }
;             }
;             if (!PLAIN) { sq0 += __shfl_xor(sq0, 1); sq0 += __shfl_xor(sq0, 2); sq0 += __shfl_xor(sq0, 4);
;             sq1 += __shfl_xor(sq1, 1); sq1 += __shfl_xor(sq1, 2); sq1 += __shfl_xor(sq1, 4); }
;             if (!PLAIN && pc == 0) { sst[g * 16 + rr] = sq0; sst[g * 16 + 8 + rr] = sq1; }
.LBB0_1323:
	s_or_b64 exec, exec, s[16:17]
	ds_write_b128 v200, v[14:17]
	ds_write_b128 v200, v[10:13] offset:64
	ds_read_b128 v[10:13], v201
	ds_read_b128 v[14:17], v201 offset:1152
	s_waitcnt lgkmcnt(5)
	v_lshl_add_u64 v[18:19], s[48:49], 0, v[162:163]
	v_mov_b32_e32 v79, v163
	v_lshl_add_u64 v[22:23], s[48:49], 0, v[78:79]
	s_waitcnt vmcnt(10) lgkmcnt(1)
	v_pk_fma_f32 v[12:13], v[56:57], v[12:13], v[48:49]
	v_pk_fma_f32 v[10:11], v[54:55], v[10:11], v[46:47]
	global_store_dwordx4 v[18:19], v[10:13], off nt
	v_pk_mul_f32 v[18:19], v[178:179], v[12:13]
	v_pk_mul_f32 v[20:21], v[180:181], v[10:11]
	s_waitcnt vmcnt(10) lgkmcnt(0)
	v_pk_fma_f32 v[14:15], v[54:55], v[14:15], v[42:43]
	v_cvt_pk_bf16_f32 v20, v20, v21
	v_cvt_pk_bf16_f32 v21, v18, v19
	v_pk_fma_f32 v[16:17], v[56:57], v[16:17], v[44:45]
	v_pk_mul_f32 v[18:19], v[180:181], v[14:15]
	global_store_dwordx4 v[22:23], v[14:17], off nt
	v_pk_mul_f32 v[22:23], v[178:179], v[16:17]
	v_cvt_pk_bf16_f32 v18, v18, v19
	v_mov_b32_e32 v77, v163
	v_cvt_pk_bf16_f32 v19, v22, v23
	ds_write_b128 v200, v[6:9]
	ds_write_b128 v200, v[2:5] offset:64
	ds_read_b128 v[2:5], v201
	ds_read_b128 v[6:9], v201 offset:1152
	v_lshl_add_u64 v[22:23], s[48:49], 0, v[76:77]
	v_mov_b32_e32 v75, v163
	v_lshl_add_u64 v[24:25], s[48:49], 0, v[74:75]
	s_waitcnt vmcnt(10) lgkmcnt(1)
	v_pk_fma_f32 v[4:5], v[52:53], v[4:5], v[40:41]
	v_pk_fma_f32 v[2:3], v[50:51], v[2:3], v[38:39]
	global_store_dwordx4 v[22:23], v[2:5], off nt
	v_pk_mul_f32 v[22:23], v[174:175], v[4:5]
	v_pk_mul_f32 v[26:27], v[176:177], v[2:3]
	s_waitcnt vmcnt(10) lgkmcnt(0)
	v_pk_fma_f32 v[8:9], v[52:53], v[8:9], v[36:37]
	v_cvt_pk_bf16_f32 v28, v26, v27
	v_cvt_pk_bf16_f32 v23, v22, v23
	ds_bpermute_b32 v22, v203, v28
	ds_bpermute_b32 v23, v203, v23
	v_pk_fma_f32 v[6:7], v[50:51], v[6:7], v[34:35]
	global_store_dwordx4 v[24:25], v[6:9], off nt
	v_pk_mul_f32 v[26:27], v[174:175], v[8:9]
	v_pk_mul_f32 v[24:25], v[176:177], v[6:7]
	s_nop 0
	v_cvt_pk_bf16_f32 v24, v24, v25
	v_cvt_pk_bf16_f32 v25, v26, v27
	v_add_u32_e32 v27, 0x58000, v202
	v_lshlrev_b32_e32 v26, 1, v27
	s_waitcnt lgkmcnt(0)
	v_add_u32_e32 v250, 0xfffff040, v26
	v_cndmask_b32_e64 v250, v26, v250, s[40:41]
	v_cndmask_b32_e64 v248, v20, v22, s[40:41]
	v_cndmask_b32_e64 v249, v21, v23, s[40:41]
	global_store_dwordx2 v250, v[248:249], s[46:47]
	v_cndmask_b32_e64 v246, v22, v20, s[40:41]
	v_cndmask_b32_e64 v247, v23, v21, s[40:41]
	s_waitcnt lgkmcnt(1)
	v_add_u32_e32 v22, 0x1040, v26
	v_cndmask_b32_e64 v22, v26, v22, s[38:39]
	global_store_dwordx2 v22, v[246:247], s[46:47]
	ds_bpermute_b32 v20, v203, v24
	ds_bpermute_b32 v21, v203, v25
	s_waitcnt lgkmcnt(2)
	v_add_u32_e32 v23, 0x5c000, v202
	v_lshlrev_b32_e32 v22, 1, v23
	s_waitcnt lgkmcnt(0)
	v_add_u32_e32 v250, 0xfffff040, v22
	v_cndmask_b32_e64 v250, v22, v250, s[40:41]
	v_cndmask_b32_e64 v248, v18, v20, s[40:41]
	v_cndmask_b32_e64 v249, v19, v21, s[40:41]
	global_store_dwordx2 v250, v[248:249], s[46:47]
	v_cndmask_b32_e64 v246, v20, v18, s[40:41]
	v_cndmask_b32_e64 v247, v21, v19, s[40:41]
	v_mul_f32_e32 v3, v3, v3
	v_fmac_f32_e32 v3, v2, v2
	v_mul_f32_e32 v2, v5, v5
	v_mul_f32_e32 v13, v13, v13
	v_fmac_f32_e32 v2, v4, v4
	v_mul_f32_e32 v11, v11, v11
	v_fmac_f32_e32 v13, v12, v12
	v_mul_f32_e32 v12, v15, v15
	v_mul_f32_e32 v15, v17, v17
	v_add_f32_e32 v2, v3, v2
	v_mul_f32_e32 v3, v7, v7
	v_mul_f32_e32 v4, v9, v9
	v_fmac_f32_e32 v15, v16, v16
	v_fmac_f32_e32 v3, v6, v6
	v_fmac_f32_e32 v4, v8, v8
	v_fmac_f32_e32 v11, v10, v10
	v_fmac_f32_e32 v12, v14, v14
	v_add_f32_e32 v3, v3, v4
	v_add_f32_e32 v4, v11, v13
	v_add_f32_e32 v5, v12, v15
	v_add_f32_e32 v2, v4, v2
	v_add_f32_e32 v3, v5, v3
	ds_bpermute_b32 v4, v190, v2
	ds_bpermute_b32 v5, v190, v3
	s_waitcnt lgkmcnt(1)
	v_add_f32_e32 v2, v2, v4
	s_waitcnt lgkmcnt(0)
	v_add_f32_e32 v5, v3, v5
	ds_bpermute_b32 v4, v191, v2
	ds_bpermute_b32 v6, v191, v5
	s_waitcnt lgkmcnt(1)
	v_add_f32_e32 v2, v2, v4
	s_waitcnt lgkmcnt(0)
	v_add_f32_e32 v4, v5, v6
	ds_bpermute_b32 v3, v204, v2
	ds_bpermute_b32 v5, v204, v4
	v_add_u32_e32 v6, 0x1040, v22
	v_cndmask_b32_e64 v6, v22, v6, s[38:39]
	global_store_dwordx2 v6, v[246:247], s[46:47]
	s_and_saveexec_b64 s[16:17], s[42:43]
	s_cbranch_execz .LBB0_1333
	s_waitcnt lgkmcnt(1)
	v_add_f32_e32 v2, v2, v3
	s_waitcnt lgkmcnt(0)
	v_add_f32_e32 v3, v4, v5
	ds_write2_b32 v194, v2, v3 offset0:112 offset1:120

; #define LAS __attribute__((address_space(3)))
; #define ERN_EOFF(q, m) (eb + (unsigned)((((q) & 1) * HALF + (m) * 16) * DM + ERN_COL((q) >> 1)))
;     __device__ __forceinline__ void operator()(const f32x4 (&acc)[2][2][4][2], const Unit& u, int wr, int wc, int fr, int fq) const {
;     ...
;         for (int g = 0; g < 8; ++g) { const int ai = g >> 2, m = g & 3;
;             if (g + 1 < 8) ERN_LOADX(g + 1);
;             float sq0 = 0.f, sq1 = 0.f; u32x2 hw[2][2];
; #pragma unroll
;             for (int bj = 0; bj < 2; ++bj) {
;                 *(LAS f32x4*)(st + wr_off) = acc[ai][bj][m][0]; *(LAS f32x4*)(st + wr_off + 64) = acc[ai][bj][m][1];
;                 const f32x4 a0 = *(const LAS f32x4*)(st + rd_off), a1 = *(const LAS f32x4*)(st + rd_off + 8 * 144);
;                 { const f32x4 xv = xb[g & 1][bj][0] + gv[bj] * a0; __builtin_nontemporal_store(xv, (f32x4*)((char*)xo + 4u * ERN_EOFF(g, bj, 0)));
;                   sq0 += (xv.x * xv.x + xv.y * xv.y) + (xv.z * xv.z + xv.w * xv.w);
;                   const f32x4 hv = xv * gsn[bj]; hw[bj][0].x = cvt_pk_bf16(hv.x, hv.y); hw[bj][0].y = cvt_pk_bf16(hv.z, hv.w); }
;                 { const f32x4 xv = xb[g & 1][bj][1] + gv[bj] * a1; __builtin_nontemporal_store(xv, (f32x4*)((char*)xo + 4u * ERN_EOFF(g, bj, 1)));
;                   sq1 += (xv.x * xv.x + xv.y * xv.y) + (xv.z * xv.z + xv.w * xv.w);
;                   const f32x4 hv = xv * gsn[bj]; hw[bj][1].x = cvt_pk_bf16(hv.x, hv.y); hw[bj][1].y = cvt_pk_bf16(hv.z, hv.w); }
;             }
;             if (!NOH && !PLAIN) {
; #pragma unroll
;                 for (int rh = 0; rh < 2; ++rh) { u32x2 rv; rv.x = __shfl_xor(hw[1][rh].x, 8); rv.y = __shfl_xor(hw[1][rh].y, 8);
;                     const unsigned e0 = ERN_EOFF(g, 0, rh);
;                     const unsigned ee = odd ? (e0 - DM + 32) : e0, eo2 = odd ? e0 : (e0 + DM + 32);
;                     *(u32x2*)((char*)ho + 2u * ee) = odd ? rv : hw[0][rh];
;                     *(u32x2*)((char*)ho + 2u * eo2) = odd ? hw[0][rh] : rv; }
;             }
;             if (!PLAIN) { sq0 += __shfl_xor(sq0, 1); sq0 += __shfl_xor(sq0, 2); sq0 += __shfl_xor(sq0, 4);
;             sq1 += __shfl_xor(sq1, 1); sq1 += __shfl_xor(sq1, 2); sq1 += __shfl_xor(sq1, 4); }
;             if (!PLAIN && pc == 0) { sst[g * 16 + rr] = sq0; sst[g * 16 + 8 + rr] = sq1; }
.LBB0_1618:
	s_or_b64 exec, exec, s[16:17]
	v_lshl_add_u64 v[134:135], s[22:23], 0, v[154:155]
	v_add_u32_e32 v98, 0x60000, v205
	v_add_u32_e32 v154, 0x70000, v205
	v_add_u32_e32 v130, 0x60080, v205
	global_load_dwordx4 v[106:109], v154, s[22:23]
	global_load_dwordx4 v[102:105], v130, s[22:23]
	v_add_u32_e32 v132, 0x70080, v205
	global_load_dwordx4 v[110:113], v98, s[22:23]
	s_waitcnt lgkmcnt(0)
	global_load_dwordx4 v[98:101], v132, s[22:23]
	ds_write_b128 v200, v[94:97]
	ds_write_b128 v200, v[90:93] offset:64
	ds_read_b128 v[90:93], v201
	ds_read_b128 v[94:97], v201 offset:1152
	v_mov_b32_e32 v187, v155
	v_mov_b32_e32 v189, v155
	s_waitcnt vmcnt(12) lgkmcnt(1)
	v_pk_fma_f32 v[92:93], v[176:177], v[92:93], v[128:129]
	v_add_u32_e32 v128, 0x10000, v202
	v_pk_fma_f32 v[90:91], v[180:181], v[90:91], v[126:127]
	v_lshlrev_b32_e32 v126, 2, v128
	s_waitcnt lgkmcnt(0)
	v_pk_fma_f32 v[94:95], v[180:181], v[94:95], v[122:123]
	global_store_dwordx4 v126, v[90:93], s[22:23] nt
	v_pk_mul_f32 v[126:127], v[178:179], v[90:91]
	v_pk_fma_f32 v[96:97], v[176:177], v[96:97], v[124:125]
	v_pk_mul_f32 v[122:123], v[178:179], v[94:95]
	v_pk_mul_f32 v[136:137], v[174:175], v[92:93]
	v_cvt_pk_bf16_f32 v126, v126, v127
	v_pk_mul_f32 v[124:125], v[174:175], v[96:97]
	v_cvt_pk_bf16_f32 v127, v136, v137
	global_store_dwordx4 v[134:135], v[94:97], off nt
	v_cvt_pk_bf16_f32 v122, v122, v123
	v_cvt_pk_bf16_f32 v123, v124, v125
	ds_write_b128 v200, v[86:89]
	ds_write_b128 v200, v[82:85] offset:64
	ds_read_b128 v[82:85], v201
	ds_read_b128 v[86:89], v201 offset:1152
	v_lshl_add_u64 v[124:125], s[22:23], 0, v[186:187]
	v_lshl_add_u64 v[134:135], s[22:23], 0, v[188:189]
	s_waitcnt lgkmcnt(1)
	v_pk_fma_f32 v[82:83], v[168:169], v[82:83], v[118:119]
	v_pk_fma_f32 v[84:85], v[166:167], v[84:85], v[120:121]
	v_pk_mul_f32 v[120:121], v[172:173], v[82:83]
	global_store_dwordx4 v[124:125], v[82:85], off nt
	v_pk_mul_f32 v[118:119], v[170:171], v[84:85]
	v_cvt_pk_bf16_f32 v120, v120, v121
	s_waitcnt vmcnt(14) lgkmcnt(0)
	v_pk_fma_f32 v[86:87], v[168:169], v[86:87], v[114:115]
	v_cvt_pk_bf16_f32 v121, v118, v119
	ds_bpermute_b32 v114, v203, v120
	ds_bpermute_b32 v115, v203, v121
	v_pk_fma_f32 v[88:89], v[166:167], v[88:89], v[116:117]
	v_pk_mul_f32 v[116:117], v[172:173], v[86:87]
	v_pk_mul_f32 v[118:119], v[170:171], v[88:89]
	global_store_dwordx4 v[134:135], v[86:89], off nt
	v_cvt_pk_bf16_f32 v116, v116, v117
	v_cvt_pk_bf16_f32 v117, v118, v119
	v_lshlrev_b32_e32 v118, 1, v128
	s_waitcnt lgkmcnt(0)
	v_add_u32_e32 v250, 0xfffff040, v118
	v_cndmask_b32_e64 v250, v118, v250, s[40:41]
	v_cndmask_b32_e64 v248, v126, v114, s[40:41]
	v_cndmask_b32_e64 v249, v127, v115, s[40:41]
	global_store_dwordx2 v250, v[248:249], s[20:21]
	v_cndmask_b32_e64 v246, v114, v126, s[40:41]
	v_cndmask_b32_e64 v247, v115, v127, s[40:41]
	s_waitcnt lgkmcnt(1)
	v_add_u32_e32 v114, 0x1040, v118
	v_cndmask_b32_e64 v114, v118, v114, s[38:39]
	global_store_dwordx2 v114, v[246:247], s[20:21]
	ds_bpermute_b32 v114, v203, v116
	s_waitcnt lgkmcnt(1)
	ds_bpermute_b32 v115, v203, v117
	v_add_u32_e32 v117, 0x14000, v202
	v_lshlrev_b32_e32 v116, 1, v117
	s_waitcnt lgkmcnt(0)
	v_add_u32_e32 v250, 0xfffff040, v116
	v_cndmask_b32_e64 v250, v116, v250, s[40:41]
	v_cndmask_b32_e64 v248, v122, v114, s[40:41]
	v_cndmask_b32_e64 v249, v123, v115, s[40:41]
	global_store_dwordx2 v250, v[248:249], s[20:21]
	v_cndmask_b32_e64 v246, v114, v122, s[40:41]
	v_cndmask_b32_e64 v247, v115, v123, s[40:41]
	v_mul_f32_e32 v83, v83, v83
	v_fmac_f32_e32 v83, v82, v82
	v_mul_f32_e32 v82, v85, v85
	v_mul_f32_e32 v93, v93, v93
	v_fmac_f32_e32 v82, v84, v84
	v_mul_f32_e32 v91, v91, v91
	v_fmac_f32_e32 v93, v92, v92
	v_mul_f32_e32 v92, v95, v95
	v_mul_f32_e32 v95, v97, v97
	v_add_f32_e32 v82, v83, v82
	v_mul_f32_e32 v83, v87, v87
	v_mul_f32_e32 v84, v89, v89
	v_fmac_f32_e32 v95, v96, v96
	v_fmac_f32_e32 v83, v86, v86
	v_fmac_f32_e32 v84, v88, v88
	v_fmac_f32_e32 v91, v90, v90
	v_fmac_f32_e32 v92, v94, v94
	v_add_f32_e32 v83, v83, v84
	v_add_f32_e32 v84, v91, v93
	v_add_f32_e32 v85, v92, v95
	v_add_f32_e32 v82, v84, v82
	v_add_f32_e32 v83, v85, v83
	ds_bpermute_b32 v84, v190, v82
	ds_bpermute_b32 v85, v190, v83
	s_waitcnt lgkmcnt(1)
	v_add_f32_e32 v82, v82, v84
	s_waitcnt lgkmcnt(0)
	v_add_f32_e32 v85, v83, v85
	ds_bpermute_b32 v84, v191, v82
	ds_bpermute_b32 v86, v191, v85
	s_waitcnt lgkmcnt(1)
	v_add_f32_e32 v82, v82, v84
	s_waitcnt lgkmcnt(0)
	v_add_f32_e32 v84, v85, v86
	ds_bpermute_b32 v83, v204, v82
	ds_bpermute_b32 v85, v204, v84
	v_add_u32_e32 v86, 0x1040, v116
	v_cndmask_b32_e64 v86, v116, v86, s[38:39]
	global_store_dwordx2 v86, v[246:247], s[20:21]
	s_and_saveexec_b64 s[16:17], s[42:43]
	s_cbranch_execz .LBB0_1628
	s_waitcnt lgkmcnt(1)
	v_add_f32_e32 v82, v82, v83
	s_waitcnt lgkmcnt(0)
	v_add_f32_e32 v83, v84, v85
	ds_write2_b32 v194, v82, v83 offset0:32 offset1:40
; #define LAS __attribute__((address_space(3)))
; #define ERN_EOFF(q, m) (eb + (unsigned)((((q) & 1) * HALF + (m) * 16) * DM + ERN_COL((q) >> 1)))
;     __device__ __forceinline__ void operator()(const f32x4 (&acc)[2][2][4][2], const Unit& u, int wr, int wc, int fr, int fq) const {
;     ...
;         for (int g = 0; g < 8; ++g) { const int ai = g >> 2, m = g & 3;
;             if (g + 1 < 8) ERN_LOADX(g + 1);
;             float sq0 = 0.f, sq1 = 0.f; u32x2 hw[2][2];
; #pragma unroll
;             for (int bj = 0; bj < 2; ++bj) {
;                 *(LAS f32x4*)(st + wr_off) = acc[ai][bj][m][0]; *(LAS f32x4*)(st + wr_off + 64) = acc[ai][bj][m][1];
;                 const f32x4 a0 = *(const LAS f32x4*)(st + rd_off), a1 = *(const LAS f32x4*)(st + rd_off + 8 * 144);
;                 { const f32x4 xv = xb[g & 1][bj][0] + gv[bj] * a0; __builtin_nontemporal_store(xv, (f32x4*)((char*)xo + 4u * ERN_EOFF(g, bj, 0)));
;                   sq0 += (xv.x * xv.x + xv.y * xv.y) + (xv.z * xv.z + xv.w * xv.w);
;                   const f32x4 hv = xv * gsn[bj]; hw[bj][0].x = cvt_pk_bf16(hv.x, hv.y); hw[bj][0].y = cvt_pk_bf16(hv.z, hv.w); }
;                 { const f32x4 xv = xb[g & 1][bj][1] + gv[bj] * a1; __builtin_nontemporal_store(xv, (f32x4*)((char*)xo + 4u * ERN_EOFF(g, bj, 1)));
;                   sq1 += (xv.x * xv.x + xv.y * xv.y) + (xv.z * xv.z + xv.w * xv.w);
;                   const f32x4 hv = xv * gsn[bj]; hw[bj][1].x = cvt_pk_bf16(hv.x, hv.y); hw[bj][1].y = cvt_pk_bf16(hv.z, hv.w); }
;             }
;             if (!NOH && !PLAIN) {
; #pragma unroll
;                 for (int rh = 0; rh < 2; ++rh) { u32x2 rv; rv.x = __shfl_xor(hw[1][rh].x, 8); rv.y = __shfl_xor(hw[1][rh].y, 8);
;                     const unsigned e0 = ERN_EOFF(g, 0, rh);
;                     const unsigned ee = odd ? (e0 - DM + 32) : e0, eo2 = odd ? e0 : (e0 + DM + 32);
;                     *(u32x2*)((char*)ho + 2u * ee) = odd ? rv : hw[0][rh];
;                     *(u32x2*)((char*)ho + 2u * eo2) = odd ? hw[0][rh] : rv; }
;             }
;             if (!PLAIN) { sq0 += __shfl_xor(sq0, 1); sq0 += __shfl_xor(sq0, 2); sq0 += __shfl_xor(sq0, 4);
;             sq1 += __shfl_xor(sq1, 1); sq1 += __shfl_xor(sq1, 2); sq1 += __shfl_xor(sq1, 4); }
;             if (!PLAIN && pc == 0) { sst[g * 16 + rr] = sq0; sst[g * 16 + 8 + rr] = sq1; }
.LBB0_1628:
	s_or_b64 exec, exec, s[16:17]
	v_lshl_add_u64 v[116:117], s[22:23], 0, v[154:155]
	v_add_u32_e32 v82, 0x100000, v205
	s_waitcnt lgkmcnt(1)
	v_add_u32_e32 v83, 0x110000, v205
	v_add_u32_e32 v154, 0x100080, v205
	global_load_dwordx4 v[94:97], v82, s[22:23]
	global_load_dwordx4 v[90:93], v83, s[22:23]
	v_add_u32_e32 v114, 0x110080, v205
	global_load_dwordx4 v[86:89], v154, s[22:23]
	s_waitcnt lgkmcnt(0)
	global_load_dwordx4 v[82:85], v114, s[22:23]
	ds_write_b128 v200, v[78:81]
	ds_write_b128 v200, v[74:77] offset:64
	ds_read_b128 v[74:77], v201
	ds_read_b128 v[78:81], v201 offset:1152
	v_mov_b32_e32 v131, v155
	v_mov_b32_e32 v133, v155
	s_waitcnt vmcnt(12) lgkmcnt(1)
	v_pk_fma_f32 v[76:77], v[176:177], v[76:77], v[112:113]
	v_add_u32_e32 v112, 0x18000, v202
	v_pk_fma_f32 v[74:75], v[180:181], v[74:75], v[110:111]
	v_lshlrev_b32_e32 v110, 2, v112
	s_waitcnt lgkmcnt(0)
	v_pk_fma_f32 v[78:79], v[180:181], v[78:79], v[106:107]
	global_store_dwordx4 v110, v[74:77], s[22:23] nt
	v_pk_mul_f32 v[110:111], v[178:179], v[74:75]
	v_pk_fma_f32 v[80:81], v[176:177], v[80:81], v[108:109]
	v_pk_mul_f32 v[106:107], v[178:179], v[78:79]
	v_pk_mul_f32 v[118:119], v[174:175], v[76:77]
	v_cvt_pk_bf16_f32 v110, v110, v111
	v_pk_mul_f32 v[108:109], v[174:175], v[80:81]
	v_cvt_pk_bf16_f32 v111, v118, v119
	global_store_dwordx4 v[116:117], v[78:81], off nt
	v_cvt_pk_bf16_f32 v106, v106, v107
	v_cvt_pk_bf16_f32 v107, v108, v109
	ds_write_b128 v200, v[70:73]
	ds_write_b128 v200, v[66:69] offset:64
	ds_read_b128 v[66:69], v201
	ds_read_b128 v[70:73], v201 offset:1152
	v_lshl_add_u64 v[108:109], s[22:23], 0, v[130:131]
	v_lshl_add_u64 v[116:117], s[22:23], 0, v[132:133]
	s_waitcnt lgkmcnt(1)
	v_pk_fma_f32 v[66:67], v[168:169], v[66:67], v[102:103]
	v_pk_fma_f32 v[68:69], v[166:167], v[68:69], v[104:105]
	v_pk_mul_f32 v[104:105], v[172:173], v[66:67]
	global_store_dwordx4 v[108:109], v[66:69], off nt
	v_pk_mul_f32 v[102:103], v[170:171], v[68:69]
	v_cvt_pk_bf16_f32 v104, v104, v105
	s_waitcnt vmcnt(14) lgkmcnt(0)
	v_pk_fma_f32 v[70:71], v[168:169], v[70:71], v[98:99]
	v_cvt_pk_bf16_f32 v105, v102, v103
	ds_bpermute_b32 v98, v203, v104
	ds_bpermute_b32 v99, v203, v105
	v_pk_fma_f32 v[72:73], v[166:167], v[72:73], v[100:101]
	v_pk_mul_f32 v[100:101], v[172:173], v[70:71]
	v_pk_mul_f32 v[102:103], v[170:171], v[72:73]
	global_store_dwordx4 v[116:117], v[70:73], off nt
	v_cvt_pk_bf16_f32 v100, v100, v101
	v_cvt_pk_bf16_f32 v101, v102, v103
	v_lshlrev_b32_e32 v102, 1, v112
	s_waitcnt lgkmcnt(0)
	v_add_u32_e32 v250, 0xfffff040, v102
	v_cndmask_b32_e64 v250, v102, v250, s[40:41]
	v_cndmask_b32_e64 v248, v110, v98, s[40:41]
	v_cndmask_b32_e64 v249, v111, v99, s[40:41]
	global_store_dwordx2 v250, v[248:249], s[20:21]
	v_cndmask_b32_e64 v246, v98, v110, s[40:41]
	v_cndmask_b32_e64 v247, v99, v111, s[40:41]
	s_waitcnt lgkmcnt(1)
	v_add_u32_e32 v98, 0x1040, v102
	v_cndmask_b32_e64 v98, v102, v98, s[38:39]
	global_store_dwordx2 v98, v[246:247], s[20:21]
	ds_bpermute_b32 v98, v203, v100
	s_waitcnt lgkmcnt(1)
	ds_bpermute_b32 v99, v203, v101
	v_add_u32_e32 v101, 0x1c000, v202
	v_lshlrev_b32_e32 v100, 1, v101
	s_waitcnt lgkmcnt(0)
	v_add_u32_e32 v250, 0xfffff040, v100
	v_cndmask_b32_e64 v250, v100, v250, s[40:41]
	v_cndmask_b32_e64 v248, v106, v98, s[40:41]
	v_cndmask_b32_e64 v249, v107, v99, s[40:41]
	global_store_dwordx2 v250, v[248:249], s[20:21]
	v_cndmask_b32_e64 v246, v98, v106, s[40:41]
	v_cndmask_b32_e64 v247, v99, v107, s[40:41]
	v_mul_f32_e32 v67, v67, v67
	v_fmac_f32_e32 v67, v66, v66
	v_mul_f32_e32 v66, v69, v69
	v_mul_f32_e32 v77, v77, v77
	v_fmac_f32_e32 v66, v68, v68
	v_mul_f32_e32 v75, v75, v75
	v_fmac_f32_e32 v77, v76, v76
	v_mul_f32_e32 v76, v79, v79
	v_mul_f32_e32 v79, v81, v81
	v_add_f32_e32 v66, v67, v66
	v_mul_f32_e32 v67, v71, v71
	v_mul_f32_e32 v68, v73, v73
	v_fmac_f32_e32 v79, v80, v80
	v_fmac_f32_e32 v67, v70, v70
	v_fmac_f32_e32 v68, v72, v72
	v_fmac_f32_e32 v75, v74, v74
	v_fmac_f32_e32 v76, v78, v78
	v_add_f32_e32 v67, v67, v68
	v_add_f32_e32 v68, v75, v77
	v_add_f32_e32 v69, v76, v79
	v_add_f32_e32 v66, v68, v66
	v_add_f32_e32 v67, v69, v67
	ds_bpermute_b32 v68, v190, v66
	ds_bpermute_b32 v69, v190, v67
	s_waitcnt lgkmcnt(1)
	v_add_f32_e32 v66, v66, v68
	s_waitcnt lgkmcnt(0)
	v_add_f32_e32 v69, v67, v69
	ds_bpermute_b32 v68, v191, v66
	ds_bpermute_b32 v70, v191, v69
	s_waitcnt lgkmcnt(1)
	v_add_f32_e32 v66, v66, v68
	s_waitcnt lgkmcnt(0)
	v_add_f32_e32 v68, v69, v70
	ds_bpermute_b32 v67, v204, v66
	ds_bpermute_b32 v69, v204, v68
	v_add_u32_e32 v70, 0x1040, v100
	v_cndmask_b32_e64 v70, v100, v70, s[38:39]
	global_store_dwordx2 v70, v[246:247], s[20:21]
	s_and_saveexec_b64 s[16:17], s[42:43]
	s_cbranch_execz .LBB0_1638
	s_waitcnt lgkmcnt(1)
	v_add_f32_e32 v66, v66, v67
	s_waitcnt lgkmcnt(0)
	v_add_f32_e32 v67, v68, v69
	ds_write2_b32 v194, v66, v67 offset0:48 offset1:56
; #define LAS __attribute__((address_space(3)))
; #define ERN_EOFF(q, m) (eb + (unsigned)((((q) & 1) * HALF + (m) * 16) * DM + ERN_COL((q) >> 1)))
;     __device__ __forceinline__ void operator()(const f32x4 (&acc)[2][2][4][2], const Unit& u, int wr, int wc, int fr, int fq) const {
;     ...
;         ERN_LOADX(0);
; #pragma unroll
;         for (int g = 0; g < 8; ++g) { const int ai = g >> 2, m = g & 3;
;             if (g + 1 < 8) ERN_LOADX(g + 1);
;             float sq0 = 0.f, sq1 = 0.f; u32x2 hw[2][2];
; #pragma unroll
;             for (int bj = 0; bj < 2; ++bj) {
;                 *(LAS f32x4*)(st + wr_off) = acc[ai][bj][m][0]; *(LAS f32x4*)(st + wr_off + 64) = acc[ai][bj][m][1];
;                 const f32x4 a0 = *(const LAS f32x4*)(st + rd_off), a1 = *(const LAS f32x4*)(st + rd_off + 8 * 144);
;                 { const f32x4 xv = xb[g & 1][bj][0] + gv[bj] * a0; __builtin_nontemporal_store(xv, (f32x4*)((char*)xo + 4u * ERN_EOFF(g, bj, 0)));
;                   sq0 += (xv.x * xv.x + xv.y * xv.y) + (xv.z * xv.z + xv.w * xv.w);
;                   const f32x4 hv = xv * gsn[bj]; hw[bj][0].x = cvt_pk_bf16(hv.x, hv.y); hw[bj][0].y = cvt_pk_bf16(hv.z, hv.w); }
;                 { const f32x4 xv = xb[g & 1][bj][1] + gv[bj] * a1; __builtin_nontemporal_store(xv, (f32x4*)((char*)xo + 4u * ERN_EOFF(g, bj, 1)));
;                   sq1 += (xv.x * xv.x + xv.y * xv.y) + (xv.z * xv.z + xv.w * xv.w);
;                   const f32x4 hv = xv * gsn[bj]; hw[bj][1].x = cvt_pk_bf16(hv.x, hv.y); hw[bj][1].y = cvt_pk_bf16(hv.z, hv.w); }
;             }
;             if (!NOH && !PLAIN) {
; #pragma unroll
;                 for (int rh = 0; rh < 2; ++rh) { u32x2 rv; rv.x = __shfl_xor(hw[1][rh].x, 8); rv.y = __shfl_xor(hw[1][rh].y, 8);
;                     const unsigned e0 = ERN_EOFF(g, 0, rh);
;                     const unsigned ee = odd ? (e0 - DM + 32) : e0, eo2 = odd ? e0 : (e0 + DM + 32);
;                     *(u32x2*)((char*)ho + 2u * ee) = odd ? rv : hw[0][rh];
;                     *(u32x2*)((char*)ho + 2u * eo2) = odd ? hw[0][rh] : rv; }
;             }
;             if (!PLAIN) { sq0 += __shfl_xor(sq0, 1); sq0 += __shfl_xor(sq0, 2); sq0 += __shfl_xor(sq0, 4);
;             sq1 += __shfl_xor(sq1, 1); sq1 += __shfl_xor(sq1, 2); sq1 += __shfl_xor(sq1, 4); }
;             if (!PLAIN && pc == 0) { sst[g * 16 + rr] = sq0; sst[g * 16 + 8 + rr] = sq1; }
.LBB0_1638:
	s_or_b64 exec, exec, s[16:17]
	v_lshl_add_u64 v[104:105], s[22:23], 0, v[154:155]
	v_add_u32_e32 v154, 0x120000, v205
	v_add_u32_e32 v100, 0x120080, v205
	v_add_u32_e32 v102, 0x130000, v205
	global_load_dwordx4 v[78:81], v154, s[22:23]
	global_load_dwordx4 v[74:77], v102, s[22:23]
	v_add_u32_e32 v98, 0x130080, v205
	global_load_dwordx4 v[70:73], v100, s[22:23]
	s_waitcnt lgkmcnt(0)
	global_load_dwordx4 v[66:69], v98, s[22:23]
	ds_write_b128 v200, v[62:65]
	ds_write_b128 v200, v[58:61] offset:64
	ds_read_b128 v[58:61], v201
	ds_read_b128 v[62:65], v201 offset:1152
	v_mov_b32_e32 v115, v155
	s_waitcnt vmcnt(14) lgkmcnt(1)
	v_pk_fma_f32 v[60:61], v[176:177], v[60:61], v[96:97]
	v_add_u32_e32 v96, 0x40000, v202
	v_pk_fma_f32 v[58:59], v[180:181], v[58:59], v[94:95]
	v_lshlrev_b32_e32 v94, 2, v96
	s_waitcnt vmcnt(13) lgkmcnt(0)
	v_pk_fma_f32 v[64:65], v[176:177], v[64:65], v[92:93]
	v_add_u32_e32 v92, 0x44000, v202
	global_store_dwordx4 v94, v[58:61], s[22:23] nt
	v_pk_mul_f32 v[94:95], v[178:179], v[58:59]
	v_pk_fma_f32 v[62:63], v[180:181], v[62:63], v[90:91]
	v_lshlrev_b32_e32 v90, 2, v92
	v_pk_mul_f32 v[106:107], v[174:175], v[60:61]
	v_cvt_pk_bf16_f32 v94, v94, v95
	s_nop 0
	v_cvt_pk_bf16_f32 v95, v106, v107
	global_store_dwordx4 v90, v[62:65], s[22:23] nt
	v_pk_mul_f32 v[90:91], v[178:179], v[62:63]
	v_pk_mul_f32 v[106:107], v[174:175], v[64:65]
	v_cvt_pk_bf16_f32 v90, v90, v91
	s_nop 0
	v_cvt_pk_bf16_f32 v91, v106, v107
	ds_write_b128 v200, v[54:57]
	ds_write_b128 v200, v[50:53] offset:64
	ds_read_b128 v[50:53], v201
	ds_read_b128 v[54:57], v201 offset:1152
	v_lshl_add_u64 v[106:107], s[22:23], 0, v[114:115]
	s_waitcnt vmcnt(14) lgkmcnt(1)
	v_pk_fma_f32 v[50:51], v[168:169], v[50:51], v[86:87]
	v_pk_fma_f32 v[52:53], v[166:167], v[52:53], v[88:89]
	v_pk_mul_f32 v[88:89], v[172:173], v[50:51]
	global_store_dwordx4 v[104:105], v[50:53], off nt
	v_pk_mul_f32 v[86:87], v[170:171], v[52:53]
	v_cvt_pk_bf16_f32 v88, v88, v89
	s_waitcnt vmcnt(14) lgkmcnt(0)
	v_pk_fma_f32 v[54:55], v[168:169], v[54:55], v[82:83]
	v_cvt_pk_bf16_f32 v89, v86, v87
	ds_bpermute_b32 v82, v203, v88
	ds_bpermute_b32 v83, v203, v89
	v_pk_fma_f32 v[56:57], v[166:167], v[56:57], v[84:85]
	v_pk_mul_f32 v[84:85], v[172:173], v[54:55]
	v_pk_mul_f32 v[86:87], v[170:171], v[56:57]
	global_store_dwordx4 v[106:107], v[54:57], off nt
	v_cvt_pk_bf16_f32 v84, v84, v85
	v_cvt_pk_bf16_f32 v85, v86, v87
	v_lshlrev_b32_e32 v86, 1, v96
	s_waitcnt lgkmcnt(0)
	v_add_u32_e32 v250, 0xfffff040, v86
	v_cndmask_b32_e64 v250, v86, v250, s[40:41]
	v_cndmask_b32_e64 v248, v94, v82, s[40:41]
	v_cndmask_b32_e64 v249, v95, v83, s[40:41]
	global_store_dwordx2 v250, v[248:249], s[20:21]
	v_cndmask_b32_e64 v246, v82, v94, s[40:41]
	v_cndmask_b32_e64 v247, v83, v95, s[40:41]
	s_waitcnt lgkmcnt(1)
	v_add_u32_e32 v82, 0x1040, v86
	v_cndmask_b32_e64 v82, v86, v82, s[38:39]
	global_store_dwordx2 v82, v[246:247], s[20:21]
	ds_bpermute_b32 v82, v203, v84
	s_waitcnt lgkmcnt(1)
	ds_bpermute_b32 v83, v203, v85
	v_lshlrev_b32_e32 v84, 1, v92
	s_waitcnt lgkmcnt(0)
	v_add_u32_e32 v250, 0xfffff040, v84
	v_cndmask_b32_e64 v250, v84, v250, s[40:41]
	v_cndmask_b32_e64 v248, v90, v82, s[40:41]
	v_cndmask_b32_e64 v249, v91, v83, s[40:41]
	global_store_dwordx2 v250, v[248:249], s[20:21]
	v_cndmask_b32_e64 v246, v82, v90, s[40:41]
	v_cndmask_b32_e64 v247, v83, v91, s[40:41]
	v_mul_f32_e32 v51, v51, v51
	v_fmac_f32_e32 v51, v50, v50
	v_mul_f32_e32 v50, v53, v53
	v_mul_f32_e32 v61, v61, v61
	v_fmac_f32_e32 v50, v52, v52
	v_mul_f32_e32 v59, v59, v59
	v_fmac_f32_e32 v61, v60, v60
	v_mul_f32_e32 v60, v63, v63
	v_mul_f32_e32 v63, v65, v65
	v_add_f32_e32 v50, v51, v50
	v_mul_f32_e32 v51, v55, v55
	v_mul_f32_e32 v52, v57, v57
	v_fmac_f32_e32 v63, v64, v64
	v_fmac_f32_e32 v51, v54, v54
	v_fmac_f32_e32 v52, v56, v56
	v_fmac_f32_e32 v59, v58, v58
	v_fmac_f32_e32 v60, v62, v62
	v_add_f32_e32 v51, v51, v52
	v_add_f32_e32 v52, v59, v61
	v_add_f32_e32 v53, v60, v63
	v_add_f32_e32 v50, v52, v50
	v_add_f32_e32 v51, v53, v51
	ds_bpermute_b32 v52, v190, v50
	ds_bpermute_b32 v53, v190, v51
	s_waitcnt lgkmcnt(1)
	v_add_f32_e32 v50, v50, v52
	s_waitcnt lgkmcnt(0)
	v_add_f32_e32 v53, v51, v53
	ds_bpermute_b32 v52, v191, v50
	ds_bpermute_b32 v54, v191, v53
	s_waitcnt lgkmcnt(1)
	v_add_f32_e32 v50, v50, v52
	s_waitcnt lgkmcnt(0)
	v_add_f32_e32 v52, v53, v54
	ds_bpermute_b32 v51, v204, v50
	ds_bpermute_b32 v53, v204, v52
	v_add_u32_e32 v54, 0x1040, v84
	v_cndmask_b32_e64 v54, v84, v54, s[38:39]
	global_store_dwordx2 v54, v[246:247], s[20:21]
	s_and_saveexec_b64 s[16:17], s[42:43]
	s_cbranch_execz .LBB0_1648
	s_waitcnt lgkmcnt(1)
	v_add_f32_e32 v50, v50, v51
	s_waitcnt lgkmcnt(0)
	v_add_f32_e32 v51, v52, v53
	ds_write2_b32 v194, v50, v51 offset0:64 offset1:72
; #define LAS __attribute__((address_space(3)))
; #define ERN_EOFF(q, m) (eb + (unsigned)((((q) & 1) * HALF + (m) * 16) * DM + ERN_COL((q) >> 1)))
;     __device__ __forceinline__ void operator()(const f32x4 (&acc)[2][2][4][2], const Unit& u, int wr, int wc, int fr, int fq) const {
;     ...
;         ERN_LOADX(0);
; #pragma unroll
;         for (int g = 0; g < 8; ++g) { const int ai = g >> 2, m = g & 3;
;             if (g + 1 < 8) ERN_LOADX(g + 1);
;             float sq0 = 0.f, sq1 = 0.f; u32x2 hw[2][2];
; #pragma unroll
;             for (int bj = 0; bj < 2; ++bj) {
;                 *(LAS f32x4*)(st + wr_off) = acc[ai][bj][m][0]; *(LAS f32x4*)(st + wr_off + 64) = acc[ai][bj][m][1];
;                 const f32x4 a0 = *(const LAS f32x4*)(st + rd_off), a1 = *(const LAS f32x4*)(st + rd_off + 8 * 144);
;                 { const f32x4 xv = xb[g & 1][bj][0] + gv[bj] * a0; __builtin_nontemporal_store(xv, (f32x4*)((char*)xo + 4u * ERN_EOFF(g, bj, 0)));
;                   sq0 += (xv.x * xv.x + xv.y * xv.y) + (xv.z * xv.z + xv.w * xv.w);
;                   const f32x4 hv = xv * gsn[bj]; hw[bj][0].x = cvt_pk_bf16(hv.x, hv.y); hw[bj][0].y = cvt_pk_bf16(hv.z, hv.w); }
;                 { const f32x4 xv = xb[g & 1][bj][1] + gv[bj] * a1; __builtin_nontemporal_store(xv, (f32x4*)((char*)xo + 4u * ERN_EOFF(g, bj, 1)));
;                   sq1 += (xv.x * xv.x + xv.y * xv.y) + (xv.z * xv.z + xv.w * xv.w);
;                   const f32x4 hv = xv * gsn[bj]; hw[bj][1].x = cvt_pk_bf16(hv.x, hv.y); hw[bj][1].y = cvt_pk_bf16(hv.z, hv.w); }
;             }
;             if (!NOH && !PLAIN) {
; #pragma unroll
;                 for (int rh = 0; rh < 2; ++rh) { u32x2 rv; rv.x = __shfl_xor(hw[1][rh].x, 8); rv.y = __shfl_xor(hw[1][rh].y, 8);
;                     const unsigned e0 = ERN_EOFF(g, 0, rh);
;                     const unsigned ee = odd ? (e0 - DM + 32) : e0, eo2 = odd ? e0 : (e0 + DM + 32);
;                     *(u32x2*)((char*)ho + 2u * ee) = odd ? rv : hw[0][rh];
;                     *(u32x2*)((char*)ho + 2u * eo2) = odd ? hw[0][rh] : rv; }
;             }
;             if (!PLAIN) { sq0 += __shfl_xor(sq0, 1); sq0 += __shfl_xor(sq0, 2); sq0 += __shfl_xor(sq0, 4);
;             sq1 += __shfl_xor(sq1, 1); sq1 += __shfl_xor(sq1, 2); sq1 += __shfl_xor(sq1, 4); }
;             if (!PLAIN && pc == 0) { sst[g * 16 + rr] = sq0; sst[g * 16 + 8 + rr] = sq1; }
.LBB0_1648:
	s_or_b64 exec, exec, s[16:17]
	v_lshl_add_u64 v[88:89], s[22:23], 0, v[154:155]
	v_add_u32_e32 v154, 0x140000, v205
	v_add_u32_e32 v84, 0x140080, v205
	v_add_u32_e32 v86, 0x150000, v205
	global_load_dwordx4 v[62:65], v154, s[22:23]
	global_load_dwordx4 v[58:61], v86, s[22:23]
	v_add_u32_e32 v82, 0x150080, v205
	global_load_dwordx4 v[54:57], v84, s[22:23]
	s_waitcnt lgkmcnt(0)
	global_load_dwordx4 v[50:53], v82, s[22:23]
	ds_write_b128 v200, v[46:49]
	ds_write_b128 v200, v[42:45] offset:64
	ds_read_b128 v[42:45], v201
	ds_read_b128 v[46:49], v201 offset:1152
	v_mov_b32_e32 v103, v155
	v_lshl_add_u64 v[90:91], s[22:23], 0, v[102:103]
	v_mov_b32_e32 v101, v155
	s_waitcnt vmcnt(14) lgkmcnt(1)
	v_pk_fma_f32 v[42:43], v[180:181], v[42:43], v[78:79]
	s_waitcnt vmcnt(13) lgkmcnt(0)
	v_pk_fma_f32 v[46:47], v[180:181], v[46:47], v[74:75]
	v_pk_fma_f32 v[44:45], v[176:177], v[44:45], v[80:81]
	v_pk_mul_f32 v[78:79], v[178:179], v[42:43]
	v_pk_fma_f32 v[48:49], v[176:177], v[48:49], v[76:77]
	v_pk_mul_f32 v[74:75], v[178:179], v[46:47]
	global_store_dwordx4 v[88:89], v[42:45], off nt
	v_pk_mul_f32 v[80:81], v[174:175], v[44:45]
	v_cvt_pk_bf16_f32 v78, v78, v79
	v_pk_mul_f32 v[76:77], v[174:175], v[48:49]
	v_cvt_pk_bf16_f32 v79, v80, v81
	global_store_dwordx4 v[90:91], v[46:49], off nt
	v_cvt_pk_bf16_f32 v74, v74, v75
	v_cvt_pk_bf16_f32 v75, v76, v77
	ds_write_b128 v200, v[38:41]
	ds_write_b128 v200, v[34:37] offset:64
	ds_read_b128 v[34:37], v201
	ds_read_b128 v[38:41], v201 offset:1152
	v_lshl_add_u64 v[76:77], s[22:23], 0, v[100:101]
	v_mov_b32_e32 v99, v155
	v_lshl_add_u64 v[80:81], s[22:23], 0, v[98:99]
	s_waitcnt vmcnt(14) lgkmcnt(1)
	v_pk_fma_f32 v[34:35], v[168:169], v[34:35], v[70:71]
	v_pk_fma_f32 v[36:37], v[166:167], v[36:37], v[72:73]
	v_pk_mul_f32 v[72:73], v[172:173], v[34:35]
	global_store_dwordx4 v[76:77], v[34:37], off nt
	v_pk_mul_f32 v[70:71], v[170:171], v[36:37]
	v_cvt_pk_bf16_f32 v72, v72, v73
	s_waitcnt vmcnt(14) lgkmcnt(0)
	v_pk_fma_f32 v[38:39], v[168:169], v[38:39], v[66:67]
	v_cvt_pk_bf16_f32 v73, v70, v71
	ds_bpermute_b32 v66, v203, v72
	ds_bpermute_b32 v67, v203, v73
	v_pk_fma_f32 v[40:41], v[166:167], v[40:41], v[68:69]
	v_pk_mul_f32 v[68:69], v[172:173], v[38:39]
	v_pk_mul_f32 v[70:71], v[170:171], v[40:41]
	global_store_dwordx4 v[80:81], v[38:41], off nt
	v_cvt_pk_bf16_f32 v68, v68, v69
	v_cvt_pk_bf16_f32 v69, v70, v71
	v_add_u32_e32 v71, 0x48000, v202
	v_lshlrev_b32_e32 v70, 1, v71
	s_waitcnt lgkmcnt(0)
	v_add_u32_e32 v250, 0xfffff040, v70
	v_cndmask_b32_e64 v250, v70, v250, s[40:41]
	v_cndmask_b32_e64 v248, v78, v66, s[40:41]
	v_cndmask_b32_e64 v249, v79, v67, s[40:41]
	global_store_dwordx2 v250, v[248:249], s[20:21]
	v_cndmask_b32_e64 v246, v66, v78, s[40:41]
	v_cndmask_b32_e64 v247, v67, v79, s[40:41]
	s_waitcnt lgkmcnt(1)
	v_add_u32_e32 v66, 0x1040, v70
	v_cndmask_b32_e64 v66, v70, v66, s[38:39]
	global_store_dwordx2 v66, v[246:247], s[20:21]
	ds_bpermute_b32 v66, v203, v68
	s_waitcnt lgkmcnt(1)
	ds_bpermute_b32 v67, v203, v69
	v_add_u32_e32 v69, 0x4c000, v202
	v_lshlrev_b32_e32 v68, 1, v69
	s_waitcnt lgkmcnt(0)
	v_add_u32_e32 v250, 0xfffff040, v68
	v_cndmask_b32_e64 v250, v68, v250, s[40:41]
	v_cndmask_b32_e64 v248, v74, v66, s[40:41]
	v_cndmask_b32_e64 v249, v75, v67, s[40:41]
	global_store_dwordx2 v250, v[248:249], s[20:21]
	v_cndmask_b32_e64 v246, v66, v74, s[40:41]
	v_cndmask_b32_e64 v247, v67, v75, s[40:41]
	v_mul_f32_e32 v35, v35, v35
	v_fmac_f32_e32 v35, v34, v34
	v_mul_f32_e32 v34, v37, v37
	v_mul_f32_e32 v45, v45, v45
	v_fmac_f32_e32 v34, v36, v36
	v_mul_f32_e32 v43, v43, v43
	v_fmac_f32_e32 v45, v44, v44
	v_mul_f32_e32 v44, v47, v47
	v_mul_f32_e32 v47, v49, v49
	v_add_f32_e32 v34, v35, v34
	v_mul_f32_e32 v35, v39, v39
	v_mul_f32_e32 v36, v41, v41
	v_fmac_f32_e32 v47, v48, v48
	v_fmac_f32_e32 v35, v38, v38
	v_fmac_f32_e32 v36, v40, v40
	v_fmac_f32_e32 v43, v42, v42
	v_fmac_f32_e32 v44, v46, v46
	v_add_f32_e32 v35, v35, v36
	v_add_f32_e32 v36, v43, v45
	v_add_f32_e32 v37, v44, v47
	v_add_f32_e32 v34, v36, v34
	v_add_f32_e32 v35, v37, v35
	ds_bpermute_b32 v36, v190, v34
	ds_bpermute_b32 v37, v190, v35
	s_waitcnt lgkmcnt(1)
	v_add_f32_e32 v34, v34, v36
	s_waitcnt lgkmcnt(0)
	v_add_f32_e32 v37, v35, v37
	ds_bpermute_b32 v36, v191, v34
	ds_bpermute_b32 v38, v191, v37
	s_waitcnt lgkmcnt(1)
	v_add_f32_e32 v34, v34, v36
	s_waitcnt lgkmcnt(0)
	v_add_f32_e32 v36, v37, v38
	ds_bpermute_b32 v35, v204, v34
	ds_bpermute_b32 v37, v204, v36
	v_add_u32_e32 v38, 0x1040, v68
	v_cndmask_b32_e64 v38, v68, v38, s[38:39]
	global_store_dwordx2 v38, v[246:247], s[20:21]
	s_and_saveexec_b64 s[16:17], s[42:43]
	s_cbranch_execz .LBB0_1658
	s_waitcnt lgkmcnt(1)
	v_add_f32_e32 v34, v34, v35
	s_waitcnt lgkmcnt(0)
	v_add_f32_e32 v35, v36, v37
	ds_write2_b32 v194, v34, v35 offset0:80 offset1:88
; #define LAS __attribute__((address_space(3)))
; #define ERN_EOFF(q, m) (eb + (unsigned)((((q) & 1) * HALF + (m) * 16) * DM + ERN_COL((q) >> 1)))
;     __device__ __forceinline__ void operator()(const f32x4 (&acc)[2][2][4][2], const Unit& u, int wr, int wc, int fr, int fq) const {
;     ...
;         ERN_LOADX(0);
; #pragma unroll
;         for (int g = 0; g < 8; ++g) { const int ai = g >> 2, m = g & 3;
;             if (g + 1 < 8) ERN_LOADX(g + 1);
;             float sq0 = 0.f, sq1 = 0.f; u32x2 hw[2][2];
; #pragma unroll
;             for (int bj = 0; bj < 2; ++bj) {
;                 *(LAS f32x4*)(st + wr_off) = acc[ai][bj][m][0]; *(LAS f32x4*)(st + wr_off + 64) = acc[ai][bj][m][1];
;                 const f32x4 a0 = *(const LAS f32x4*)(st + rd_off), a1 = *(const LAS f32x4*)(st + rd_off + 8 * 144);
;                 { const f32x4 xv = xb[g & 1][bj][0] + gv[bj] * a0; __builtin_nontemporal_store(xv, (f32x4*)((char*)xo + 4u * ERN_EOFF(g, bj, 0)));
;                   sq0 += (xv.x * xv.x + xv.y * xv.y) + (xv.z * xv.z + xv.w * xv.w);
;                   const f32x4 hv = xv * gsn[bj]; hw[bj][0].x = cvt_pk_bf16(hv.x, hv.y); hw[bj][0].y = cvt_pk_bf16(hv.z, hv.w); }
;                 { const f32x4 xv = xb[g & 1][bj][1] + gv[bj] * a1; __builtin_nontemporal_store(xv, (f32x4*)((char*)xo + 4u * ERN_EOFF(g, bj, 1)));
;                   sq1 += (xv.x * xv.x + xv.y * xv.y) + (xv.z * xv.z + xv.w * xv.w);
;                   const f32x4 hv = xv * gsn[bj]; hw[bj][1].x = cvt_pk_bf16(hv.x, hv.y); hw[bj][1].y = cvt_pk_bf16(hv.z, hv.w); }
;             }
;             if (!NOH && !PLAIN) {
; #pragma unroll
;                 for (int rh = 0; rh < 2; ++rh) { u32x2 rv; rv.x = __shfl_xor(hw[1][rh].x, 8); rv.y = __shfl_xor(hw[1][rh].y, 8);
;                     const unsigned e0 = ERN_EOFF(g, 0, rh);
;                     const unsigned ee = odd ? (e0 - DM + 32) : e0, eo2 = odd ? e0 : (e0 + DM + 32);
;                     *(u32x2*)((char*)ho + 2u * ee) = odd ? rv : hw[0][rh];
;                     *(u32x2*)((char*)ho + 2u * eo2) = odd ? hw[0][rh] : rv; }
;             }
;             if (!PLAIN) { sq0 += __shfl_xor(sq0, 1); sq0 += __shfl_xor(sq0, 2); sq0 += __shfl_xor(sq0, 4);
;             sq1 += __shfl_xor(sq1, 1); sq1 += __shfl_xor(sq1, 2); sq1 += __shfl_xor(sq1, 4); }
;             if (!PLAIN && pc == 0) { sst[g * 16 + rr] = sq0; sst[g * 16 + 8 + rr] = sq1; }
.LBB0_1658:
	s_or_b64 exec, exec, s[16:17]
	v_lshl_add_u64 v[72:73], s[22:23], 0, v[154:155]
	v_add_u32_e32 v154, 0x160000, v205
	v_add_u32_e32 v68, 0x160080, v205
	v_add_u32_e32 v70, 0x170000, v205
	global_load_dwordx4 v[46:49], v154, s[22:23]
	global_load_dwordx4 v[42:45], v70, s[22:23]
	v_add_u32_e32 v66, 0x170080, v205
	global_load_dwordx4 v[38:41], v68, s[22:23]
	s_waitcnt lgkmcnt(0)
	global_load_dwordx4 v[34:37], v66, s[22:23]
	ds_write_b128 v200, v[30:33]
	ds_write_b128 v200, v[26:29] offset:64
	ds_read_b128 v[26:29], v201
	ds_read_b128 v[30:33], v201 offset:1152
	v_mov_b32_e32 v87, v155
	v_lshl_add_u64 v[74:75], s[22:23], 0, v[86:87]
	v_mov_b32_e32 v85, v155
	s_waitcnt vmcnt(14) lgkmcnt(1)
	v_pk_fma_f32 v[26:27], v[180:181], v[26:27], v[62:63]
	s_waitcnt vmcnt(13) lgkmcnt(0)
	v_pk_fma_f32 v[30:31], v[180:181], v[30:31], v[58:59]
	v_pk_fma_f32 v[28:29], v[176:177], v[28:29], v[64:65]
	v_pk_mul_f32 v[62:63], v[178:179], v[26:27]
	v_pk_fma_f32 v[32:33], v[176:177], v[32:33], v[60:61]
	v_pk_mul_f32 v[58:59], v[178:179], v[30:31]
	global_store_dwordx4 v[72:73], v[26:29], off nt
	v_pk_mul_f32 v[64:65], v[174:175], v[28:29]
	v_cvt_pk_bf16_f32 v62, v62, v63
	v_pk_mul_f32 v[60:61], v[174:175], v[32:33]
	v_cvt_pk_bf16_f32 v63, v64, v65
	global_store_dwordx4 v[74:75], v[30:33], off nt
	v_cvt_pk_bf16_f32 v58, v58, v59
	v_cvt_pk_bf16_f32 v59, v60, v61
	ds_write_b128 v200, v[22:25]
	ds_write_b128 v200, v[18:21] offset:64
	ds_read_b128 v[18:21], v201
	ds_read_b128 v[22:25], v201 offset:1152
	v_lshl_add_u64 v[60:61], s[22:23], 0, v[84:85]
	v_mov_b32_e32 v83, v155
	v_lshl_add_u64 v[64:65], s[22:23], 0, v[82:83]
	s_waitcnt vmcnt(14) lgkmcnt(1)
	v_pk_fma_f32 v[18:19], v[168:169], v[18:19], v[54:55]
	v_pk_fma_f32 v[20:21], v[166:167], v[20:21], v[56:57]
	v_pk_mul_f32 v[56:57], v[172:173], v[18:19]
	global_store_dwordx4 v[60:61], v[18:21], off nt
	v_pk_mul_f32 v[54:55], v[170:171], v[20:21]
	v_cvt_pk_bf16_f32 v56, v56, v57
	s_waitcnt vmcnt(14) lgkmcnt(0)
	v_pk_fma_f32 v[22:23], v[168:169], v[22:23], v[50:51]
	v_cvt_pk_bf16_f32 v57, v54, v55
	ds_bpermute_b32 v50, v203, v56
	ds_bpermute_b32 v51, v203, v57
	v_pk_fma_f32 v[24:25], v[166:167], v[24:25], v[52:53]
	v_pk_mul_f32 v[52:53], v[172:173], v[22:23]
	v_pk_mul_f32 v[54:55], v[170:171], v[24:25]
	global_store_dwordx4 v[64:65], v[22:25], off nt
	v_cvt_pk_bf16_f32 v52, v52, v53
	v_cvt_pk_bf16_f32 v53, v54, v55
	v_add_u32_e32 v55, 0x50000, v202
	v_lshlrev_b32_e32 v54, 1, v55
	s_waitcnt lgkmcnt(0)
	v_add_u32_e32 v250, 0xfffff040, v54
	v_cndmask_b32_e64 v250, v54, v250, s[40:41]
	v_cndmask_b32_e64 v248, v62, v50, s[40:41]
	v_cndmask_b32_e64 v249, v63, v51, s[40:41]
	global_store_dwordx2 v250, v[248:249], s[20:21]
	v_cndmask_b32_e64 v246, v50, v62, s[40:41]
	v_cndmask_b32_e64 v247, v51, v63, s[40:41]
	s_waitcnt lgkmcnt(1)
	v_add_u32_e32 v50, 0x1040, v54
	v_cndmask_b32_e64 v50, v54, v50, s[38:39]
	global_store_dwordx2 v50, v[246:247], s[20:21]
	ds_bpermute_b32 v50, v203, v52
	s_waitcnt lgkmcnt(1)
	ds_bpermute_b32 v51, v203, v53
	v_add_u32_e32 v53, 0x54000, v202
	v_lshlrev_b32_e32 v52, 1, v53
	s_waitcnt lgkmcnt(0)
	v_add_u32_e32 v250, 0xfffff040, v52
	v_cndmask_b32_e64 v250, v52, v250, s[40:41]
	v_cndmask_b32_e64 v248, v58, v50, s[40:41]
	v_cndmask_b32_e64 v249, v59, v51, s[40:41]
	global_store_dwordx2 v250, v[248:249], s[20:21]
	v_cndmask_b32_e64 v246, v50, v58, s[40:41]
	v_cndmask_b32_e64 v247, v51, v59, s[40:41]
	v_mul_f32_e32 v19, v19, v19
	v_fmac_f32_e32 v19, v18, v18
	v_mul_f32_e32 v18, v21, v21
	v_mul_f32_e32 v29, v29, v29
	v_fmac_f32_e32 v18, v20, v20
	v_mul_f32_e32 v27, v27, v27
	v_fmac_f32_e32 v29, v28, v28
	v_mul_f32_e32 v28, v31, v31
	v_mul_f32_e32 v31, v33, v33
	v_add_f32_e32 v18, v19, v18
	v_mul_f32_e32 v19, v23, v23
	v_mul_f32_e32 v20, v25, v25
	v_fmac_f32_e32 v31, v32, v32
	v_fmac_f32_e32 v19, v22, v22
	v_fmac_f32_e32 v20, v24, v24
	v_fmac_f32_e32 v27, v26, v26
	v_fmac_f32_e32 v28, v30, v30
	v_add_f32_e32 v19, v19, v20
	v_add_f32_e32 v20, v27, v29
	v_add_f32_e32 v21, v28, v31
	v_add_f32_e32 v18, v20, v18
	v_add_f32_e32 v19, v21, v19
	ds_bpermute_b32 v20, v190, v18
	ds_bpermute_b32 v21, v190, v19
	s_waitcnt lgkmcnt(1)
	v_add_f32_e32 v18, v18, v20
	s_waitcnt lgkmcnt(0)
	v_add_f32_e32 v21, v19, v21
	ds_bpermute_b32 v20, v191, v18
	ds_bpermute_b32 v22, v191, v21
	s_waitcnt lgkmcnt(1)
	v_add_f32_e32 v18, v18, v20
	s_waitcnt lgkmcnt(0)
	v_add_f32_e32 v20, v21, v22
	ds_bpermute_b32 v19, v204, v18
	ds_bpermute_b32 v21, v204, v20
	v_add_u32_e32 v22, 0x1040, v52
	v_cndmask_b32_e64 v22, v52, v22, s[38:39]
	global_store_dwordx2 v22, v[246:247], s[20:21]
	s_and_saveexec_b64 s[16:17], s[42:43]
	s_cbranch_execz .LBB0_1668
	s_waitcnt lgkmcnt(1)
	v_add_f32_e32 v18, v18, v19
	s_waitcnt lgkmcnt(0)
	v_add_f32_e32 v19, v20, v21
	ds_write2_b32 v194, v18, v19 offset0:96 offset1:104
; #define LAS __attribute__((address_space(3)))
; #define ERN_EOFF(q, m) (eb + (unsigned)((((q) & 1) * HALF + (m) * 16) * DM + ERN_COL((q) >> 1)))
;     __device__ __forceinline__ void operator()(const f32x4 (&acc)[2][2][4][2], const Unit& u, int wr, int wc, int fr, int fq) const {
;     ...
;         ERN_LOADX(0);
; #pragma unroll
;         for (int g = 0; g < 8; ++g) { const int ai = g >> 2, m = g & 3;
;             if (g + 1 < 8) ERN_LOADX(g + 1);
;             float sq0 = 0.f, sq1 = 0.f; u32x2 hw[2][2];
; #pragma unroll
;             for (int bj = 0; bj < 2; ++bj) {
;                 *(LAS f32x4*)(st + wr_off) = acc[ai][bj][m][0]; *(LAS f32x4*)(st + wr_off + 64) = acc[ai][bj][m][1];
;                 const f32x4 a0 = *(const LAS f32x4*)(st + rd_off), a1 = *(const LAS f32x4*)(st + rd_off + 8 * 144);
;                 { const f32x4 xv = xb[g & 1][bj][0] + gv[bj] * a0; __builtin_nontemporal_store(xv, (f32x4*)((char*)xo + 4u * ERN_EOFF(g, bj, 0)));
;                   sq0 += (xv.x * xv.x + xv.y * xv.y) + (xv.z * xv.z + xv.w * xv.w);
;                   const f32x4 hv = xv * gsn[bj]; hw[bj][0].x = cvt_pk_bf16(hv.x, hv.y); hw[bj][0].y = cvt_pk_bf16(hv.z, hv.w); }
;                 { const f32x4 xv = xb[g & 1][bj][1] + gv[bj] * a1; __builtin_nontemporal_store(xv, (f32x4*)((char*)xo + 4u * ERN_EOFF(g, bj, 1)));
;                   sq1 += (xv.x * xv.x + xv.y * xv.y) + (xv.z * xv.z + xv.w * xv.w);
;                   const f32x4 hv = xv * gsn[bj]; hw[bj][1].x = cvt_pk_bf16(hv.x, hv.y); hw[bj][1].y = cvt_pk_bf16(hv.z, hv.w); }
;             }
;             if (!NOH && !PLAIN) {
; #pragma unroll
;                 for (int rh = 0; rh < 2; ++rh) { u32x2 rv; rv.x = __shfl_xor(hw[1][rh].x, 8); rv.y = __shfl_xor(hw[1][rh].y, 8);
;                     const unsigned e0 = ERN_EOFF(g, 0, rh);
;                     const unsigned ee = odd ? (e0 - DM + 32) : e0, eo2 = odd ? e0 : (e0 + DM + 32);
;                     *(u32x2*)((char*)ho + 2u * ee) = odd ? rv : hw[0][rh];
;                     *(u32x2*)((char*)ho + 2u * eo2) = odd ? hw[0][rh] : rv; }
;             }
;             if (!PLAIN) { sq0 += __shfl_xor(sq0, 1); sq0 += __shfl_xor(sq0, 2); sq0 += __shfl_xor(sq0, 4);
;             sq1 += __shfl_xor(sq1, 1); sq1 += __shfl_xor(sq1, 2); sq1 += __shfl_xor(sq1, 4); }
;             if (!PLAIN && pc == 0) { sst[g * 16 + rr] = sq0; sst[g * 16 + 8 + rr] = sq1; }
.LBB0_1668:
	s_or_b64 exec, exec, s[16:17]
	ds_write_b128 v200, v[14:17]
	ds_write_b128 v200, v[10:13] offset:64
	ds_read_b128 v[10:13], v201
	ds_read_b128 v[14:17], v201 offset:1152
	s_waitcnt lgkmcnt(5)
	v_lshl_add_u64 v[18:19], s[22:23], 0, v[154:155]
	v_mov_b32_e32 v71, v155
	v_lshl_add_u64 v[22:23], s[22:23], 0, v[70:71]
	s_waitcnt vmcnt(10) lgkmcnt(1)
	v_pk_fma_f32 v[12:13], v[176:177], v[12:13], v[48:49]
	v_pk_fma_f32 v[10:11], v[180:181], v[10:11], v[46:47]
	global_store_dwordx4 v[18:19], v[10:13], off nt
	v_pk_mul_f32 v[18:19], v[174:175], v[12:13]
	v_pk_mul_f32 v[20:21], v[178:179], v[10:11]
	s_waitcnt vmcnt(10) lgkmcnt(0)
	v_pk_fma_f32 v[14:15], v[180:181], v[14:15], v[42:43]
	v_cvt_pk_bf16_f32 v20, v20, v21
	v_cvt_pk_bf16_f32 v21, v18, v19
	v_pk_fma_f32 v[16:17], v[176:177], v[16:17], v[44:45]
	v_pk_mul_f32 v[18:19], v[178:179], v[14:15]
	global_store_dwordx4 v[22:23], v[14:17], off nt
	v_pk_mul_f32 v[22:23], v[174:175], v[16:17]
	v_cvt_pk_bf16_f32 v18, v18, v19
	v_mov_b32_e32 v69, v155
	v_cvt_pk_bf16_f32 v19, v22, v23
	ds_write_b128 v200, v[6:9]
	ds_write_b128 v200, v[2:5] offset:64
	ds_read_b128 v[2:5], v201
	ds_read_b128 v[6:9], v201 offset:1152
	v_lshl_add_u64 v[22:23], s[22:23], 0, v[68:69]
	v_mov_b32_e32 v67, v155
	v_lshl_add_u64 v[24:25], s[22:23], 0, v[66:67]
	s_waitcnt vmcnt(10) lgkmcnt(1)
	v_pk_fma_f32 v[4:5], v[166:167], v[4:5], v[40:41]
	v_pk_fma_f32 v[2:3], v[168:169], v[2:3], v[38:39]
	global_store_dwordx4 v[22:23], v[2:5], off nt
	v_pk_mul_f32 v[22:23], v[170:171], v[4:5]
	v_pk_mul_f32 v[26:27], v[172:173], v[2:3]
	s_waitcnt vmcnt(10) lgkmcnt(0)
	v_pk_fma_f32 v[8:9], v[166:167], v[8:9], v[36:37]
	v_cvt_pk_bf16_f32 v28, v26, v27
	v_cvt_pk_bf16_f32 v23, v22, v23
	ds_bpermute_b32 v22, v203, v28
	ds_bpermute_b32 v23, v203, v23
	v_pk_fma_f32 v[6:7], v[168:169], v[6:7], v[34:35]
	global_store_dwordx4 v[24:25], v[6:9], off nt
	v_pk_mul_f32 v[26:27], v[170:171], v[8:9]
	v_pk_mul_f32 v[24:25], v[172:173], v[6:7]
	s_nop 0
	v_cvt_pk_bf16_f32 v24, v24, v25
	v_cvt_pk_bf16_f32 v25, v26, v27
	v_add_u32_e32 v27, 0x58000, v202
	v_lshlrev_b32_e32 v26, 1, v27
	s_waitcnt lgkmcnt(0)
	v_add_u32_e32 v250, 0xfffff040, v26
	v_cndmask_b32_e64 v250, v26, v250, s[40:41]
	v_cndmask_b32_e64 v248, v20, v22, s[40:41]
	v_cndmask_b32_e64 v249, v21, v23, s[40:41]
	global_store_dwordx2 v250, v[248:249], s[20:21]
	v_cndmask_b32_e64 v246, v22, v20, s[40:41]
	v_cndmask_b32_e64 v247, v23, v21, s[40:41]
	s_waitcnt lgkmcnt(1)
	v_add_u32_e32 v22, 0x1040, v26
	v_cndmask_b32_e64 v22, v26, v22, s[38:39]
	global_store_dwordx2 v22, v[246:247], s[20:21]
	ds_bpermute_b32 v20, v203, v24
	ds_bpermute_b32 v21, v203, v25
	s_waitcnt lgkmcnt(2)
	v_add_u32_e32 v23, 0x5c000, v202
	v_lshlrev_b32_e32 v22, 1, v23
	s_waitcnt lgkmcnt(0)
	v_add_u32_e32 v250, 0xfffff040, v22
	v_cndmask_b32_e64 v250, v22, v250, s[40:41]
	v_cndmask_b32_e64 v248, v18, v20, s[40:41]
	v_cndmask_b32_e64 v249, v19, v21, s[40:41]
	global_store_dwordx2 v250, v[248:249], s[20:21]
	v_cndmask_b32_e64 v246, v20, v18, s[40:41]
	v_cndmask_b32_e64 v247, v21, v19, s[40:41]
	v_mul_f32_e32 v3, v3, v3
	v_fmac_f32_e32 v3, v2, v2
	v_mul_f32_e32 v2, v5, v5
	v_mul_f32_e32 v13, v13, v13
	v_fmac_f32_e32 v2, v4, v4
	v_mul_f32_e32 v11, v11, v11
	v_fmac_f32_e32 v13, v12, v12
	v_mul_f32_e32 v12, v15, v15
	v_mul_f32_e32 v15, v17, v17
	v_add_f32_e32 v2, v3, v2
	v_mul_f32_e32 v3, v7, v7
	v_mul_f32_e32 v4, v9, v9
	v_fmac_f32_e32 v15, v16, v16
	v_fmac_f32_e32 v3, v6, v6
	v_fmac_f32_e32 v4, v8, v8
	v_fmac_f32_e32 v11, v10, v10
	v_fmac_f32_e32 v12, v14, v14
	v_add_f32_e32 v3, v3, v4
	v_add_f32_e32 v4, v11, v13
	v_add_f32_e32 v5, v12, v15
	v_add_f32_e32 v2, v4, v2
	v_add_f32_e32 v3, v5, v3
	ds_bpermute_b32 v4, v190, v2
	ds_bpermute_b32 v5, v190, v3
	s_waitcnt lgkmcnt(1)
	v_add_f32_e32 v2, v2, v4
	s_waitcnt lgkmcnt(0)
	v_add_f32_e32 v5, v3, v5
	ds_bpermute_b32 v4, v191, v2
	ds_bpermute_b32 v6, v191, v5
	s_waitcnt lgkmcnt(1)
	v_add_f32_e32 v2, v2, v4
	s_waitcnt lgkmcnt(0)
	v_add_f32_e32 v4, v5, v6
	ds_bpermute_b32 v3, v204, v2
	ds_bpermute_b32 v5, v204, v4
	v_add_u32_e32 v6, 0x1040, v22
	v_cndmask_b32_e64 v6, v22, v6, s[38:39]
	global_store_dwordx2 v6, v[246:247], s[20:21]
	s_and_saveexec_b64 s[16:17], s[42:43]
	s_cbranch_execz .LBB0_1678
	s_waitcnt lgkmcnt(1)
	v_add_f32_e32 v2, v2, v3
	s_waitcnt lgkmcnt(0)
	v_add_f32_e32 v3, v4, v5
	ds_write2_b32 v194, v2, v3 offset0:112 offset1:120

; #define LAS __attribute__((address_space(3)))
; #define ERN_EOFF(q, m) (eb + (unsigned)((((q) & 1) * HALF + (m) * 16) * DM + ERN_COL((q) >> 1)))
;     __device__ __forceinline__ void operator()(const f32x4 (&acc)[2][2][4][2], const Unit& u, int wr, int wc, int fr, int fq) const {
;     ...
;         ERN_LOADX(0);
; #pragma unroll
;         for (int g = 0; g < 8; ++g) { const int ai = g >> 2, m = g & 3;
;             if (g + 1 < 8) ERN_LOADX(g + 1);
;             float sq0 = 0.f, sq1 = 0.f; u32x2 hw[2][2];
; #pragma unroll
;             for (int bj = 0; bj < 2; ++bj) {
;                 *(LAS f32x4*)(st + wr_off) = acc[ai][bj][m][0]; *(LAS f32x4*)(st + wr_off + 64) = acc[ai][bj][m][1];
;                 const f32x4 a0 = *(const LAS f32x4*)(st + rd_off), a1 = *(const LAS f32x4*)(st + rd_off + 8 * 144);
;                 { const f32x4 xv = xb[g & 1][bj][0] + gv[bj] * a0; __builtin_nontemporal_store(xv, (f32x4*)((char*)xo + 4u * ERN_EOFF(g, bj, 0)));
;                   sq0 += (xv.x * xv.x + xv.y * xv.y) + (xv.z * xv.z + xv.w * xv.w);
;                   const f32x4 hv = xv * gsn[bj]; hw[bj][0].x = cvt_pk_bf16(hv.x, hv.y); hw[bj][0].y = cvt_pk_bf16(hv.z, hv.w); }
;                 { const f32x4 xv = xb[g & 1][bj][1] + gv[bj] * a1; __builtin_nontemporal_store(xv, (f32x4*)((char*)xo + 4u * ERN_EOFF(g, bj, 1)));
;                   sq1 += (xv.x * xv.x + xv.y * xv.y) + (xv.z * xv.z + xv.w * xv.w);
;                   const f32x4 hv = xv * gsn[bj]; hw[bj][1].x = cvt_pk_bf16(hv.x, hv.y); hw[bj][1].y = cvt_pk_bf16(hv.z, hv.w); }
;             }
;             if (!NOH && !PLAIN) {
; #pragma unroll
;                 for (int rh = 0; rh < 2; ++rh) { u32x2 rv; rv.x = __shfl_xor(hw[1][rh].x, 8); rv.y = __shfl_xor(hw[1][rh].y, 8);
;                     const unsigned e0 = ERN_EOFF(g, 0, rh);
;                     const unsigned ee = odd ? (e0 - DM + 32) : e0, eo2 = odd ? e0 : (e0 + DM + 32);
;                     *(u32x2*)((char*)ho + 2u * ee) = odd ? rv : hw[0][rh];
;                     *(u32x2*)((char*)ho + 2u * eo2) = odd ? hw[0][rh] : rv; }
;             }
;             if (!PLAIN) { sq0 += __shfl_xor(sq0, 1); sq0 += __shfl_xor(sq0, 2); sq0 += __shfl_xor(sq0, 4);
;             sq1 += __shfl_xor(sq1, 1); sq1 += __shfl_xor(sq1, 2); sq1 += __shfl_xor(sq1, 4); }
;             if (!PLAIN && pc == 0) { sst[g * 16 + rr] = sq0; sst[g * 16 + 8 + rr] = sq1; }
.LBB0_1949:
	s_or_b64 exec, exec, s[22:23]
	v_lshl_add_u64 v[134:135], s[20:21], 0, v[154:155]
	v_add_u32_e32 v98, 0x60000, v205
	v_add_u32_e32 v154, 0x70000, v205
	v_add_u32_e32 v130, 0x60080, v205
	global_load_dwordx4 v[106:109], v154, s[20:21]
	global_load_dwordx4 v[102:105], v130, s[20:21]
	v_add_u32_e32 v132, 0x70080, v205
	global_load_dwordx4 v[110:113], v98, s[20:21]
	s_waitcnt lgkmcnt(0)
	global_load_dwordx4 v[98:101], v132, s[20:21]
	ds_write_b128 v200, v[94:97]
	ds_write_b128 v200, v[90:93] offset:64
	ds_read_b128 v[90:93], v201
	ds_read_b128 v[94:97], v201 offset:1152
	v_mov_b32_e32 v187, v155
	v_mov_b32_e32 v189, v155
	s_waitcnt vmcnt(12) lgkmcnt(1)
	v_pk_fma_f32 v[92:93], v[176:177], v[92:93], v[128:129]
	v_add_u32_e32 v128, 0x10000, v202
	v_pk_fma_f32 v[90:91], v[180:181], v[90:91], v[126:127]
	v_lshlrev_b32_e32 v126, 2, v128
	s_waitcnt lgkmcnt(0)
	v_pk_fma_f32 v[94:95], v[180:181], v[94:95], v[122:123]
	global_store_dwordx4 v126, v[90:93], s[20:21] nt
	v_pk_mul_f32 v[126:127], v[178:179], v[90:91]
	v_pk_fma_f32 v[96:97], v[176:177], v[96:97], v[124:125]
	v_pk_mul_f32 v[122:123], v[178:179], v[94:95]
	v_pk_mul_f32 v[136:137], v[174:175], v[92:93]
	v_cvt_pk_bf16_f32 v126, v126, v127
	v_pk_mul_f32 v[124:125], v[174:175], v[96:97]
	v_cvt_pk_bf16_f32 v127, v136, v137
	global_store_dwordx4 v[134:135], v[94:97], off nt
	v_cvt_pk_bf16_f32 v122, v122, v123
	v_cvt_pk_bf16_f32 v123, v124, v125
	ds_write_b128 v200, v[86:89]
	ds_write_b128 v200, v[82:85] offset:64
	ds_read_b128 v[82:85], v201
	ds_read_b128 v[86:89], v201 offset:1152
	v_lshl_add_u64 v[124:125], s[20:21], 0, v[186:187]
	v_lshl_add_u64 v[134:135], s[20:21], 0, v[188:189]
	s_waitcnt lgkmcnt(1)
	v_pk_fma_f32 v[82:83], v[168:169], v[82:83], v[118:119]
	v_pk_fma_f32 v[84:85], v[166:167], v[84:85], v[120:121]
	v_pk_mul_f32 v[120:121], v[172:173], v[82:83]
	global_store_dwordx4 v[124:125], v[82:85], off nt
	v_pk_mul_f32 v[118:119], v[170:171], v[84:85]
	v_cvt_pk_bf16_f32 v120, v120, v121
	s_waitcnt vmcnt(14) lgkmcnt(0)
	v_pk_fma_f32 v[86:87], v[168:169], v[86:87], v[114:115]
	v_cvt_pk_bf16_f32 v121, v118, v119
	ds_bpermute_b32 v114, v203, v120
	ds_bpermute_b32 v115, v203, v121
	v_pk_fma_f32 v[88:89], v[166:167], v[88:89], v[116:117]
	v_pk_mul_f32 v[116:117], v[172:173], v[86:87]
	v_pk_mul_f32 v[118:119], v[170:171], v[88:89]
	global_store_dwordx4 v[134:135], v[86:89], off nt
	v_cvt_pk_bf16_f32 v116, v116, v117
	v_cvt_pk_bf16_f32 v117, v118, v119
	v_lshlrev_b32_e32 v118, 1, v128
	s_waitcnt lgkmcnt(0)
	v_add_u32_e32 v250, 0xfffff040, v118
	v_cndmask_b32_e64 v250, v118, v250, s[40:41]
	v_cndmask_b32_e64 v248, v126, v114, s[40:41]
	v_cndmask_b32_e64 v249, v127, v115, s[40:41]
	global_store_dwordx2 v250, v[248:249], s[18:19]
	v_cndmask_b32_e64 v246, v114, v126, s[40:41]
	v_cndmask_b32_e64 v247, v115, v127, s[40:41]
	s_waitcnt lgkmcnt(1)
	v_add_u32_e32 v114, 0x1040, v118
	v_cndmask_b32_e64 v114, v118, v114, s[38:39]
	global_store_dwordx2 v114, v[246:247], s[18:19]
	ds_bpermute_b32 v114, v203, v116
	s_waitcnt lgkmcnt(1)
	ds_bpermute_b32 v115, v203, v117
	v_add_u32_e32 v117, 0x14000, v202
	v_lshlrev_b32_e32 v116, 1, v117
	s_waitcnt lgkmcnt(0)
	v_add_u32_e32 v250, 0xfffff040, v116
	v_cndmask_b32_e64 v250, v116, v250, s[40:41]
	v_cndmask_b32_e64 v248, v122, v114, s[40:41]
	v_cndmask_b32_e64 v249, v123, v115, s[40:41]
	global_store_dwordx2 v250, v[248:249], s[18:19]
	v_cndmask_b32_e64 v246, v114, v122, s[40:41]
	v_cndmask_b32_e64 v247, v115, v123, s[40:41]
	v_mul_f32_e32 v83, v83, v83
	v_fmac_f32_e32 v83, v82, v82
	v_mul_f32_e32 v82, v85, v85
	v_mul_f32_e32 v93, v93, v93
	v_fmac_f32_e32 v82, v84, v84
	v_mul_f32_e32 v91, v91, v91
	v_fmac_f32_e32 v93, v92, v92
	v_mul_f32_e32 v92, v95, v95
	v_mul_f32_e32 v95, v97, v97
	v_add_f32_e32 v82, v83, v82
	v_mul_f32_e32 v83, v87, v87
	v_mul_f32_e32 v84, v89, v89
	v_fmac_f32_e32 v95, v96, v96
	v_fmac_f32_e32 v83, v86, v86
	v_fmac_f32_e32 v84, v88, v88
	v_fmac_f32_e32 v91, v90, v90
	v_fmac_f32_e32 v92, v94, v94
	v_add_f32_e32 v83, v83, v84
	v_add_f32_e32 v84, v91, v93
	v_add_f32_e32 v85, v92, v95
	v_add_f32_e32 v82, v84, v82
	v_add_f32_e32 v83, v85, v83
	ds_bpermute_b32 v84, v190, v82
	ds_bpermute_b32 v85, v190, v83
	s_waitcnt lgkmcnt(1)
	v_add_f32_e32 v82, v82, v84
	s_waitcnt lgkmcnt(0)
	v_add_f32_e32 v85, v83, v85
	ds_bpermute_b32 v84, v191, v82
	ds_bpermute_b32 v86, v191, v85
	s_waitcnt lgkmcnt(1)
	v_add_f32_e32 v82, v82, v84
	s_waitcnt lgkmcnt(0)
	v_add_f32_e32 v84, v85, v86
	ds_bpermute_b32 v83, v204, v82
	ds_bpermute_b32 v85, v204, v84
	v_add_u32_e32 v86, 0x1040, v116
	v_cndmask_b32_e64 v86, v116, v86, s[38:39]
	global_store_dwordx2 v86, v[246:247], s[18:19]
	s_and_saveexec_b64 s[22:23], s[42:43]
	s_cbranch_execz .LBB0_1959
	s_waitcnt lgkmcnt(1)
	v_add_f32_e32 v82, v82, v83
	s_waitcnt lgkmcnt(0)
	v_add_f32_e32 v83, v84, v85
	ds_write2_b32 v194, v82, v83 offset0:32 offset1:40
; #define LAS __attribute__((address_space(3)))
; #define ERN_EOFF(q, m) (eb + (unsigned)((((q) & 1) * HALF + (m) * 16) * DM + ERN_COL((q) >> 1)))
;     __device__ __forceinline__ void operator()(const f32x4 (&acc)[2][2][4][2], const Unit& u, int wr, int wc, int fr, int fq) const {
;     ...
;         ERN_LOADX(0);
; #pragma unroll
;         for (int g = 0; g < 8; ++g) { const int ai = g >> 2, m = g & 3;
;             if (g + 1 < 8) ERN_LOADX(g + 1);
;             float sq0 = 0.f, sq1 = 0.f; u32x2 hw[2][2];
; #pragma unroll
;             for (int bj = 0; bj < 2; ++bj) {
;                 *(LAS f32x4*)(st + wr_off) = acc[ai][bj][m][0]; *(LAS f32x4*)(st + wr_off + 64) = acc[ai][bj][m][1];
;                 const f32x4 a0 = *(const LAS f32x4*)(st + rd_off), a1 = *(const LAS f32x4*)(st + rd_off + 8 * 144);
;                 { const f32x4 xv = xb[g & 1][bj][0] + gv[bj] * a0; __builtin_nontemporal_store(xv, (f32x4*)((char*)xo + 4u * ERN_EOFF(g, bj, 0)));
;                   sq0 += (xv.x * xv.x + xv.y * xv.y) + (xv.z * xv.z + xv.w * xv.w);
;                   const f32x4 hv = xv * gsn[bj]; hw[bj][0].x = cvt_pk_bf16(hv.x, hv.y); hw[bj][0].y = cvt_pk_bf16(hv.z, hv.w); }
;                 { const f32x4 xv = xb[g & 1][bj][1] + gv[bj] * a1; __builtin_nontemporal_store(xv, (f32x4*)((char*)xo + 4u * ERN_EOFF(g, bj, 1)));
;                   sq1 += (xv.x * xv.x + xv.y * xv.y) + (xv.z * xv.z + xv.w * xv.w);
;                   const f32x4 hv = xv * gsn[bj]; hw[bj][1].x = cvt_pk_bf16(hv.x, hv.y); hw[bj][1].y = cvt_pk_bf16(hv.z, hv.w); }
;             }
;             if (!NOH && !PLAIN) {
; #pragma unroll
;                 for (int rh = 0; rh < 2; ++rh) { u32x2 rv; rv.x = __shfl_xor(hw[1][rh].x, 8); rv.y = __shfl_xor(hw[1][rh].y, 8);
;                     const unsigned e0 = ERN_EOFF(g, 0, rh);
;                     const unsigned ee = odd ? (e0 - DM + 32) : e0, eo2 = odd ? e0 : (e0 + DM + 32);
;                     *(u32x2*)((char*)ho + 2u * ee) = odd ? rv : hw[0][rh];
;                     *(u32x2*)((char*)ho + 2u * eo2) = odd ? hw[0][rh] : rv; }
;             }
;             if (!PLAIN) { sq0 += __shfl_xor(sq0, 1); sq0 += __shfl_xor(sq0, 2); sq0 += __shfl_xor(sq0, 4);
;             sq1 += __shfl_xor(sq1, 1); sq1 += __shfl_xor(sq1, 2); sq1 += __shfl_xor(sq1, 4); }
;             if (!PLAIN && pc == 0) { sst[g * 16 + rr] = sq0; sst[g * 16 + 8 + rr] = sq1; }
.LBB0_1959:
	s_or_b64 exec, exec, s[22:23]
	v_lshl_add_u64 v[116:117], s[20:21], 0, v[154:155]
	v_add_u32_e32 v82, 0x100000, v205
	s_waitcnt lgkmcnt(1)
	v_add_u32_e32 v83, 0x110000, v205
	v_add_u32_e32 v154, 0x100080, v205
	global_load_dwordx4 v[94:97], v82, s[20:21]
	global_load_dwordx4 v[90:93], v83, s[20:21]
	v_add_u32_e32 v114, 0x110080, v205
	global_load_dwordx4 v[86:89], v154, s[20:21]
	s_waitcnt lgkmcnt(0)
	global_load_dwordx4 v[82:85], v114, s[20:21]
	ds_write_b128 v200, v[78:81]
	ds_write_b128 v200, v[74:77] offset:64
	ds_read_b128 v[74:77], v201
	ds_read_b128 v[78:81], v201 offset:1152
	v_mov_b32_e32 v131, v155
	v_mov_b32_e32 v133, v155
	s_waitcnt vmcnt(12) lgkmcnt(1)
	v_pk_fma_f32 v[76:77], v[176:177], v[76:77], v[112:113]
	v_add_u32_e32 v112, 0x18000, v202
	v_pk_fma_f32 v[74:75], v[180:181], v[74:75], v[110:111]
	v_lshlrev_b32_e32 v110, 2, v112
	s_waitcnt lgkmcnt(0)
	v_pk_fma_f32 v[78:79], v[180:181], v[78:79], v[106:107]
	global_store_dwordx4 v110, v[74:77], s[20:21] nt
	v_pk_mul_f32 v[110:111], v[178:179], v[74:75]
	v_pk_fma_f32 v[80:81], v[176:177], v[80:81], v[108:109]
	v_pk_mul_f32 v[106:107], v[178:179], v[78:79]
	v_pk_mul_f32 v[118:119], v[174:175], v[76:77]
	v_cvt_pk_bf16_f32 v110, v110, v111
	v_pk_mul_f32 v[108:109], v[174:175], v[80:81]
	v_cvt_pk_bf16_f32 v111, v118, v119
	global_store_dwordx4 v[116:117], v[78:81], off nt
	v_cvt_pk_bf16_f32 v106, v106, v107
	v_cvt_pk_bf16_f32 v107, v108, v109
	ds_write_b128 v200, v[70:73]
	ds_write_b128 v200, v[66:69] offset:64
	ds_read_b128 v[66:69], v201
	ds_read_b128 v[70:73], v201 offset:1152
	v_lshl_add_u64 v[108:109], s[20:21], 0, v[130:131]
	v_lshl_add_u64 v[116:117], s[20:21], 0, v[132:133]
	s_waitcnt lgkmcnt(1)
	v_pk_fma_f32 v[66:67], v[168:169], v[66:67], v[102:103]
	v_pk_fma_f32 v[68:69], v[166:167], v[68:69], v[104:105]
	v_pk_mul_f32 v[104:105], v[172:173], v[66:67]
	global_store_dwordx4 v[108:109], v[66:69], off nt
	v_pk_mul_f32 v[102:103], v[170:171], v[68:69]
	v_cvt_pk_bf16_f32 v104, v104, v105
	s_waitcnt vmcnt(14) lgkmcnt(0)
	v_pk_fma_f32 v[70:71], v[168:169], v[70:71], v[98:99]
	v_cvt_pk_bf16_f32 v105, v102, v103
	ds_bpermute_b32 v98, v203, v104
	ds_bpermute_b32 v99, v203, v105
	v_pk_fma_f32 v[72:73], v[166:167], v[72:73], v[100:101]
	v_pk_mul_f32 v[100:101], v[172:173], v[70:71]
	v_pk_mul_f32 v[102:103], v[170:171], v[72:73]
	global_store_dwordx4 v[116:117], v[70:73], off nt
	v_cvt_pk_bf16_f32 v100, v100, v101
	v_cvt_pk_bf16_f32 v101, v102, v103
	v_lshlrev_b32_e32 v102, 1, v112
	s_waitcnt lgkmcnt(0)
	v_add_u32_e32 v250, 0xfffff040, v102
	v_cndmask_b32_e64 v250, v102, v250, s[40:41]
	v_cndmask_b32_e64 v248, v110, v98, s[40:41]
	v_cndmask_b32_e64 v249, v111, v99, s[40:41]
	global_store_dwordx2 v250, v[248:249], s[18:19]
	v_cndmask_b32_e64 v246, v98, v110, s[40:41]
	v_cndmask_b32_e64 v247, v99, v111, s[40:41]
	s_waitcnt lgkmcnt(1)
	v_add_u32_e32 v98, 0x1040, v102
	v_cndmask_b32_e64 v98, v102, v98, s[38:39]
	global_store_dwordx2 v98, v[246:247], s[18:19]
	ds_bpermute_b32 v98, v203, v100
	s_waitcnt lgkmcnt(1)
	ds_bpermute_b32 v99, v203, v101
	v_add_u32_e32 v101, 0x1c000, v202
	v_lshlrev_b32_e32 v100, 1, v101
	s_waitcnt lgkmcnt(0)
	v_add_u32_e32 v250, 0xfffff040, v100
	v_cndmask_b32_e64 v250, v100, v250, s[40:41]
	v_cndmask_b32_e64 v248, v106, v98, s[40:41]
	v_cndmask_b32_e64 v249, v107, v99, s[40:41]
	global_store_dwordx2 v250, v[248:249], s[18:19]
	v_cndmask_b32_e64 v246, v98, v106, s[40:41]
	v_cndmask_b32_e64 v247, v99, v107, s[40:41]
	v_mul_f32_e32 v67, v67, v67
	v_fmac_f32_e32 v67, v66, v66
	v_mul_f32_e32 v66, v69, v69
	v_mul_f32_e32 v77, v77, v77
	v_fmac_f32_e32 v66, v68, v68
	v_mul_f32_e32 v75, v75, v75
	v_fmac_f32_e32 v77, v76, v76
	v_mul_f32_e32 v76, v79, v79
	v_mul_f32_e32 v79, v81, v81
	v_add_f32_e32 v66, v67, v66
	v_mul_f32_e32 v67, v71, v71
	v_mul_f32_e32 v68, v73, v73
	v_fmac_f32_e32 v79, v80, v80
	v_fmac_f32_e32 v67, v70, v70
	v_fmac_f32_e32 v68, v72, v72
	v_fmac_f32_e32 v75, v74, v74
	v_fmac_f32_e32 v76, v78, v78
	v_add_f32_e32 v67, v67, v68
	v_add_f32_e32 v68, v75, v77
	v_add_f32_e32 v69, v76, v79
	v_add_f32_e32 v66, v68, v66
	v_add_f32_e32 v67, v69, v67
	ds_bpermute_b32 v68, v190, v66
	ds_bpermute_b32 v69, v190, v67
	s_waitcnt lgkmcnt(1)
	v_add_f32_e32 v66, v66, v68
	s_waitcnt lgkmcnt(0)
	v_add_f32_e32 v69, v67, v69
	ds_bpermute_b32 v68, v191, v66
	ds_bpermute_b32 v70, v191, v69
	s_waitcnt lgkmcnt(1)
	v_add_f32_e32 v66, v66, v68
	s_waitcnt lgkmcnt(0)
	v_add_f32_e32 v68, v69, v70
	ds_bpermute_b32 v67, v204, v66
	ds_bpermute_b32 v69, v204, v68
	v_add_u32_e32 v70, 0x1040, v100
	v_cndmask_b32_e64 v70, v100, v70, s[38:39]
	global_store_dwordx2 v70, v[246:247], s[18:19]
	s_and_saveexec_b64 s[22:23], s[42:43]
	s_cbranch_execz .LBB0_1969
	s_waitcnt lgkmcnt(1)
	v_add_f32_e32 v66, v66, v67
	s_waitcnt lgkmcnt(0)
	v_add_f32_e32 v67, v68, v69
	ds_write2_b32 v194, v66, v67 offset0:48 offset1:56
; #define LAS __attribute__((address_space(3)))
; #define ERN_EOFF(q, m) (eb + (unsigned)((((q) & 1) * HALF + (m) * 16) * DM + ERN_COL((q) >> 1)))
;     __device__ __forceinline__ void operator()(const f32x4 (&acc)[2][2][4][2], const Unit& u, int wr, int wc, int fr, int fq) const {
;     ...
;         ERN_LOADX(0);
; #pragma unroll
;         for (int g = 0; g < 8; ++g) { const int ai = g >> 2, m = g & 3;
;             if (g + 1 < 8) ERN_LOADX(g + 1);
;             float sq0 = 0.f, sq1 = 0.f; u32x2 hw[2][2];
; #pragma unroll
;             for (int bj = 0; bj < 2; ++bj) {
;                 *(LAS f32x4*)(st + wr_off) = acc[ai][bj][m][0]; *(LAS f32x4*)(st + wr_off + 64) = acc[ai][bj][m][1];
;                 const f32x4 a0 = *(const LAS f32x4*)(st + rd_off), a1 = *(const LAS f32x4*)(st + rd_off + 8 * 144);
;                 { const f32x4 xv = xb[g & 1][bj][0] + gv[bj] * a0; __builtin_nontemporal_store(xv, (f32x4*)((char*)xo + 4u * ERN_EOFF(g, bj, 0)));
;                   sq0 += (xv.x * xv.x + xv.y * xv.y) + (xv.z * xv.z + xv.w * xv.w);
;                   const f32x4 hv = xv * gsn[bj]; hw[bj][0].x = cvt_pk_bf16(hv.x, hv.y); hw[bj][0].y = cvt_pk_bf16(hv.z, hv.w); }
;                 { const f32x4 xv = xb[g & 1][bj][1] + gv[bj] * a1; __builtin_nontemporal_store(xv, (f32x4*)((char*)xo + 4u * ERN_EOFF(g, bj, 1)));
;                   sq1 += (xv.x * xv.x + xv.y * xv.y) + (xv.z * xv.z + xv.w * xv.w);
;                   const f32x4 hv = xv * gsn[bj]; hw[bj][1].x = cvt_pk_bf16(hv.x, hv.y); hw[bj][1].y = cvt_pk_bf16(hv.z, hv.w); }
;             }
;             if (!NOH && !PLAIN) {
; #pragma unroll
;                 for (int rh = 0; rh < 2; ++rh) { u32x2 rv; rv.x = __shfl_xor(hw[1][rh].x, 8); rv.y = __shfl_xor(hw[1][rh].y, 8);
;                     const unsigned e0 = ERN_EOFF(g, 0, rh);
;                     const unsigned ee = odd ? (e0 - DM + 32) : e0, eo2 = odd ? e0 : (e0 + DM + 32);
;                     *(u32x2*)((char*)ho + 2u * ee) = odd ? rv : hw[0][rh];
;                     *(u32x2*)((char*)ho + 2u * eo2) = odd ? hw[0][rh] : rv; }
;             }
;             if (!PLAIN) { sq0 += __shfl_xor(sq0, 1); sq0 += __shfl_xor(sq0, 2); sq0 += __shfl_xor(sq0, 4);
;             sq1 += __shfl_xor(sq1, 1); sq1 += __shfl_xor(sq1, 2); sq1 += __shfl_xor(sq1, 4); }
;             if (!PLAIN && pc == 0) { sst[g * 16 + rr] = sq0; sst[g * 16 + 8 + rr] = sq1; }
.LBB0_1969:
	s_or_b64 exec, exec, s[22:23]
	v_lshl_add_u64 v[104:105], s[20:21], 0, v[154:155]
	v_add_u32_e32 v154, 0x120000, v205
	v_add_u32_e32 v100, 0x120080, v205
	v_add_u32_e32 v102, 0x130000, v205
	global_load_dwordx4 v[78:81], v154, s[20:21]
	global_load_dwordx4 v[74:77], v102, s[20:21]
	v_add_u32_e32 v98, 0x130080, v205
	global_load_dwordx4 v[70:73], v100, s[20:21]
	s_waitcnt lgkmcnt(0)
	global_load_dwordx4 v[66:69], v98, s[20:21]
	ds_write_b128 v200, v[62:65]
	ds_write_b128 v200, v[58:61] offset:64
	ds_read_b128 v[58:61], v201
	ds_read_b128 v[62:65], v201 offset:1152
	v_mov_b32_e32 v115, v155
	s_waitcnt vmcnt(14) lgkmcnt(1)
	v_pk_fma_f32 v[60:61], v[176:177], v[60:61], v[96:97]
	v_add_u32_e32 v96, 0x40000, v202
	v_pk_fma_f32 v[58:59], v[180:181], v[58:59], v[94:95]
	v_lshlrev_b32_e32 v94, 2, v96
	s_waitcnt vmcnt(13) lgkmcnt(0)
	v_pk_fma_f32 v[64:65], v[176:177], v[64:65], v[92:93]
	v_add_u32_e32 v92, 0x44000, v202
	global_store_dwordx4 v94, v[58:61], s[20:21] nt
	v_pk_mul_f32 v[94:95], v[178:179], v[58:59]
	v_pk_fma_f32 v[62:63], v[180:181], v[62:63], v[90:91]
	v_lshlrev_b32_e32 v90, 2, v92
	v_pk_mul_f32 v[106:107], v[174:175], v[60:61]
	v_cvt_pk_bf16_f32 v94, v94, v95
	s_nop 0
	v_cvt_pk_bf16_f32 v95, v106, v107
	global_store_dwordx4 v90, v[62:65], s[20:21] nt
	v_pk_mul_f32 v[90:91], v[178:179], v[62:63]
	v_pk_mul_f32 v[106:107], v[174:175], v[64:65]
	v_cvt_pk_bf16_f32 v90, v90, v91
	s_nop 0
	v_cvt_pk_bf16_f32 v91, v106, v107
	ds_write_b128 v200, v[54:57]
	ds_write_b128 v200, v[50:53] offset:64
	ds_read_b128 v[50:53], v201
	ds_read_b128 v[54:57], v201 offset:1152
	v_lshl_add_u64 v[106:107], s[20:21], 0, v[114:115]
	s_waitcnt vmcnt(14) lgkmcnt(1)
	v_pk_fma_f32 v[50:51], v[168:169], v[50:51], v[86:87]
	v_pk_fma_f32 v[52:53], v[166:167], v[52:53], v[88:89]
	v_pk_mul_f32 v[88:89], v[172:173], v[50:51]
	global_store_dwordx4 v[104:105], v[50:53], off nt
	v_pk_mul_f32 v[86:87], v[170:171], v[52:53]
	v_cvt_pk_bf16_f32 v88, v88, v89
	s_waitcnt vmcnt(14) lgkmcnt(0)
	v_pk_fma_f32 v[54:55], v[168:169], v[54:55], v[82:83]
	v_cvt_pk_bf16_f32 v89, v86, v87
	ds_bpermute_b32 v82, v203, v88
	ds_bpermute_b32 v83, v203, v89
	v_pk_fma_f32 v[56:57], v[166:167], v[56:57], v[84:85]
	v_pk_mul_f32 v[84:85], v[172:173], v[54:55]
	v_pk_mul_f32 v[86:87], v[170:171], v[56:57]
	global_store_dwordx4 v[106:107], v[54:57], off nt
	v_cvt_pk_bf16_f32 v84, v84, v85
	v_cvt_pk_bf16_f32 v85, v86, v87
	v_lshlrev_b32_e32 v86, 1, v96
	s_waitcnt lgkmcnt(0)
	v_add_u32_e32 v250, 0xfffff040, v86
	v_cndmask_b32_e64 v250, v86, v250, s[40:41]
	v_cndmask_b32_e64 v248, v94, v82, s[40:41]
	v_cndmask_b32_e64 v249, v95, v83, s[40:41]
	global_store_dwordx2 v250, v[248:249], s[18:19]
	v_cndmask_b32_e64 v246, v82, v94, s[40:41]
	v_cndmask_b32_e64 v247, v83, v95, s[40:41]
	s_waitcnt lgkmcnt(1)
	v_add_u32_e32 v82, 0x1040, v86
	v_cndmask_b32_e64 v82, v86, v82, s[38:39]
	global_store_dwordx2 v82, v[246:247], s[18:19]
	ds_bpermute_b32 v82, v203, v84
	s_waitcnt lgkmcnt(1)
	ds_bpermute_b32 v83, v203, v85
	v_lshlrev_b32_e32 v84, 1, v92
	s_waitcnt lgkmcnt(0)
	v_add_u32_e32 v250, 0xfffff040, v84
	v_cndmask_b32_e64 v250, v84, v250, s[40:41]
	v_cndmask_b32_e64 v248, v90, v82, s[40:41]
	v_cndmask_b32_e64 v249, v91, v83, s[40:41]
	global_store_dwordx2 v250, v[248:249], s[18:19]
	v_cndmask_b32_e64 v246, v82, v90, s[40:41]
	v_cndmask_b32_e64 v247, v83, v91, s[40:41]
	v_mul_f32_e32 v51, v51, v51
	v_fmac_f32_e32 v51, v50, v50
	v_mul_f32_e32 v50, v53, v53
	v_mul_f32_e32 v61, v61, v61
	v_fmac_f32_e32 v50, v52, v52
	v_mul_f32_e32 v59, v59, v59
	v_fmac_f32_e32 v61, v60, v60
	v_mul_f32_e32 v60, v63, v63
	v_mul_f32_e32 v63, v65, v65
	v_add_f32_e32 v50, v51, v50
	v_mul_f32_e32 v51, v55, v55
	v_mul_f32_e32 v52, v57, v57
	v_fmac_f32_e32 v63, v64, v64
	v_fmac_f32_e32 v51, v54, v54
	v_fmac_f32_e32 v52, v56, v56
	v_fmac_f32_e32 v59, v58, v58
	v_fmac_f32_e32 v60, v62, v62
	v_add_f32_e32 v51, v51, v52
	v_add_f32_e32 v52, v59, v61
	v_add_f32_e32 v53, v60, v63
	v_add_f32_e32 v50, v52, v50
	v_add_f32_e32 v51, v53, v51
	ds_bpermute_b32 v52, v190, v50
	ds_bpermute_b32 v53, v190, v51
	s_waitcnt lgkmcnt(1)
	v_add_f32_e32 v50, v50, v52
	s_waitcnt lgkmcnt(0)
	v_add_f32_e32 v53, v51, v53
	ds_bpermute_b32 v52, v191, v50
	ds_bpermute_b32 v54, v191, v53
	s_waitcnt lgkmcnt(1)
	v_add_f32_e32 v50, v50, v52
	s_waitcnt lgkmcnt(0)
	v_add_f32_e32 v52, v53, v54
	ds_bpermute_b32 v51, v204, v50
	ds_bpermute_b32 v53, v204, v52
	v_add_u32_e32 v54, 0x1040, v84
	v_cndmask_b32_e64 v54, v84, v54, s[38:39]
	global_store_dwordx2 v54, v[246:247], s[18:19]
	s_and_saveexec_b64 s[22:23], s[42:43]
	s_cbranch_execz .LBB0_1979
	s_waitcnt lgkmcnt(1)
	v_add_f32_e32 v50, v50, v51
	s_waitcnt lgkmcnt(0)
	v_add_f32_e32 v51, v52, v53
	ds_write2_b32 v194, v50, v51 offset0:64 offset1:72
; #define LAS __attribute__((address_space(3)))
; #define ERN_EOFF(q, m) (eb + (unsigned)((((q) & 1) * HALF + (m) * 16) * DM + ERN_COL((q) >> 1)))
;     __device__ __forceinline__ void operator()(const f32x4 (&acc)[2][2][4][2], const Unit& u, int wr, int wc, int fr, int fq) const {
;     ...
;         ERN_LOADX(0);
; #pragma unroll
;         for (int g = 0; g < 8; ++g) { const int ai = g >> 2, m = g & 3;
;             if (g + 1 < 8) ERN_LOADX(g + 1);
;             float sq0 = 0.f, sq1 = 0.f; u32x2 hw[2][2];
; #pragma unroll
;             for (int bj = 0; bj < 2; ++bj) {
;                 *(LAS f32x4*)(st + wr_off) = acc[ai][bj][m][0]; *(LAS f32x4*)(st + wr_off + 64) = acc[ai][bj][m][1];
;                 const f32x4 a0 = *(const LAS f32x4*)(st + rd_off), a1 = *(const LAS f32x4*)(st + rd_off + 8 * 144);
;                 { const f32x4 xv = xb[g & 1][bj][0] + gv[bj] * a0; __builtin_nontemporal_store(xv, (f32x4*)((char*)xo + 4u * ERN_EOFF(g, bj, 0)));
;                   sq0 += (xv.x * xv.x + xv.y * xv.y) + (xv.z * xv.z + xv.w * xv.w);
;                   const f32x4 hv = xv * gsn[bj]; hw[bj][0].x = cvt_pk_bf16(hv.x, hv.y); hw[bj][0].y = cvt_pk_bf16(hv.z, hv.w); }
;                 { const f32x4 xv = xb[g & 1][bj][1] + gv[bj] * a1; __builtin_nontemporal_store(xv, (f32x4*)((char*)xo + 4u * ERN_EOFF(g, bj, 1)));
;                   sq1 += (xv.x * xv.x + xv.y * xv.y) + (xv.z * xv.z + xv.w * xv.w);
;                   const f32x4 hv = xv * gsn[bj]; hw[bj][1].x = cvt_pk_bf16(hv.x, hv.y); hw[bj][1].y = cvt_pk_bf16(hv.z, hv.w); }
;             }
;             if (!NOH && !PLAIN) {
; #pragma unroll
;                 for (int rh = 0; rh < 2; ++rh) { u32x2 rv; rv.x = __shfl_xor(hw[1][rh].x, 8); rv.y = __shfl_xor(hw[1][rh].y, 8);
;                     const unsigned e0 = ERN_EOFF(g, 0, rh);
;                     const unsigned ee = odd ? (e0 - DM + 32) : e0, eo2 = odd ? e0 : (e0 + DM + 32);
;                     *(u32x2*)((char*)ho + 2u * ee) = odd ? rv : hw[0][rh];
;                     *(u32x2*)((char*)ho + 2u * eo2) = odd ? hw[0][rh] : rv; }
;             }
;             if (!PLAIN) { sq0 += __shfl_xor(sq0, 1); sq0 += __shfl_xor(sq0, 2); sq0 += __shfl_xor(sq0, 4);
;             sq1 += __shfl_xor(sq1, 1); sq1 += __shfl_xor(sq1, 2); sq1 += __shfl_xor(sq1, 4); }
;             if (!PLAIN && pc == 0) { sst[g * 16 + rr] = sq0; sst[g * 16 + 8 + rr] = sq1; }
.LBB0_1979:
	s_or_b64 exec, exec, s[22:23]
	v_lshl_add_u64 v[88:89], s[20:21], 0, v[154:155]
	v_add_u32_e32 v154, 0x140000, v205
	v_add_u32_e32 v84, 0x140080, v205
	v_add_u32_e32 v86, 0x150000, v205
	global_load_dwordx4 v[62:65], v154, s[20:21]
	global_load_dwordx4 v[58:61], v86, s[20:21]
	v_add_u32_e32 v82, 0x150080, v205
	global_load_dwordx4 v[54:57], v84, s[20:21]
	s_waitcnt lgkmcnt(0)
	global_load_dwordx4 v[50:53], v82, s[20:21]
	ds_write_b128 v200, v[46:49]
	ds_write_b128 v200, v[42:45] offset:64
	ds_read_b128 v[42:45], v201
	ds_read_b128 v[46:49], v201 offset:1152
	v_mov_b32_e32 v103, v155
	v_lshl_add_u64 v[90:91], s[20:21], 0, v[102:103]
	v_mov_b32_e32 v101, v155
	s_waitcnt vmcnt(14) lgkmcnt(1)
	v_pk_fma_f32 v[42:43], v[180:181], v[42:43], v[78:79]
	s_waitcnt vmcnt(13) lgkmcnt(0)
	v_pk_fma_f32 v[46:47], v[180:181], v[46:47], v[74:75]
	v_pk_fma_f32 v[44:45], v[176:177], v[44:45], v[80:81]
	v_pk_mul_f32 v[78:79], v[178:179], v[42:43]
	v_pk_fma_f32 v[48:49], v[176:177], v[48:49], v[76:77]
	v_pk_mul_f32 v[74:75], v[178:179], v[46:47]
	global_store_dwordx4 v[88:89], v[42:45], off nt
	v_pk_mul_f32 v[80:81], v[174:175], v[44:45]
	v_cvt_pk_bf16_f32 v78, v78, v79
	v_pk_mul_f32 v[76:77], v[174:175], v[48:49]
	v_cvt_pk_bf16_f32 v79, v80, v81
	global_store_dwordx4 v[90:91], v[46:49], off nt
	v_cvt_pk_bf16_f32 v74, v74, v75
	v_cvt_pk_bf16_f32 v75, v76, v77
	ds_write_b128 v200, v[38:41]
	ds_write_b128 v200, v[34:37] offset:64
	ds_read_b128 v[34:37], v201
	ds_read_b128 v[38:41], v201 offset:1152
	v_lshl_add_u64 v[76:77], s[20:21], 0, v[100:101]
	v_mov_b32_e32 v99, v155
	v_lshl_add_u64 v[80:81], s[20:21], 0, v[98:99]
	s_waitcnt vmcnt(14) lgkmcnt(1)
	v_pk_fma_f32 v[34:35], v[168:169], v[34:35], v[70:71]
	v_pk_fma_f32 v[36:37], v[166:167], v[36:37], v[72:73]
	v_pk_mul_f32 v[72:73], v[172:173], v[34:35]
	global_store_dwordx4 v[76:77], v[34:37], off nt
	v_pk_mul_f32 v[70:71], v[170:171], v[36:37]
	v_cvt_pk_bf16_f32 v72, v72, v73
	s_waitcnt vmcnt(14) lgkmcnt(0)
	v_pk_fma_f32 v[38:39], v[168:169], v[38:39], v[66:67]
	v_cvt_pk_bf16_f32 v73, v70, v71
	ds_bpermute_b32 v66, v203, v72
	ds_bpermute_b32 v67, v203, v73
	v_pk_fma_f32 v[40:41], v[166:167], v[40:41], v[68:69]
	v_pk_mul_f32 v[68:69], v[172:173], v[38:39]
	v_pk_mul_f32 v[70:71], v[170:171], v[40:41]
	global_store_dwordx4 v[80:81], v[38:41], off nt
	v_cvt_pk_bf16_f32 v68, v68, v69
	v_cvt_pk_bf16_f32 v69, v70, v71
	v_add_u32_e32 v71, 0x48000, v202
	v_lshlrev_b32_e32 v70, 1, v71
	s_waitcnt lgkmcnt(0)
	v_add_u32_e32 v250, 0xfffff040, v70
	v_cndmask_b32_e64 v250, v70, v250, s[40:41]
	v_cndmask_b32_e64 v248, v78, v66, s[40:41]
	v_cndmask_b32_e64 v249, v79, v67, s[40:41]
	global_store_dwordx2 v250, v[248:249], s[18:19]
	v_cndmask_b32_e64 v246, v66, v78, s[40:41]
	v_cndmask_b32_e64 v247, v67, v79, s[40:41]
	s_waitcnt lgkmcnt(1)
	v_add_u32_e32 v66, 0x1040, v70
	v_cndmask_b32_e64 v66, v70, v66, s[38:39]
	global_store_dwordx2 v66, v[246:247], s[18:19]
	ds_bpermute_b32 v66, v203, v68
	s_waitcnt lgkmcnt(1)
	ds_bpermute_b32 v67, v203, v69
	v_add_u32_e32 v69, 0x4c000, v202
	v_lshlrev_b32_e32 v68, 1, v69
	s_waitcnt lgkmcnt(0)
	v_add_u32_e32 v250, 0xfffff040, v68
	v_cndmask_b32_e64 v250, v68, v250, s[40:41]
	v_cndmask_b32_e64 v248, v74, v66, s[40:41]
	v_cndmask_b32_e64 v249, v75, v67, s[40:41]
	global_store_dwordx2 v250, v[248:249], s[18:19]
	v_cndmask_b32_e64 v246, v66, v74, s[40:41]
	v_cndmask_b32_e64 v247, v67, v75, s[40:41]
	v_mul_f32_e32 v35, v35, v35
	v_fmac_f32_e32 v35, v34, v34
	v_mul_f32_e32 v34, v37, v37
	v_mul_f32_e32 v45, v45, v45
	v_fmac_f32_e32 v34, v36, v36
	v_mul_f32_e32 v43, v43, v43
	v_fmac_f32_e32 v45, v44, v44
	v_mul_f32_e32 v44, v47, v47
	v_mul_f32_e32 v47, v49, v49
	v_add_f32_e32 v34, v35, v34
	v_mul_f32_e32 v35, v39, v39
	v_mul_f32_e32 v36, v41, v41
	v_fmac_f32_e32 v47, v48, v48
	v_fmac_f32_e32 v35, v38, v38
	v_fmac_f32_e32 v36, v40, v40
	v_fmac_f32_e32 v43, v42, v42
	v_fmac_f32_e32 v44, v46, v46
	v_add_f32_e32 v35, v35, v36
	v_add_f32_e32 v36, v43, v45
	v_add_f32_e32 v37, v44, v47
	v_add_f32_e32 v34, v36, v34
	v_add_f32_e32 v35, v37, v35
	ds_bpermute_b32 v36, v190, v34
	ds_bpermute_b32 v37, v190, v35
	s_waitcnt lgkmcnt(1)
	v_add_f32_e32 v34, v34, v36
	s_waitcnt lgkmcnt(0)
	v_add_f32_e32 v37, v35, v37
	ds_bpermute_b32 v36, v191, v34
	ds_bpermute_b32 v38, v191, v37
	s_waitcnt lgkmcnt(1)
	v_add_f32_e32 v34, v34, v36
	s_waitcnt lgkmcnt(0)
	v_add_f32_e32 v36, v37, v38
	ds_bpermute_b32 v35, v204, v34
	ds_bpermute_b32 v37, v204, v36
	v_add_u32_e32 v38, 0x1040, v68
	v_cndmask_b32_e64 v38, v68, v38, s[38:39]
	global_store_dwordx2 v38, v[246:247], s[18:19]
	s_and_saveexec_b64 s[22:23], s[42:43]
	s_cbranch_execz .LBB0_1989
	s_waitcnt lgkmcnt(1)
	v_add_f32_e32 v34, v34, v35
	s_waitcnt lgkmcnt(0)
	v_add_f32_e32 v35, v36, v37
	ds_write2_b32 v194, v34, v35 offset0:80 offset1:88
; #define LAS __attribute__((address_space(3)))
; #define ERN_EOFF(q, m) (eb + (unsigned)((((q) & 1) * HALF + (m) * 16) * DM + ERN_COL((q) >> 1)))
;     __device__ __forceinline__ void operator()(const f32x4 (&acc)[2][2][4][2], const Unit& u, int wr, int wc, int fr, int fq) const {
;     ...
;         ERN_LOADX(0);
; #pragma unroll
;         for (int g = 0; g < 8; ++g) { const int ai = g >> 2, m = g & 3;
;             if (g + 1 < 8) ERN_LOADX(g + 1);
;             float sq0 = 0.f, sq1 = 0.f; u32x2 hw[2][2];
; #pragma unroll
;             for (int bj = 0; bj < 2; ++bj) {
;                 *(LAS f32x4*)(st + wr_off) = acc[ai][bj][m][0]; *(LAS f32x4*)(st + wr_off + 64) = acc[ai][bj][m][1];
;                 const f32x4 a0 = *(const LAS f32x4*)(st + rd_off), a1 = *(const LAS f32x4*)(st + rd_off + 8 * 144);
;                 { const f32x4 xv = xb[g & 1][bj][0] + gv[bj] * a0; __builtin_nontemporal_store(xv, (f32x4*)((char*)xo + 4u * ERN_EOFF(g, bj, 0)));
;                   sq0 += (xv.x * xv.x + xv.y * xv.y) + (xv.z * xv.z + xv.w * xv.w);
;                   const f32x4 hv = xv * gsn[bj]; hw[bj][0].x = cvt_pk_bf16(hv.x, hv.y); hw[bj][0].y = cvt_pk_bf16(hv.z, hv.w); }
;                 { const f32x4 xv = xb[g & 1][bj][1] + gv[bj] * a1; __builtin_nontemporal_store(xv, (f32x4*)((char*)xo + 4u * ERN_EOFF(g, bj, 1)));
;                   sq1 += (xv.x * xv.x + xv.y * xv.y) + (xv.z * xv.z + xv.w * xv.w);
;                   const f32x4 hv = xv * gsn[bj]; hw[bj][1].x = cvt_pk_bf16(hv.x, hv.y); hw[bj][1].y = cvt_pk_bf16(hv.z, hv.w); }
;             }
;             if (!NOH && !PLAIN) {
; #pragma unroll
;                 for (int rh = 0; rh < 2; ++rh) { u32x2 rv; rv.x = __shfl_xor(hw[1][rh].x, 8); rv.y = __shfl_xor(hw[1][rh].y, 8);
;                     const unsigned e0 = ERN_EOFF(g, 0, rh);
;                     const unsigned ee = odd ? (e0 - DM + 32) : e0, eo2 = odd ? e0 : (e0 + DM + 32);
;                     *(u32x2*)((char*)ho + 2u * ee) = odd ? rv : hw[0][rh];
;                     *(u32x2*)((char*)ho + 2u * eo2) = odd ? hw[0][rh] : rv; }
;             }
;             if (!PLAIN) { sq0 += __shfl_xor(sq0, 1); sq0 += __shfl_xor(sq0, 2); sq0 += __shfl_xor(sq0, 4);
;             sq1 += __shfl_xor(sq1, 1); sq1 += __shfl_xor(sq1, 2); sq1 += __shfl_xor(sq1, 4); }
;             if (!PLAIN && pc == 0) { sst[g * 16 + rr] = sq0; sst[g * 16 + 8 + rr] = sq1; }
.LBB0_1989:
	s_or_b64 exec, exec, s[22:23]
	v_lshl_add_u64 v[72:73], s[20:21], 0, v[154:155]
	v_add_u32_e32 v154, 0x160000, v205
	v_add_u32_e32 v68, 0x160080, v205
	v_add_u32_e32 v70, 0x170000, v205
	global_load_dwordx4 v[46:49], v154, s[20:21]
	global_load_dwordx4 v[42:45], v70, s[20:21]
	v_add_u32_e32 v66, 0x170080, v205
	global_load_dwordx4 v[38:41], v68, s[20:21]
	s_waitcnt lgkmcnt(0)
	global_load_dwordx4 v[34:37], v66, s[20:21]
	ds_write_b128 v200, v[30:33]
	ds_write_b128 v200, v[26:29] offset:64
	ds_read_b128 v[26:29], v201
	ds_read_b128 v[30:33], v201 offset:1152
	v_mov_b32_e32 v87, v155
	v_lshl_add_u64 v[74:75], s[20:21], 0, v[86:87]
	v_mov_b32_e32 v85, v155
	s_waitcnt vmcnt(14) lgkmcnt(1)
	v_pk_fma_f32 v[26:27], v[180:181], v[26:27], v[62:63]
	s_waitcnt vmcnt(13) lgkmcnt(0)
	v_pk_fma_f32 v[30:31], v[180:181], v[30:31], v[58:59]
	v_pk_fma_f32 v[28:29], v[176:177], v[28:29], v[64:65]
	v_pk_mul_f32 v[62:63], v[178:179], v[26:27]
	v_pk_fma_f32 v[32:33], v[176:177], v[32:33], v[60:61]
	v_pk_mul_f32 v[58:59], v[178:179], v[30:31]
	global_store_dwordx4 v[72:73], v[26:29], off nt
	v_pk_mul_f32 v[64:65], v[174:175], v[28:29]
	v_cvt_pk_bf16_f32 v62, v62, v63
	v_pk_mul_f32 v[60:61], v[174:175], v[32:33]
	v_cvt_pk_bf16_f32 v63, v64, v65
	global_store_dwordx4 v[74:75], v[30:33], off nt
	v_cvt_pk_bf16_f32 v58, v58, v59
	v_cvt_pk_bf16_f32 v59, v60, v61
	ds_write_b128 v200, v[22:25]
	ds_write_b128 v200, v[18:21] offset:64
	ds_read_b128 v[18:21], v201
	ds_read_b128 v[22:25], v201 offset:1152
	v_lshl_add_u64 v[60:61], s[20:21], 0, v[84:85]
	v_mov_b32_e32 v83, v155
	v_lshl_add_u64 v[64:65], s[20:21], 0, v[82:83]
	s_waitcnt vmcnt(14) lgkmcnt(1)
	v_pk_fma_f32 v[18:19], v[168:169], v[18:19], v[54:55]
	v_pk_fma_f32 v[20:21], v[166:167], v[20:21], v[56:57]
	v_pk_mul_f32 v[56:57], v[172:173], v[18:19]
	global_store_dwordx4 v[60:61], v[18:21], off nt
	v_pk_mul_f32 v[54:55], v[170:171], v[20:21]
	v_cvt_pk_bf16_f32 v56, v56, v57
	s_waitcnt vmcnt(14) lgkmcnt(0)
	v_pk_fma_f32 v[22:23], v[168:169], v[22:23], v[50:51]
	v_cvt_pk_bf16_f32 v57, v54, v55
	ds_bpermute_b32 v50, v203, v56
	ds_bpermute_b32 v51, v203, v57
	v_pk_fma_f32 v[24:25], v[166:167], v[24:25], v[52:53]
	v_pk_mul_f32 v[52:53], v[172:173], v[22:23]
	v_pk_mul_f32 v[54:55], v[170:171], v[24:25]
	global_store_dwordx4 v[64:65], v[22:25], off nt
	v_cvt_pk_bf16_f32 v52, v52, v53
	v_cvt_pk_bf16_f32 v53, v54, v55
	v_add_u32_e32 v55, 0x50000, v202
	v_lshlrev_b32_e32 v54, 1, v55
	s_waitcnt lgkmcnt(0)
	v_add_u32_e32 v250, 0xfffff040, v54
	v_cndmask_b32_e64 v250, v54, v250, s[40:41]
	v_cndmask_b32_e64 v248, v62, v50, s[40:41]
	v_cndmask_b32_e64 v249, v63, v51, s[40:41]
	global_store_dwordx2 v250, v[248:249], s[18:19]
	v_cndmask_b32_e64 v246, v50, v62, s[40:41]
	v_cndmask_b32_e64 v247, v51, v63, s[40:41]
	s_waitcnt lgkmcnt(1)
	v_add_u32_e32 v50, 0x1040, v54
	v_cndmask_b32_e64 v50, v54, v50, s[38:39]
	global_store_dwordx2 v50, v[246:247], s[18:19]
	ds_bpermute_b32 v50, v203, v52
	s_waitcnt lgkmcnt(1)
	ds_bpermute_b32 v51, v203, v53
	v_add_u32_e32 v53, 0x54000, v202
	v_lshlrev_b32_e32 v52, 1, v53
	s_waitcnt lgkmcnt(0)
	v_add_u32_e32 v250, 0xfffff040, v52
	v_cndmask_b32_e64 v250, v52, v250, s[40:41]
	v_cndmask_b32_e64 v248, v58, v50, s[40:41]
	v_cndmask_b32_e64 v249, v59, v51, s[40:41]
	global_store_dwordx2 v250, v[248:249], s[18:19]
	v_cndmask_b32_e64 v246, v50, v58, s[40:41]
	v_cndmask_b32_e64 v247, v51, v59, s[40:41]
	v_mul_f32_e32 v19, v19, v19
	v_fmac_f32_e32 v19, v18, v18
	v_mul_f32_e32 v18, v21, v21
	v_mul_f32_e32 v29, v29, v29
	v_fmac_f32_e32 v18, v20, v20
	v_mul_f32_e32 v27, v27, v27
	v_fmac_f32_e32 v29, v28, v28
	v_mul_f32_e32 v28, v31, v31
	v_mul_f32_e32 v31, v33, v33
	v_add_f32_e32 v18, v19, v18
	v_mul_f32_e32 v19, v23, v23
	v_mul_f32_e32 v20, v25, v25
	v_fmac_f32_e32 v31, v32, v32
	v_fmac_f32_e32 v19, v22, v22
	v_fmac_f32_e32 v20, v24, v24
	v_fmac_f32_e32 v27, v26, v26
	v_fmac_f32_e32 v28, v30, v30
	v_add_f32_e32 v19, v19, v20
	v_add_f32_e32 v20, v27, v29
	v_add_f32_e32 v21, v28, v31
	v_add_f32_e32 v18, v20, v18
	v_add_f32_e32 v19, v21, v19
	ds_bpermute_b32 v20, v190, v18
	ds_bpermute_b32 v21, v190, v19
	s_waitcnt lgkmcnt(1)
	v_add_f32_e32 v18, v18, v20
	s_waitcnt lgkmcnt(0)
	v_add_f32_e32 v21, v19, v21
	ds_bpermute_b32 v20, v191, v18
	ds_bpermute_b32 v22, v191, v21
	s_waitcnt lgkmcnt(1)
	v_add_f32_e32 v18, v18, v20
	s_waitcnt lgkmcnt(0)
	v_add_f32_e32 v20, v21, v22
	ds_bpermute_b32 v19, v204, v18
	ds_bpermute_b32 v21, v204, v20
	v_add_u32_e32 v22, 0x1040, v52
	v_cndmask_b32_e64 v22, v52, v22, s[38:39]
	global_store_dwordx2 v22, v[246:247], s[18:19]
	s_and_saveexec_b64 s[22:23], s[42:43]
	s_cbranch_execz .LBB0_1999
	s_waitcnt lgkmcnt(1)
	v_add_f32_e32 v18, v18, v19
	s_waitcnt lgkmcnt(0)
	v_add_f32_e32 v19, v20, v21
	ds_write2_b32 v194, v18, v19 offset0:96 offset1:104
; #define LAS __attribute__((address_space(3)))
; #define ERN_EOFF(q, m) (eb + (unsigned)((((q) & 1) * HALF + (m) * 16) * DM + ERN_COL((q) >> 1)))
;     __device__ __forceinline__ void operator()(const f32x4 (&acc)[2][2][4][2], const Unit& u, int wr, int wc, int fr, int fq) const {
;     ...
;         ERN_LOADX(0);
; #pragma unroll
;         for (int g = 0; g < 8; ++g) { const int ai = g >> 2, m = g & 3;
;             if (g + 1 < 8) ERN_LOADX(g + 1);
;             float sq0 = 0.f, sq1 = 0.f; u32x2 hw[2][2];
; #pragma unroll
;             for (int bj = 0; bj < 2; ++bj) {
;                 *(LAS f32x4*)(st + wr_off) = acc[ai][bj][m][0]; *(LAS f32x4*)(st + wr_off + 64) = acc[ai][bj][m][1];
;                 const f32x4 a0 = *(const LAS f32x4*)(st + rd_off), a1 = *(const LAS f32x4*)(st + rd_off + 8 * 144);
;                 { const f32x4 xv = xb[g & 1][bj][0] + gv[bj] * a0; __builtin_nontemporal_store(xv, (f32x4*)((char*)xo + 4u * ERN_EOFF(g, bj, 0)));
;                   sq0 += (xv.x * xv.x + xv.y * xv.y) + (xv.z * xv.z + xv.w * xv.w);
;                   const f32x4 hv = xv * gsn[bj]; hw[bj][0].x = cvt_pk_bf16(hv.x, hv.y); hw[bj][0].y = cvt_pk_bf16(hv.z, hv.w); }
;                 { const f32x4 xv = xb[g & 1][bj][1] + gv[bj] * a1; __builtin_nontemporal_store(xv, (f32x4*)((char*)xo + 4u * ERN_EOFF(g, bj, 1)));
;                   sq1 += (xv.x * xv.x + xv.y * xv.y) + (xv.z * xv.z + xv.w * xv.w);
;                   const f32x4 hv = xv * gsn[bj]; hw[bj][1].x = cvt_pk_bf16(hv.x, hv.y); hw[bj][1].y = cvt_pk_bf16(hv.z, hv.w); }
;             }
;             if (!NOH && !PLAIN) {
; #pragma unroll
;                 for (int rh = 0; rh < 2; ++rh) { u32x2 rv; rv.x = __shfl_xor(hw[1][rh].x, 8); rv.y = __shfl_xor(hw[1][rh].y, 8);
;                     const unsigned e0 = ERN_EOFF(g, 0, rh);
;                     const unsigned ee = odd ? (e0 - DM + 32) : e0, eo2 = odd ? e0 : (e0 + DM + 32);
;                     *(u32x2*)((char*)ho + 2u * ee) = odd ? rv : hw[0][rh];
;                     *(u32x2*)((char*)ho + 2u * eo2) = odd ? hw[0][rh] : rv; }
;             }
;             if (!PLAIN) { sq0 += __shfl_xor(sq0, 1); sq0 += __shfl_xor(sq0, 2); sq0 += __shfl_xor(sq0, 4);
;             sq1 += __shfl_xor(sq1, 1); sq1 += __shfl_xor(sq1, 2); sq1 += __shfl_xor(sq1, 4); }
;             if (!PLAIN && pc == 0) { sst[g * 16 + rr] = sq0; sst[g * 16 + 8 + rr] = sq1; }
.LBB0_1999:
	s_or_b64 exec, exec, s[22:23]
	ds_write_b128 v200, v[14:17]
	ds_write_b128 v200, v[10:13] offset:64
	ds_read_b128 v[10:13], v201
	ds_read_b128 v[14:17], v201 offset:1152
	s_waitcnt lgkmcnt(5)
	v_lshl_add_u64 v[18:19], s[20:21], 0, v[154:155]
	v_mov_b32_e32 v71, v155
	v_lshl_add_u64 v[22:23], s[20:21], 0, v[70:71]
	s_waitcnt vmcnt(10) lgkmcnt(1)
	v_pk_fma_f32 v[12:13], v[176:177], v[12:13], v[48:49]
	v_pk_fma_f32 v[10:11], v[180:181], v[10:11], v[46:47]
	global_store_dwordx4 v[18:19], v[10:13], off nt
	v_pk_mul_f32 v[18:19], v[174:175], v[12:13]
	v_pk_mul_f32 v[20:21], v[178:179], v[10:11]
	s_waitcnt vmcnt(10) lgkmcnt(0)
	v_pk_fma_f32 v[14:15], v[180:181], v[14:15], v[42:43]
	v_cvt_pk_bf16_f32 v20, v20, v21
	v_cvt_pk_bf16_f32 v21, v18, v19
	v_pk_fma_f32 v[16:17], v[176:177], v[16:17], v[44:45]
	v_pk_mul_f32 v[18:19], v[178:179], v[14:15]
	global_store_dwordx4 v[22:23], v[14:17], off nt
	v_pk_mul_f32 v[22:23], v[174:175], v[16:17]
	v_cvt_pk_bf16_f32 v18, v18, v19
	v_mov_b32_e32 v69, v155
	v_cvt_pk_bf16_f32 v19, v22, v23
	ds_write_b128 v200, v[6:9]
	ds_write_b128 v200, v[2:5] offset:64
	ds_read_b128 v[2:5], v201
	ds_read_b128 v[6:9], v201 offset:1152
	v_lshl_add_u64 v[22:23], s[20:21], 0, v[68:69]
	v_mov_b32_e32 v67, v155
	v_lshl_add_u64 v[24:25], s[20:21], 0, v[66:67]
	s_waitcnt vmcnt(10) lgkmcnt(1)
	v_pk_fma_f32 v[4:5], v[166:167], v[4:5], v[40:41]
	v_pk_fma_f32 v[2:3], v[168:169], v[2:3], v[38:39]
	global_store_dwordx4 v[22:23], v[2:5], off nt
	v_pk_mul_f32 v[22:23], v[170:171], v[4:5]
	v_pk_mul_f32 v[26:27], v[172:173], v[2:3]
	s_waitcnt vmcnt(10) lgkmcnt(0)
	v_pk_fma_f32 v[8:9], v[166:167], v[8:9], v[36:37]
	v_cvt_pk_bf16_f32 v28, v26, v27
	v_cvt_pk_bf16_f32 v23, v22, v23
	ds_bpermute_b32 v22, v203, v28
	ds_bpermute_b32 v23, v203, v23
	v_pk_fma_f32 v[6:7], v[168:169], v[6:7], v[34:35]
	global_store_dwordx4 v[24:25], v[6:9], off nt
	v_pk_mul_f32 v[26:27], v[170:171], v[8:9]
	v_pk_mul_f32 v[24:25], v[172:173], v[6:7]
	s_nop 0
	v_cvt_pk_bf16_f32 v24, v24, v25
	v_cvt_pk_bf16_f32 v25, v26, v27
	v_add_u32_e32 v27, 0x58000, v202
	v_lshlrev_b32_e32 v26, 1, v27
	s_waitcnt lgkmcnt(0)
	v_add_u32_e32 v250, 0xfffff040, v26
	v_cndmask_b32_e64 v250, v26, v250, s[40:41]
	v_cndmask_b32_e64 v248, v20, v22, s[40:41]
	v_cndmask_b32_e64 v249, v21, v23, s[40:41]
	global_store_dwordx2 v250, v[248:249], s[18:19]
	v_cndmask_b32_e64 v246, v22, v20, s[40:41]
	v_cndmask_b32_e64 v247, v23, v21, s[40:41]
	s_waitcnt lgkmcnt(1)
	v_add_u32_e32 v22, 0x1040, v26
	v_cndmask_b32_e64 v22, v26, v22, s[38:39]
	global_store_dwordx2 v22, v[246:247], s[18:19]
	ds_bpermute_b32 v20, v203, v24
	ds_bpermute_b32 v21, v203, v25
	s_waitcnt lgkmcnt(2)
	v_add_u32_e32 v23, 0x5c000, v202
	v_lshlrev_b32_e32 v22, 1, v23
	s_waitcnt lgkmcnt(0)
	v_add_u32_e32 v250, 0xfffff040, v22
	v_cndmask_b32_e64 v250, v22, v250, s[40:41]
	v_cndmask_b32_e64 v248, v18, v20, s[40:41]
	v_cndmask_b32_e64 v249, v19, v21, s[40:41]
	global_store_dwordx2 v250, v[248:249], s[18:19]
	v_cndmask_b32_e64 v246, v20, v18, s[40:41]
	v_cndmask_b32_e64 v247, v21, v19, s[40:41]
	v_mul_f32_e32 v3, v3, v3
	v_fmac_f32_e32 v3, v2, v2
	v_mul_f32_e32 v2, v5, v5
	v_mul_f32_e32 v13, v13, v13
	v_fmac_f32_e32 v2, v4, v4
	v_mul_f32_e32 v11, v11, v11
	v_fmac_f32_e32 v13, v12, v12
	v_mul_f32_e32 v12, v15, v15
	v_mul_f32_e32 v15, v17, v17
	v_add_f32_e32 v2, v3, v2
	v_mul_f32_e32 v3, v7, v7
	v_mul_f32_e32 v4, v9, v9
	v_fmac_f32_e32 v15, v16, v16
	v_fmac_f32_e32 v3, v6, v6
	v_fmac_f32_e32 v4, v8, v8
	v_fmac_f32_e32 v11, v10, v10
	v_fmac_f32_e32 v12, v14, v14
	v_add_f32_e32 v3, v3, v4
	v_add_f32_e32 v4, v11, v13
	v_add_f32_e32 v5, v12, v15
	v_add_f32_e32 v2, v4, v2
	v_add_f32_e32 v3, v5, v3
	ds_bpermute_b32 v4, v190, v2
	ds_bpermute_b32 v5, v190, v3
	s_waitcnt lgkmcnt(1)
	v_add_f32_e32 v2, v2, v4
	s_waitcnt lgkmcnt(0)
	v_add_f32_e32 v5, v3, v5
	ds_bpermute_b32 v4, v191, v2
	ds_bpermute_b32 v6, v191, v5
	s_waitcnt lgkmcnt(1)
	v_add_f32_e32 v2, v2, v4
	s_waitcnt lgkmcnt(0)
	v_add_f32_e32 v4, v5, v6
	ds_bpermute_b32 v3, v204, v2
	ds_bpermute_b32 v5, v204, v4
	v_add_u32_e32 v6, 0x1040, v22
	v_cndmask_b32_e64 v6, v22, v6, s[38:39]
	global_store_dwordx2 v6, v[246:247], s[18:19]
	s_and_saveexec_b64 s[18:19], s[42:43]
	s_cbranch_execz .LBB0_2009
	s_waitcnt lgkmcnt(1)
	v_add_f32_e32 v2, v2, v3
	s_waitcnt lgkmcnt(0)
	v_add_f32_e32 v3, v4, v5
	ds_write2_b32 v194, v2, v3 offset0:112 offset1:120

; #define LAS __attribute__((address_space(3)))
; #define ERN_EOFF(q, m) (eb + (unsigned)((((q) & 1) * HALF + (m) * 16) * DM + ERN_COL((q) >> 1)))
;     __device__ __forceinline__ void operator()(const f32x4 (&acc)[2][2][4][2], const Unit& u, int wr, int wc, int fr, int fq) const {
;     ...
;         ERN_LOADX(0);
; #pragma unroll
;         for (int g = 0; g < 8; ++g) { const int ai = g >> 2, m = g & 3;
;             if (g + 1 < 8) ERN_LOADX(g + 1);
;             float sq0 = 0.f, sq1 = 0.f; u32x2 hw[2][2];
; #pragma unroll
;             for (int bj = 0; bj < 2; ++bj) {
;                 *(LAS f32x4*)(st + wr_off) = acc[ai][bj][m][0]; *(LAS f32x4*)(st + wr_off + 64) = acc[ai][bj][m][1];
;                 const f32x4 a0 = *(const LAS f32x4*)(st + rd_off), a1 = *(const LAS f32x4*)(st + rd_off + 8 * 144);
;                 { const f32x4 xv = xb[g & 1][bj][0] + gv[bj] * a0; __builtin_nontemporal_store(xv, (f32x4*)((char*)xo + 4u * ERN_EOFF(g, bj, 0)));
;                   sq0 += (xv.x * xv.x + xv.y * xv.y) + (xv.z * xv.z + xv.w * xv.w);
;                   const f32x4 hv = xv * gsn[bj]; hw[bj][0].x = cvt_pk_bf16(hv.x, hv.y); hw[bj][0].y = cvt_pk_bf16(hv.z, hv.w); }
;                 { const f32x4 xv = xb[g & 1][bj][1] + gv[bj] * a1; __builtin_nontemporal_store(xv, (f32x4*)((char*)xo + 4u * ERN_EOFF(g, bj, 1)));
;                   sq1 += (xv.x * xv.x + xv.y * xv.y) + (xv.z * xv.z + xv.w * xv.w);
;                   const f32x4 hv = xv * gsn[bj]; hw[bj][1].x = cvt_pk_bf16(hv.x, hv.y); hw[bj][1].y = cvt_pk_bf16(hv.z, hv.w); }
;             }
;             if (!NOH && !PLAIN) {
; #pragma unroll
;                 for (int rh = 0; rh < 2; ++rh) { u32x2 rv; rv.x = __shfl_xor(hw[1][rh].x, 8); rv.y = __shfl_xor(hw[1][rh].y, 8);
;                     const unsigned e0 = ERN_EOFF(g, 0, rh);
;                     const unsigned ee = odd ? (e0 - DM + 32) : e0, eo2 = odd ? e0 : (e0 + DM + 32);
;                     *(u32x2*)((char*)ho + 2u * ee) = odd ? rv : hw[0][rh];
;                     *(u32x2*)((char*)ho + 2u * eo2) = odd ? hw[0][rh] : rv; }
;             }
;             if (!PLAIN) { sq0 += __shfl_xor(sq0, 1); sq0 += __shfl_xor(sq0, 2); sq0 += __shfl_xor(sq0, 4);
;             sq1 += __shfl_xor(sq1, 1); sq1 += __shfl_xor(sq1, 2); sq1 += __shfl_xor(sq1, 4); }
;             if (!PLAIN && pc == 0) { sst[g * 16 + rr] = sq0; sst[g * 16 + 8 + rr] = sq1; }
.LBB0_2789:
	s_or_b64 exec, exec, s[24:25]
	v_lshl_add_u64 v[142:143], s[22:23], 0, v[162:163]
	v_add_u32_e32 v106, 0x60000, v205
	v_add_u32_e32 v162, 0x70000, v205
	v_add_u32_e32 v138, 0x60080, v205
	global_load_dwordx4 v[114:117], v162, s[22:23]
	global_load_dwordx4 v[110:113], v138, s[22:23]
	v_add_u32_e32 v140, 0x70080, v205
	global_load_dwordx4 v[118:121], v106, s[22:23]
	s_waitcnt lgkmcnt(0)
	global_load_dwordx4 v[106:109], v140, s[22:23]
	ds_write_b128 v200, v[102:105]
	ds_write_b128 v200, v[98:101] offset:64
	ds_read_b128 v[98:101], v201
	ds_read_b128 v[102:105], v201 offset:1152
	v_mov_b32_e32 v187, v163
	v_mov_b32_e32 v189, v163
	s_waitcnt vmcnt(12) lgkmcnt(1)
	v_pk_fma_f32 v[100:101], v[56:57], v[100:101], v[136:137]
	v_add_u32_e32 v136, 0x10000, v202
	v_pk_fma_f32 v[98:99], v[54:55], v[98:99], v[134:135]
	v_lshlrev_b32_e32 v134, 2, v136
	s_waitcnt lgkmcnt(0)
	v_pk_fma_f32 v[102:103], v[54:55], v[102:103], v[130:131]
	global_store_dwordx4 v134, v[98:101], s[22:23] nt
	v_pk_mul_f32 v[134:135], v[180:181], v[98:99]
	v_pk_fma_f32 v[104:105], v[56:57], v[104:105], v[132:133]
	v_pk_mul_f32 v[130:131], v[180:181], v[102:103]
	v_pk_mul_f32 v[144:145], v[178:179], v[100:101]
	v_cvt_pk_bf16_f32 v134, v134, v135
	v_pk_mul_f32 v[132:133], v[178:179], v[104:105]
	v_cvt_pk_bf16_f32 v135, v144, v145
	global_store_dwordx4 v[142:143], v[102:105], off nt
	v_cvt_pk_bf16_f32 v130, v130, v131
	v_cvt_pk_bf16_f32 v131, v132, v133
	ds_write_b128 v200, v[94:97]
	ds_write_b128 v200, v[90:93] offset:64
	ds_read_b128 v[90:93], v201
	ds_read_b128 v[94:97], v201 offset:1152
	v_lshl_add_u64 v[132:133], s[22:23], 0, v[186:187]
	v_lshl_add_u64 v[142:143], s[22:23], 0, v[188:189]
	s_waitcnt lgkmcnt(1)
	v_pk_fma_f32 v[90:91], v[50:51], v[90:91], v[126:127]
	v_pk_fma_f32 v[92:93], v[52:53], v[92:93], v[128:129]
	v_pk_mul_f32 v[128:129], v[176:177], v[90:91]
	global_store_dwordx4 v[132:133], v[90:93], off nt
	v_pk_mul_f32 v[126:127], v[174:175], v[92:93]
	v_cvt_pk_bf16_f32 v128, v128, v129
	s_waitcnt vmcnt(14) lgkmcnt(0)
	v_pk_fma_f32 v[94:95], v[50:51], v[94:95], v[122:123]
	v_cvt_pk_bf16_f32 v129, v126, v127
	ds_bpermute_b32 v122, v203, v128
	ds_bpermute_b32 v123, v203, v129
	v_pk_fma_f32 v[96:97], v[52:53], v[96:97], v[124:125]
	v_pk_mul_f32 v[124:125], v[176:177], v[94:95]
	v_pk_mul_f32 v[126:127], v[174:175], v[96:97]
	global_store_dwordx4 v[142:143], v[94:97], off nt
	v_cvt_pk_bf16_f32 v124, v124, v125
	v_cvt_pk_bf16_f32 v125, v126, v127
	v_lshlrev_b32_e32 v126, 1, v136
	s_waitcnt lgkmcnt(0)
	v_add_u32_e32 v250, 0xfffff040, v126
	v_cndmask_b32_e64 v250, v126, v250, s[38:39]
	v_cndmask_b32_e64 v248, v134, v122, s[38:39]
	v_cndmask_b32_e64 v249, v135, v123, s[38:39]
	global_store_dwordx2 v250, v[248:249], s[20:21]
	v_cndmask_b32_e64 v246, v122, v134, s[38:39]
	v_cndmask_b32_e64 v247, v123, v135, s[38:39]
	s_waitcnt lgkmcnt(1)
	v_add_u32_e32 v122, 0x1040, v126
	v_cndmask_b32_e64 v122, v126, v122, s[36:37]
	global_store_dwordx2 v122, v[246:247], s[20:21]
	ds_bpermute_b32 v122, v203, v124
	s_waitcnt lgkmcnt(1)
	ds_bpermute_b32 v123, v203, v125
	v_add_u32_e32 v125, 0x14000, v202
	v_lshlrev_b32_e32 v124, 1, v125
	s_waitcnt lgkmcnt(0)
	v_add_u32_e32 v250, 0xfffff040, v124
	v_cndmask_b32_e64 v250, v124, v250, s[38:39]
	v_cndmask_b32_e64 v248, v130, v122, s[38:39]
	v_cndmask_b32_e64 v249, v131, v123, s[38:39]
	global_store_dwordx2 v250, v[248:249], s[20:21]
	v_cndmask_b32_e64 v246, v122, v130, s[38:39]
	v_cndmask_b32_e64 v247, v123, v131, s[38:39]
	v_mul_f32_e32 v91, v91, v91
	v_fmac_f32_e32 v91, v90, v90
	v_mul_f32_e32 v90, v93, v93
	v_mul_f32_e32 v101, v101, v101
	v_fmac_f32_e32 v90, v92, v92
	v_mul_f32_e32 v99, v99, v99
	v_fmac_f32_e32 v101, v100, v100
	v_mul_f32_e32 v100, v103, v103
	v_mul_f32_e32 v103, v105, v105
	v_add_f32_e32 v90, v91, v90
	v_mul_f32_e32 v91, v95, v95
	v_mul_f32_e32 v92, v97, v97
	v_fmac_f32_e32 v103, v104, v104
	v_fmac_f32_e32 v91, v94, v94
	v_fmac_f32_e32 v92, v96, v96
	v_fmac_f32_e32 v99, v98, v98
	v_fmac_f32_e32 v100, v102, v102
	v_add_f32_e32 v91, v91, v92
	v_add_f32_e32 v92, v99, v101
	v_add_f32_e32 v93, v100, v103
	v_add_f32_e32 v90, v92, v90
	v_add_f32_e32 v91, v93, v91
	ds_bpermute_b32 v92, v190, v90
	ds_bpermute_b32 v93, v190, v91
	s_waitcnt lgkmcnt(1)
	v_add_f32_e32 v90, v90, v92
	s_waitcnt lgkmcnt(0)
	v_add_f32_e32 v93, v91, v93
	ds_bpermute_b32 v92, v191, v90
	ds_bpermute_b32 v94, v191, v93
	s_waitcnt lgkmcnt(1)
	v_add_f32_e32 v90, v90, v92
	s_waitcnt lgkmcnt(0)
	v_add_f32_e32 v92, v93, v94
	ds_bpermute_b32 v91, v204, v90
	ds_bpermute_b32 v93, v204, v92
	v_add_u32_e32 v94, 0x1040, v124
	v_cndmask_b32_e64 v94, v124, v94, s[36:37]
	global_store_dwordx2 v94, v[246:247], s[20:21]
	s_and_saveexec_b64 s[24:25], s[40:41]
	s_cbranch_execz .LBB0_2799
	s_waitcnt lgkmcnt(1)
	v_add_f32_e32 v90, v90, v91
	s_waitcnt lgkmcnt(0)
	v_add_f32_e32 v91, v92, v93
	ds_write2_b32 v194, v90, v91 offset0:32 offset1:40
; #define LAS __attribute__((address_space(3)))
; #define ERN_EOFF(q, m) (eb + (unsigned)((((q) & 1) * HALF + (m) * 16) * DM + ERN_COL((q) >> 1)))
;     __device__ __forceinline__ void operator()(const f32x4 (&acc)[2][2][4][2], const Unit& u, int wr, int wc, int fr, int fq) const {
;     ...
;         ERN_LOADX(0);
; #pragma unroll
;         for (int g = 0; g < 8; ++g) { const int ai = g >> 2, m = g & 3;
;             if (g + 1 < 8) ERN_LOADX(g + 1);
;             float sq0 = 0.f, sq1 = 0.f; u32x2 hw[2][2];
; #pragma unroll
;             for (int bj = 0; bj < 2; ++bj) {
;                 *(LAS f32x4*)(st + wr_off) = acc[ai][bj][m][0]; *(LAS f32x4*)(st + wr_off + 64) = acc[ai][bj][m][1];
;                 const f32x4 a0 = *(const LAS f32x4*)(st + rd_off), a1 = *(const LAS f32x4*)(st + rd_off + 8 * 144);
;                 { const f32x4 xv = xb[g & 1][bj][0] + gv[bj] * a0; __builtin_nontemporal_store(xv, (f32x4*)((char*)xo + 4u * ERN_EOFF(g, bj, 0)));
;                   sq0 += (xv.x * xv.x + xv.y * xv.y) + (xv.z * xv.z + xv.w * xv.w);
;                   const f32x4 hv = xv * gsn[bj]; hw[bj][0].x = cvt_pk_bf16(hv.x, hv.y); hw[bj][0].y = cvt_pk_bf16(hv.z, hv.w); }
;                 { const f32x4 xv = xb[g & 1][bj][1] + gv[bj] * a1; __builtin_nontemporal_store(xv, (f32x4*)((char*)xo + 4u * ERN_EOFF(g, bj, 1)));
;                   sq1 += (xv.x * xv.x + xv.y * xv.y) + (xv.z * xv.z + xv.w * xv.w);
;                   const f32x4 hv = xv * gsn[bj]; hw[bj][1].x = cvt_pk_bf16(hv.x, hv.y); hw[bj][1].y = cvt_pk_bf16(hv.z, hv.w); }
;             }
;             if (!NOH && !PLAIN) {
; #pragma unroll
;                 for (int rh = 0; rh < 2; ++rh) { u32x2 rv; rv.x = __shfl_xor(hw[1][rh].x, 8); rv.y = __shfl_xor(hw[1][rh].y, 8);
;                     const unsigned e0 = ERN_EOFF(g, 0, rh);
;                     const unsigned ee = odd ? (e0 - DM + 32) : e0, eo2 = odd ? e0 : (e0 + DM + 32);
;                     *(u32x2*)((char*)ho + 2u * ee) = odd ? rv : hw[0][rh];
;                     *(u32x2*)((char*)ho + 2u * eo2) = odd ? hw[0][rh] : rv; }
;             }
;             if (!PLAIN) { sq0 += __shfl_xor(sq0, 1); sq0 += __shfl_xor(sq0, 2); sq0 += __shfl_xor(sq0, 4);
;             sq1 += __shfl_xor(sq1, 1); sq1 += __shfl_xor(sq1, 2); sq1 += __shfl_xor(sq1, 4); }
;             if (!PLAIN && pc == 0) { sst[g * 16 + rr] = sq0; sst[g * 16 + 8 + rr] = sq1; }
.LBB0_2799:
	s_or_b64 exec, exec, s[24:25]
	v_lshl_add_u64 v[124:125], s[22:23], 0, v[162:163]
	v_add_u32_e32 v90, 0x100000, v205
	s_waitcnt lgkmcnt(1)
	v_add_u32_e32 v91, 0x110000, v205
	v_add_u32_e32 v162, 0x100080, v205
	global_load_dwordx4 v[102:105], v90, s[22:23]
	global_load_dwordx4 v[98:101], v91, s[22:23]
	v_add_u32_e32 v122, 0x110080, v205
	global_load_dwordx4 v[94:97], v162, s[22:23]
	s_waitcnt lgkmcnt(0)
	global_load_dwordx4 v[90:93], v122, s[22:23]
	ds_write_b128 v200, v[86:89]
	ds_write_b128 v200, v[82:85] offset:64
	ds_read_b128 v[82:85], v201
	ds_read_b128 v[86:89], v201 offset:1152
	v_mov_b32_e32 v139, v163
	v_mov_b32_e32 v141, v163
	s_waitcnt vmcnt(12) lgkmcnt(1)
	v_pk_fma_f32 v[84:85], v[56:57], v[84:85], v[120:121]
	v_add_u32_e32 v120, 0x18000, v202
	v_pk_fma_f32 v[82:83], v[54:55], v[82:83], v[118:119]
	v_lshlrev_b32_e32 v118, 2, v120
	s_waitcnt lgkmcnt(0)
	v_pk_fma_f32 v[86:87], v[54:55], v[86:87], v[114:115]
	global_store_dwordx4 v118, v[82:85], s[22:23] nt
	v_pk_mul_f32 v[118:119], v[180:181], v[82:83]
	v_pk_fma_f32 v[88:89], v[56:57], v[88:89], v[116:117]
	v_pk_mul_f32 v[114:115], v[180:181], v[86:87]
	v_pk_mul_f32 v[126:127], v[178:179], v[84:85]
	v_cvt_pk_bf16_f32 v118, v118, v119
	v_pk_mul_f32 v[116:117], v[178:179], v[88:89]
	v_cvt_pk_bf16_f32 v119, v126, v127
	global_store_dwordx4 v[124:125], v[86:89], off nt
	v_cvt_pk_bf16_f32 v114, v114, v115
	v_cvt_pk_bf16_f32 v115, v116, v117
	ds_write_b128 v200, v[78:81]
	ds_write_b128 v200, v[74:77] offset:64
	ds_read_b128 v[74:77], v201
	ds_read_b128 v[78:81], v201 offset:1152
	v_lshl_add_u64 v[116:117], s[22:23], 0, v[138:139]
	v_lshl_add_u64 v[124:125], s[22:23], 0, v[140:141]
	s_waitcnt lgkmcnt(1)
	v_pk_fma_f32 v[74:75], v[50:51], v[74:75], v[110:111]
	v_pk_fma_f32 v[76:77], v[52:53], v[76:77], v[112:113]
	v_pk_mul_f32 v[112:113], v[176:177], v[74:75]
	global_store_dwordx4 v[116:117], v[74:77], off nt
	v_pk_mul_f32 v[110:111], v[174:175], v[76:77]
	v_cvt_pk_bf16_f32 v112, v112, v113
	s_waitcnt vmcnt(14) lgkmcnt(0)
	v_pk_fma_f32 v[78:79], v[50:51], v[78:79], v[106:107]
	v_cvt_pk_bf16_f32 v113, v110, v111
	ds_bpermute_b32 v106, v203, v112
	ds_bpermute_b32 v107, v203, v113
	v_pk_fma_f32 v[80:81], v[52:53], v[80:81], v[108:109]
	v_pk_mul_f32 v[108:109], v[176:177], v[78:79]
	v_pk_mul_f32 v[110:111], v[174:175], v[80:81]
	global_store_dwordx4 v[124:125], v[78:81], off nt
	v_cvt_pk_bf16_f32 v108, v108, v109
	v_cvt_pk_bf16_f32 v109, v110, v111
	v_lshlrev_b32_e32 v110, 1, v120
	s_waitcnt lgkmcnt(0)
	v_add_u32_e32 v250, 0xfffff040, v110
	v_cndmask_b32_e64 v250, v110, v250, s[38:39]
	v_cndmask_b32_e64 v248, v118, v106, s[38:39]
	v_cndmask_b32_e64 v249, v119, v107, s[38:39]
	global_store_dwordx2 v250, v[248:249], s[20:21]
	v_cndmask_b32_e64 v246, v106, v118, s[38:39]
	v_cndmask_b32_e64 v247, v107, v119, s[38:39]
	s_waitcnt lgkmcnt(1)
	v_add_u32_e32 v106, 0x1040, v110
	v_cndmask_b32_e64 v106, v110, v106, s[36:37]
	global_store_dwordx2 v106, v[246:247], s[20:21]
	ds_bpermute_b32 v106, v203, v108
	s_waitcnt lgkmcnt(1)
	ds_bpermute_b32 v107, v203, v109
	v_add_u32_e32 v109, 0x1c000, v202
	v_lshlrev_b32_e32 v108, 1, v109
	s_waitcnt lgkmcnt(0)
	v_add_u32_e32 v250, 0xfffff040, v108
	v_cndmask_b32_e64 v250, v108, v250, s[38:39]
	v_cndmask_b32_e64 v248, v114, v106, s[38:39]
	v_cndmask_b32_e64 v249, v115, v107, s[38:39]
	global_store_dwordx2 v250, v[248:249], s[20:21]
	v_cndmask_b32_e64 v246, v106, v114, s[38:39]
	v_cndmask_b32_e64 v247, v107, v115, s[38:39]
	v_mul_f32_e32 v75, v75, v75
	v_fmac_f32_e32 v75, v74, v74
	v_mul_f32_e32 v74, v77, v77
	v_mul_f32_e32 v85, v85, v85
	v_fmac_f32_e32 v74, v76, v76
	v_mul_f32_e32 v83, v83, v83
	v_fmac_f32_e32 v85, v84, v84
	v_mul_f32_e32 v84, v87, v87
	v_mul_f32_e32 v87, v89, v89
	v_add_f32_e32 v74, v75, v74
	v_mul_f32_e32 v75, v79, v79
	v_mul_f32_e32 v76, v81, v81
	v_fmac_f32_e32 v87, v88, v88
	v_fmac_f32_e32 v75, v78, v78
	v_fmac_f32_e32 v76, v80, v80
	v_fmac_f32_e32 v83, v82, v82
	v_fmac_f32_e32 v84, v86, v86
	v_add_f32_e32 v75, v75, v76
	v_add_f32_e32 v76, v83, v85
	v_add_f32_e32 v77, v84, v87
	v_add_f32_e32 v74, v76, v74
	v_add_f32_e32 v75, v77, v75
	ds_bpermute_b32 v76, v190, v74
	ds_bpermute_b32 v77, v190, v75
	s_waitcnt lgkmcnt(1)
	v_add_f32_e32 v74, v74, v76
	s_waitcnt lgkmcnt(0)
	v_add_f32_e32 v77, v75, v77
	ds_bpermute_b32 v76, v191, v74
	ds_bpermute_b32 v78, v191, v77
	s_waitcnt lgkmcnt(1)
	v_add_f32_e32 v74, v74, v76
	s_waitcnt lgkmcnt(0)
	v_add_f32_e32 v76, v77, v78
	ds_bpermute_b32 v75, v204, v74
	ds_bpermute_b32 v77, v204, v76
	v_add_u32_e32 v78, 0x1040, v108
	v_cndmask_b32_e64 v78, v108, v78, s[36:37]
	global_store_dwordx2 v78, v[246:247], s[20:21]
	s_and_saveexec_b64 s[24:25], s[40:41]
	s_cbranch_execz .LBB0_2809
	s_waitcnt lgkmcnt(1)
	v_add_f32_e32 v74, v74, v75
	s_waitcnt lgkmcnt(0)
	v_add_f32_e32 v75, v76, v77
	ds_write2_b32 v194, v74, v75 offset0:48 offset1:56
; #define LAS __attribute__((address_space(3)))
; #define ERN_EOFF(q, m) (eb + (unsigned)((((q) & 1) * HALF + (m) * 16) * DM + ERN_COL((q) >> 1)))
;     __device__ __forceinline__ void operator()(const f32x4 (&acc)[2][2][4][2], const Unit& u, int wr, int wc, int fr, int fq) const {
;     ...
;         ERN_LOADX(0);
; #pragma unroll
;         for (int g = 0; g < 8; ++g) { const int ai = g >> 2, m = g & 3;
;             if (g + 1 < 8) ERN_LOADX(g + 1);
;             float sq0 = 0.f, sq1 = 0.f; u32x2 hw[2][2];
; #pragma unroll
;             for (int bj = 0; bj < 2; ++bj) {
;                 *(LAS f32x4*)(st + wr_off) = acc[ai][bj][m][0]; *(LAS f32x4*)(st + wr_off + 64) = acc[ai][bj][m][1];
;                 const f32x4 a0 = *(const LAS f32x4*)(st + rd_off), a1 = *(const LAS f32x4*)(st + rd_off + 8 * 144);
;                 { const f32x4 xv = xb[g & 1][bj][0] + gv[bj] * a0; __builtin_nontemporal_store(xv, (f32x4*)((char*)xo + 4u * ERN_EOFF(g, bj, 0)));
;                   sq0 += (xv.x * xv.x + xv.y * xv.y) + (xv.z * xv.z + xv.w * xv.w);
;                   const f32x4 hv = xv * gsn[bj]; hw[bj][0].x = cvt_pk_bf16(hv.x, hv.y); hw[bj][0].y = cvt_pk_bf16(hv.z, hv.w); }
;                 { const f32x4 xv = xb[g & 1][bj][1] + gv[bj] * a1; __builtin_nontemporal_store(xv, (f32x4*)((char*)xo + 4u * ERN_EOFF(g, bj, 1)));
;                   sq1 += (xv.x * xv.x + xv.y * xv.y) + (xv.z * xv.z + xv.w * xv.w);
;                   const f32x4 hv = xv * gsn[bj]; hw[bj][1].x = cvt_pk_bf16(hv.x, hv.y); hw[bj][1].y = cvt_pk_bf16(hv.z, hv.w); }
;             }
;             if (!NOH && !PLAIN) {
; #pragma unroll
;                 for (int rh = 0; rh < 2; ++rh) { u32x2 rv; rv.x = __shfl_xor(hw[1][rh].x, 8); rv.y = __shfl_xor(hw[1][rh].y, 8);
;                     const unsigned e0 = ERN_EOFF(g, 0, rh);
;                     const unsigned ee = odd ? (e0 - DM + 32) : e0, eo2 = odd ? e0 : (e0 + DM + 32);
;                     *(u32x2*)((char*)ho + 2u * ee) = odd ? rv : hw[0][rh];
;                     *(u32x2*)((char*)ho + 2u * eo2) = odd ? hw[0][rh] : rv; }
;             }
;             if (!PLAIN) { sq0 += __shfl_xor(sq0, 1); sq0 += __shfl_xor(sq0, 2); sq0 += __shfl_xor(sq0, 4);
;             sq1 += __shfl_xor(sq1, 1); sq1 += __shfl_xor(sq1, 2); sq1 += __shfl_xor(sq1, 4); }
;             if (!PLAIN && pc == 0) { sst[g * 16 + rr] = sq0; sst[g * 16 + 8 + rr] = sq1; }
.LBB0_2809:
	s_or_b64 exec, exec, s[24:25]
	v_lshl_add_u64 v[112:113], s[22:23], 0, v[162:163]
	v_add_u32_e32 v162, 0x120000, v205
	v_add_u32_e32 v108, 0x120080, v205
	v_add_u32_e32 v110, 0x130000, v205
	global_load_dwordx4 v[86:89], v162, s[22:23]
	global_load_dwordx4 v[82:85], v110, s[22:23]
	v_add_u32_e32 v106, 0x130080, v205
	global_load_dwordx4 v[78:81], v108, s[22:23]
	s_waitcnt lgkmcnt(0)
	global_load_dwordx4 v[74:77], v106, s[22:23]
	ds_write_b128 v200, v[70:73]
	ds_write_b128 v200, v[66:69] offset:64
	ds_read_b128 v[66:69], v201
	ds_read_b128 v[70:73], v201 offset:1152
	v_mov_b32_e32 v123, v163
	s_waitcnt vmcnt(14) lgkmcnt(1)
	v_pk_fma_f32 v[68:69], v[56:57], v[68:69], v[104:105]
	v_add_u32_e32 v104, 0x40000, v202
	v_pk_fma_f32 v[66:67], v[54:55], v[66:67], v[102:103]
	v_lshlrev_b32_e32 v102, 2, v104
	s_waitcnt vmcnt(13) lgkmcnt(0)
	v_pk_fma_f32 v[72:73], v[56:57], v[72:73], v[100:101]
	v_add_u32_e32 v100, 0x44000, v202
	global_store_dwordx4 v102, v[66:69], s[22:23] nt
	v_pk_mul_f32 v[102:103], v[180:181], v[66:67]
	v_pk_fma_f32 v[70:71], v[54:55], v[70:71], v[98:99]
	v_lshlrev_b32_e32 v98, 2, v100
	v_pk_mul_f32 v[114:115], v[178:179], v[68:69]
	v_cvt_pk_bf16_f32 v102, v102, v103
	s_nop 0
	v_cvt_pk_bf16_f32 v103, v114, v115
	global_store_dwordx4 v98, v[70:73], s[22:23] nt
	v_pk_mul_f32 v[98:99], v[180:181], v[70:71]
	v_pk_mul_f32 v[114:115], v[178:179], v[72:73]
	v_cvt_pk_bf16_f32 v98, v98, v99
	s_nop 0
	v_cvt_pk_bf16_f32 v99, v114, v115
	ds_write_b128 v200, v[62:65]
	ds_write_b128 v200, v[58:61] offset:64
	ds_read_b128 v[58:61], v201
	ds_read_b128 v[62:65], v201 offset:1152
	v_lshl_add_u64 v[114:115], s[22:23], 0, v[122:123]
	s_waitcnt vmcnt(14) lgkmcnt(1)
	v_pk_fma_f32 v[58:59], v[50:51], v[58:59], v[94:95]
	v_pk_fma_f32 v[60:61], v[52:53], v[60:61], v[96:97]
	v_pk_mul_f32 v[96:97], v[176:177], v[58:59]
	global_store_dwordx4 v[112:113], v[58:61], off nt
	v_pk_mul_f32 v[94:95], v[174:175], v[60:61]
	v_cvt_pk_bf16_f32 v96, v96, v97
	s_waitcnt vmcnt(14) lgkmcnt(0)
	v_pk_fma_f32 v[62:63], v[50:51], v[62:63], v[90:91]
	v_cvt_pk_bf16_f32 v97, v94, v95
	ds_bpermute_b32 v90, v203, v96
	ds_bpermute_b32 v91, v203, v97
	v_pk_fma_f32 v[64:65], v[52:53], v[64:65], v[92:93]
	v_pk_mul_f32 v[92:93], v[176:177], v[62:63]
	v_pk_mul_f32 v[94:95], v[174:175], v[64:65]
	global_store_dwordx4 v[114:115], v[62:65], off nt
	v_cvt_pk_bf16_f32 v92, v92, v93
	v_cvt_pk_bf16_f32 v93, v94, v95
	v_lshlrev_b32_e32 v94, 1, v104
	s_waitcnt lgkmcnt(0)
	v_add_u32_e32 v250, 0xfffff040, v94
	v_cndmask_b32_e64 v250, v94, v250, s[38:39]
	v_cndmask_b32_e64 v248, v102, v90, s[38:39]
	v_cndmask_b32_e64 v249, v103, v91, s[38:39]
	global_store_dwordx2 v250, v[248:249], s[20:21]
	v_cndmask_b32_e64 v246, v90, v102, s[38:39]
	v_cndmask_b32_e64 v247, v91, v103, s[38:39]
	s_waitcnt lgkmcnt(1)
	v_add_u32_e32 v90, 0x1040, v94
	v_cndmask_b32_e64 v90, v94, v90, s[36:37]
	global_store_dwordx2 v90, v[246:247], s[20:21]
	ds_bpermute_b32 v90, v203, v92
	s_waitcnt lgkmcnt(1)
	ds_bpermute_b32 v91, v203, v93
	v_lshlrev_b32_e32 v92, 1, v100
	s_waitcnt lgkmcnt(0)
	v_add_u32_e32 v250, 0xfffff040, v92
	v_cndmask_b32_e64 v250, v92, v250, s[38:39]
	v_cndmask_b32_e64 v248, v98, v90, s[38:39]
	v_cndmask_b32_e64 v249, v99, v91, s[38:39]
	global_store_dwordx2 v250, v[248:249], s[20:21]
	v_cndmask_b32_e64 v246, v90, v98, s[38:39]
	v_cndmask_b32_e64 v247, v91, v99, s[38:39]
	v_mul_f32_e32 v59, v59, v59
	v_fmac_f32_e32 v59, v58, v58
	v_mul_f32_e32 v58, v61, v61
	v_mul_f32_e32 v69, v69, v69
	v_fmac_f32_e32 v58, v60, v60
	v_mul_f32_e32 v67, v67, v67
	v_fmac_f32_e32 v69, v68, v68
	v_mul_f32_e32 v68, v71, v71
	v_mul_f32_e32 v71, v73, v73
	v_add_f32_e32 v58, v59, v58
	v_mul_f32_e32 v59, v63, v63
	v_mul_f32_e32 v60, v65, v65
	v_fmac_f32_e32 v71, v72, v72
	v_fmac_f32_e32 v59, v62, v62
	v_fmac_f32_e32 v60, v64, v64
	v_fmac_f32_e32 v67, v66, v66
	v_fmac_f32_e32 v68, v70, v70
	v_add_f32_e32 v59, v59, v60
	v_add_f32_e32 v60, v67, v69
	v_add_f32_e32 v61, v68, v71
	v_add_f32_e32 v58, v60, v58
	v_add_f32_e32 v59, v61, v59
	ds_bpermute_b32 v60, v190, v58
	ds_bpermute_b32 v61, v190, v59
	s_waitcnt lgkmcnt(1)
	v_add_f32_e32 v58, v58, v60
	s_waitcnt lgkmcnt(0)
	v_add_f32_e32 v61, v59, v61
	ds_bpermute_b32 v60, v191, v58
	ds_bpermute_b32 v62, v191, v61
	s_waitcnt lgkmcnt(1)
	v_add_f32_e32 v58, v58, v60
	s_waitcnt lgkmcnt(0)
	v_add_f32_e32 v60, v61, v62
	ds_bpermute_b32 v59, v204, v58
	ds_bpermute_b32 v61, v204, v60
	v_add_u32_e32 v62, 0x1040, v92
	v_cndmask_b32_e64 v62, v92, v62, s[36:37]
	global_store_dwordx2 v62, v[246:247], s[20:21]
	s_and_saveexec_b64 s[24:25], s[40:41]
	s_cbranch_execz .LBB0_2819
	s_waitcnt lgkmcnt(1)
	v_add_f32_e32 v58, v58, v59
	s_waitcnt lgkmcnt(0)
	v_add_f32_e32 v59, v60, v61
	ds_write2_b32 v194, v58, v59 offset0:64 offset1:72
; #define LAS __attribute__((address_space(3)))
; #define ERN_EOFF(q, m) (eb + (unsigned)((((q) & 1) * HALF + (m) * 16) * DM + ERN_COL((q) >> 1)))
;     __device__ __forceinline__ void operator()(const f32x4 (&acc)[2][2][4][2], const Unit& u, int wr, int wc, int fr, int fq) const {
;     ...
;         ERN_LOADX(0);
; #pragma unroll
;         for (int g = 0; g < 8; ++g) { const int ai = g >> 2, m = g & 3;
;             if (g + 1 < 8) ERN_LOADX(g + 1);
;             float sq0 = 0.f, sq1 = 0.f; u32x2 hw[2][2];
; #pragma unroll
;             for (int bj = 0; bj < 2; ++bj) {
;                 *(LAS f32x4*)(st + wr_off) = acc[ai][bj][m][0]; *(LAS f32x4*)(st + wr_off + 64) = acc[ai][bj][m][1];
;                 const f32x4 a0 = *(const LAS f32x4*)(st + rd_off), a1 = *(const LAS f32x4*)(st + rd_off + 8 * 144);
;                 { const f32x4 xv = xb[g & 1][bj][0] + gv[bj] * a0; __builtin_nontemporal_store(xv, (f32x4*)((char*)xo + 4u * ERN_EOFF(g, bj, 0)));
;                   sq0 += (xv.x * xv.x + xv.y * xv.y) + (xv.z * xv.z + xv.w * xv.w);
;                   const f32x4 hv = xv * gsn[bj]; hw[bj][0].x = cvt_pk_bf16(hv.x, hv.y); hw[bj][0].y = cvt_pk_bf16(hv.z, hv.w); }
;                 { const f32x4 xv = xb[g & 1][bj][1] + gv[bj] * a1; __builtin_nontemporal_store(xv, (f32x4*)((char*)xo + 4u * ERN_EOFF(g, bj, 1)));
;                   sq1 += (xv.x * xv.x + xv.y * xv.y) + (xv.z * xv.z + xv.w * xv.w);
;                   const f32x4 hv = xv * gsn[bj]; hw[bj][1].x = cvt_pk_bf16(hv.x, hv.y); hw[bj][1].y = cvt_pk_bf16(hv.z, hv.w); }
;             }
;             if (!NOH && !PLAIN) {
; #pragma unroll
;                 for (int rh = 0; rh < 2; ++rh) { u32x2 rv; rv.x = __shfl_xor(hw[1][rh].x, 8); rv.y = __shfl_xor(hw[1][rh].y, 8);
;                     const unsigned e0 = ERN_EOFF(g, 0, rh);
;                     const unsigned ee = odd ? (e0 - DM + 32) : e0, eo2 = odd ? e0 : (e0 + DM + 32);
;                     *(u32x2*)((char*)ho + 2u * ee) = odd ? rv : hw[0][rh];
;                     *(u32x2*)((char*)ho + 2u * eo2) = odd ? hw[0][rh] : rv; }
;             }
;             if (!PLAIN) { sq0 += __shfl_xor(sq0, 1); sq0 += __shfl_xor(sq0, 2); sq0 += __shfl_xor(sq0, 4);
;             sq1 += __shfl_xor(sq1, 1); sq1 += __shfl_xor(sq1, 2); sq1 += __shfl_xor(sq1, 4); }
;             if (!PLAIN && pc == 0) { sst[g * 16 + rr] = sq0; sst[g * 16 + 8 + rr] = sq1; }
.LBB0_2819:
	s_or_b64 exec, exec, s[24:25]
	v_lshl_add_u64 v[96:97], s[22:23], 0, v[162:163]
	v_add_u32_e32 v162, 0x140000, v205
	v_add_u32_e32 v92, 0x140080, v205
	v_add_u32_e32 v94, 0x150000, v205
	global_load_dwordx4 v[70:73], v162, s[22:23]
	global_load_dwordx4 v[66:69], v94, s[22:23]
	v_add_u32_e32 v90, 0x150080, v205
	global_load_dwordx4 v[62:65], v92, s[22:23]
	s_waitcnt lgkmcnt(0)
	global_load_dwordx4 v[58:61], v90, s[22:23]
	ds_write_b128 v200, v[46:49]
	ds_write_b128 v200, v[42:45] offset:64
	ds_read_b128 v[42:45], v201
	ds_read_b128 v[46:49], v201 offset:1152
	v_mov_b32_e32 v111, v163
	v_lshl_add_u64 v[98:99], s[22:23], 0, v[110:111]
	v_mov_b32_e32 v109, v163
	s_waitcnt vmcnt(14) lgkmcnt(1)
	v_pk_fma_f32 v[42:43], v[54:55], v[42:43], v[86:87]
	s_waitcnt vmcnt(13) lgkmcnt(0)
	v_pk_fma_f32 v[46:47], v[54:55], v[46:47], v[82:83]
	v_pk_fma_f32 v[44:45], v[56:57], v[44:45], v[88:89]
	v_pk_mul_f32 v[86:87], v[180:181], v[42:43]
	v_pk_fma_f32 v[48:49], v[56:57], v[48:49], v[84:85]
	v_pk_mul_f32 v[82:83], v[180:181], v[46:47]
	global_store_dwordx4 v[96:97], v[42:45], off nt
	v_pk_mul_f32 v[88:89], v[178:179], v[44:45]
	v_cvt_pk_bf16_f32 v86, v86, v87
	v_pk_mul_f32 v[84:85], v[178:179], v[48:49]
	v_cvt_pk_bf16_f32 v87, v88, v89
	global_store_dwordx4 v[98:99], v[46:49], off nt
	v_cvt_pk_bf16_f32 v82, v82, v83
	v_cvt_pk_bf16_f32 v83, v84, v85
	ds_write_b128 v200, v[38:41]
	ds_write_b128 v200, v[34:37] offset:64
	ds_read_b128 v[34:37], v201
	ds_read_b128 v[38:41], v201 offset:1152
	v_lshl_add_u64 v[84:85], s[22:23], 0, v[108:109]
	v_mov_b32_e32 v107, v163
	v_lshl_add_u64 v[88:89], s[22:23], 0, v[106:107]
	s_waitcnt vmcnt(14) lgkmcnt(1)
	v_pk_fma_f32 v[34:35], v[50:51], v[34:35], v[78:79]
	v_pk_fma_f32 v[36:37], v[52:53], v[36:37], v[80:81]
	v_pk_mul_f32 v[80:81], v[176:177], v[34:35]
	global_store_dwordx4 v[84:85], v[34:37], off nt
	v_pk_mul_f32 v[78:79], v[174:175], v[36:37]
	v_cvt_pk_bf16_f32 v80, v80, v81
	s_waitcnt vmcnt(14) lgkmcnt(0)
	v_pk_fma_f32 v[38:39], v[50:51], v[38:39], v[74:75]
	v_cvt_pk_bf16_f32 v81, v78, v79
	ds_bpermute_b32 v74, v203, v80
	ds_bpermute_b32 v75, v203, v81
	v_pk_fma_f32 v[40:41], v[52:53], v[40:41], v[76:77]
	v_pk_mul_f32 v[76:77], v[176:177], v[38:39]
	v_pk_mul_f32 v[78:79], v[174:175], v[40:41]
	global_store_dwordx4 v[88:89], v[38:41], off nt
	v_cvt_pk_bf16_f32 v76, v76, v77
	v_cvt_pk_bf16_f32 v77, v78, v79
	v_add_u32_e32 v79, 0x48000, v202
	v_lshlrev_b32_e32 v78, 1, v79
	s_waitcnt lgkmcnt(0)
	v_add_u32_e32 v250, 0xfffff040, v78
	v_cndmask_b32_e64 v250, v78, v250, s[38:39]
	v_cndmask_b32_e64 v248, v86, v74, s[38:39]
	v_cndmask_b32_e64 v249, v87, v75, s[38:39]
	global_store_dwordx2 v250, v[248:249], s[20:21]
	v_cndmask_b32_e64 v246, v74, v86, s[38:39]
	v_cndmask_b32_e64 v247, v75, v87, s[38:39]
	s_waitcnt lgkmcnt(1)
	v_add_u32_e32 v74, 0x1040, v78
	v_cndmask_b32_e64 v74, v78, v74, s[36:37]
	global_store_dwordx2 v74, v[246:247], s[20:21]
	ds_bpermute_b32 v74, v203, v76
	s_waitcnt lgkmcnt(1)
	ds_bpermute_b32 v75, v203, v77
	v_add_u32_e32 v77, 0x4c000, v202
	v_lshlrev_b32_e32 v76, 1, v77
	s_waitcnt lgkmcnt(0)
	v_add_u32_e32 v250, 0xfffff040, v76
	v_cndmask_b32_e64 v250, v76, v250, s[38:39]
	v_cndmask_b32_e64 v248, v82, v74, s[38:39]
	v_cndmask_b32_e64 v249, v83, v75, s[38:39]
	global_store_dwordx2 v250, v[248:249], s[20:21]
	v_cndmask_b32_e64 v246, v74, v82, s[38:39]
	v_cndmask_b32_e64 v247, v75, v83, s[38:39]
	v_mul_f32_e32 v35, v35, v35
	v_fmac_f32_e32 v35, v34, v34
	v_mul_f32_e32 v34, v37, v37
	v_mul_f32_e32 v45, v45, v45
	v_fmac_f32_e32 v34, v36, v36
	v_mul_f32_e32 v43, v43, v43
	v_fmac_f32_e32 v45, v44, v44
	v_mul_f32_e32 v44, v47, v47
	v_mul_f32_e32 v47, v49, v49
	v_add_f32_e32 v34, v35, v34
	v_mul_f32_e32 v35, v39, v39
	v_mul_f32_e32 v36, v41, v41
	v_fmac_f32_e32 v47, v48, v48
	v_fmac_f32_e32 v35, v38, v38
	v_fmac_f32_e32 v36, v40, v40
	v_fmac_f32_e32 v43, v42, v42
	v_fmac_f32_e32 v44, v46, v46
	v_add_f32_e32 v35, v35, v36
	v_add_f32_e32 v36, v43, v45
	v_add_f32_e32 v37, v44, v47
	v_add_f32_e32 v34, v36, v34
	v_add_f32_e32 v35, v37, v35
	ds_bpermute_b32 v36, v190, v34
	ds_bpermute_b32 v37, v190, v35
	s_waitcnt lgkmcnt(1)
	v_add_f32_e32 v34, v34, v36
	s_waitcnt lgkmcnt(0)
	v_add_f32_e32 v37, v35, v37
	ds_bpermute_b32 v36, v191, v34
	ds_bpermute_b32 v38, v191, v37
	s_waitcnt lgkmcnt(1)
	v_add_f32_e32 v34, v34, v36
	s_waitcnt lgkmcnt(0)
	v_add_f32_e32 v36, v37, v38
	ds_bpermute_b32 v35, v204, v34
	ds_bpermute_b32 v37, v204, v36
	v_add_u32_e32 v38, 0x1040, v76
	v_cndmask_b32_e64 v38, v76, v38, s[36:37]
	global_store_dwordx2 v38, v[246:247], s[20:21]
	s_and_saveexec_b64 s[24:25], s[40:41]
	s_cbranch_execz .LBB0_2829
	s_waitcnt lgkmcnt(1)
	v_add_f32_e32 v34, v34, v35
	s_waitcnt lgkmcnt(0)
	v_add_f32_e32 v35, v36, v37
	ds_write2_b32 v194, v34, v35 offset0:80 offset1:88
; #define LAS __attribute__((address_space(3)))
; #define ERN_EOFF(q, m) (eb + (unsigned)((((q) & 1) * HALF + (m) * 16) * DM + ERN_COL((q) >> 1)))
;     __device__ __forceinline__ void operator()(const f32x4 (&acc)[2][2][4][2], const Unit& u, int wr, int wc, int fr, int fq) const {
;     ...
;         ERN_LOADX(0);
; #pragma unroll
;         for (int g = 0; g < 8; ++g) { const int ai = g >> 2, m = g & 3;
;             if (g + 1 < 8) ERN_LOADX(g + 1);
;             float sq0 = 0.f, sq1 = 0.f; u32x2 hw[2][2];
; #pragma unroll
;             for (int bj = 0; bj < 2; ++bj) {
;                 *(LAS f32x4*)(st + wr_off) = acc[ai][bj][m][0]; *(LAS f32x4*)(st + wr_off + 64) = acc[ai][bj][m][1];
;                 const f32x4 a0 = *(const LAS f32x4*)(st + rd_off), a1 = *(const LAS f32x4*)(st + rd_off + 8 * 144);
;                 { const f32x4 xv = xb[g & 1][bj][0] + gv[bj] * a0; __builtin_nontemporal_store(xv, (f32x4*)((char*)xo + 4u * ERN_EOFF(g, bj, 0)));
;                   sq0 += (xv.x * xv.x + xv.y * xv.y) + (xv.z * xv.z + xv.w * xv.w);
;                   const f32x4 hv = xv * gsn[bj]; hw[bj][0].x = cvt_pk_bf16(hv.x, hv.y); hw[bj][0].y = cvt_pk_bf16(hv.z, hv.w); }
;                 { const f32x4 xv = xb[g & 1][bj][1] + gv[bj] * a1; __builtin_nontemporal_store(xv, (f32x4*)((char*)xo + 4u * ERN_EOFF(g, bj, 1)));
;                   sq1 += (xv.x * xv.x + xv.y * xv.y) + (xv.z * xv.z + xv.w * xv.w);
;                   const f32x4 hv = xv * gsn[bj]; hw[bj][1].x = cvt_pk_bf16(hv.x, hv.y); hw[bj][1].y = cvt_pk_bf16(hv.z, hv.w); }
;             }
;             if (!NOH && !PLAIN) {
; #pragma unroll
;                 for (int rh = 0; rh < 2; ++rh) { u32x2 rv; rv.x = __shfl_xor(hw[1][rh].x, 8); rv.y = __shfl_xor(hw[1][rh].y, 8);
;                     const unsigned e0 = ERN_EOFF(g, 0, rh);
;                     const unsigned ee = odd ? (e0 - DM + 32) : e0, eo2 = odd ? e0 : (e0 + DM + 32);
;                     *(u32x2*)((char*)ho + 2u * ee) = odd ? rv : hw[0][rh];
;                     *(u32x2*)((char*)ho + 2u * eo2) = odd ? hw[0][rh] : rv; }
;             }
;             if (!PLAIN) { sq0 += __shfl_xor(sq0, 1); sq0 += __shfl_xor(sq0, 2); sq0 += __shfl_xor(sq0, 4);
;             sq1 += __shfl_xor(sq1, 1); sq1 += __shfl_xor(sq1, 2); sq1 += __shfl_xor(sq1, 4); }
;             if (!PLAIN && pc == 0) { sst[g * 16 + rr] = sq0; sst[g * 16 + 8 + rr] = sq1; }
.LBB0_2829:
	s_or_b64 exec, exec, s[24:25]
	v_lshl_add_u64 v[80:81], s[22:23], 0, v[162:163]
	v_add_u32_e32 v162, 0x160000, v205
	v_add_u32_e32 v76, 0x160080, v205
	v_add_u32_e32 v78, 0x170000, v205
	global_load_dwordx4 v[46:49], v162, s[22:23]
	global_load_dwordx4 v[42:45], v78, s[22:23]
	v_add_u32_e32 v74, 0x170080, v205
	global_load_dwordx4 v[38:41], v76, s[22:23]
	s_waitcnt lgkmcnt(0)
	global_load_dwordx4 v[34:37], v74, s[22:23]
	ds_write_b128 v200, v[30:33]
	ds_write_b128 v200, v[26:29] offset:64
	ds_read_b128 v[26:29], v201
	ds_read_b128 v[30:33], v201 offset:1152
	v_mov_b32_e32 v95, v163
	v_lshl_add_u64 v[82:83], s[22:23], 0, v[94:95]
	v_mov_b32_e32 v93, v163
	s_waitcnt vmcnt(14) lgkmcnt(1)
	v_pk_fma_f32 v[26:27], v[54:55], v[26:27], v[70:71]
	s_waitcnt vmcnt(13) lgkmcnt(0)
	v_pk_fma_f32 v[30:31], v[54:55], v[30:31], v[66:67]
	v_pk_fma_f32 v[28:29], v[56:57], v[28:29], v[72:73]
	v_pk_mul_f32 v[70:71], v[180:181], v[26:27]
	v_pk_fma_f32 v[32:33], v[56:57], v[32:33], v[68:69]
	v_pk_mul_f32 v[66:67], v[180:181], v[30:31]
	global_store_dwordx4 v[80:81], v[26:29], off nt
	v_pk_mul_f32 v[72:73], v[178:179], v[28:29]
	v_cvt_pk_bf16_f32 v70, v70, v71
	v_pk_mul_f32 v[68:69], v[178:179], v[32:33]
	v_cvt_pk_bf16_f32 v71, v72, v73
	global_store_dwordx4 v[82:83], v[30:33], off nt
	v_cvt_pk_bf16_f32 v66, v66, v67
	v_cvt_pk_bf16_f32 v67, v68, v69
	ds_write_b128 v200, v[22:25]
	ds_write_b128 v200, v[18:21] offset:64
	ds_read_b128 v[18:21], v201
	ds_read_b128 v[22:25], v201 offset:1152
	v_lshl_add_u64 v[68:69], s[22:23], 0, v[92:93]
	v_mov_b32_e32 v91, v163
	v_lshl_add_u64 v[72:73], s[22:23], 0, v[90:91]
	s_waitcnt vmcnt(14) lgkmcnt(1)
	v_pk_fma_f32 v[18:19], v[50:51], v[18:19], v[62:63]
	v_pk_fma_f32 v[20:21], v[52:53], v[20:21], v[64:65]
	v_pk_mul_f32 v[64:65], v[176:177], v[18:19]
	global_store_dwordx4 v[68:69], v[18:21], off nt
	v_pk_mul_f32 v[62:63], v[174:175], v[20:21]
	v_cvt_pk_bf16_f32 v64, v64, v65
	s_waitcnt vmcnt(14) lgkmcnt(0)
	v_pk_fma_f32 v[22:23], v[50:51], v[22:23], v[58:59]
	v_cvt_pk_bf16_f32 v65, v62, v63
	ds_bpermute_b32 v58, v203, v64
	ds_bpermute_b32 v59, v203, v65
	v_pk_fma_f32 v[24:25], v[52:53], v[24:25], v[60:61]
	v_pk_mul_f32 v[60:61], v[176:177], v[22:23]
	v_pk_mul_f32 v[62:63], v[174:175], v[24:25]
	global_store_dwordx4 v[72:73], v[22:25], off nt
	v_cvt_pk_bf16_f32 v60, v60, v61
	v_cvt_pk_bf16_f32 v61, v62, v63
	v_add_u32_e32 v63, 0x50000, v202
	v_lshlrev_b32_e32 v62, 1, v63
	s_waitcnt lgkmcnt(0)
	v_add_u32_e32 v250, 0xfffff040, v62
	v_cndmask_b32_e64 v250, v62, v250, s[38:39]
	v_cndmask_b32_e64 v248, v70, v58, s[38:39]
	v_cndmask_b32_e64 v249, v71, v59, s[38:39]
	global_store_dwordx2 v250, v[248:249], s[20:21]
	v_cndmask_b32_e64 v246, v58, v70, s[38:39]
	v_cndmask_b32_e64 v247, v59, v71, s[38:39]
	s_waitcnt lgkmcnt(1)
	v_add_u32_e32 v58, 0x1040, v62
	v_cndmask_b32_e64 v58, v62, v58, s[36:37]
	global_store_dwordx2 v58, v[246:247], s[20:21]
	ds_bpermute_b32 v58, v203, v60
	s_waitcnt lgkmcnt(1)
	ds_bpermute_b32 v59, v203, v61
	v_add_u32_e32 v61, 0x54000, v202
	v_lshlrev_b32_e32 v60, 1, v61
	s_waitcnt lgkmcnt(0)
	v_add_u32_e32 v250, 0xfffff040, v60
	v_cndmask_b32_e64 v250, v60, v250, s[38:39]
	v_cndmask_b32_e64 v248, v66, v58, s[38:39]
	v_cndmask_b32_e64 v249, v67, v59, s[38:39]
	global_store_dwordx2 v250, v[248:249], s[20:21]
	v_cndmask_b32_e64 v246, v58, v66, s[38:39]
	v_cndmask_b32_e64 v247, v59, v67, s[38:39]
	v_mul_f32_e32 v19, v19, v19
	v_fmac_f32_e32 v19, v18, v18
	v_mul_f32_e32 v18, v21, v21
	v_mul_f32_e32 v29, v29, v29
	v_fmac_f32_e32 v18, v20, v20
	v_mul_f32_e32 v27, v27, v27
	v_fmac_f32_e32 v29, v28, v28
	v_mul_f32_e32 v28, v31, v31
	v_mul_f32_e32 v31, v33, v33
	v_add_f32_e32 v18, v19, v18
	v_mul_f32_e32 v19, v23, v23
	v_mul_f32_e32 v20, v25, v25
	v_fmac_f32_e32 v31, v32, v32
	v_fmac_f32_e32 v19, v22, v22
	v_fmac_f32_e32 v20, v24, v24
	v_fmac_f32_e32 v27, v26, v26
	v_fmac_f32_e32 v28, v30, v30
	v_add_f32_e32 v19, v19, v20
	v_add_f32_e32 v20, v27, v29
	v_add_f32_e32 v21, v28, v31
	v_add_f32_e32 v18, v20, v18
	v_add_f32_e32 v19, v21, v19
	ds_bpermute_b32 v20, v190, v18
	ds_bpermute_b32 v21, v190, v19
	s_waitcnt lgkmcnt(1)
	v_add_f32_e32 v18, v18, v20
	s_waitcnt lgkmcnt(0)
	v_add_f32_e32 v21, v19, v21
	ds_bpermute_b32 v20, v191, v18
	ds_bpermute_b32 v22, v191, v21
	s_waitcnt lgkmcnt(1)
	v_add_f32_e32 v18, v18, v20
	s_waitcnt lgkmcnt(0)
	v_add_f32_e32 v20, v21, v22
	ds_bpermute_b32 v19, v204, v18
	ds_bpermute_b32 v21, v204, v20
	v_add_u32_e32 v22, 0x1040, v60
	v_cndmask_b32_e64 v22, v60, v22, s[36:37]
	global_store_dwordx2 v22, v[246:247], s[20:21]
	s_and_saveexec_b64 s[24:25], s[40:41]
	s_cbranch_execz .LBB0_2839
	s_waitcnt lgkmcnt(1)
	v_add_f32_e32 v18, v18, v19
	s_waitcnt lgkmcnt(0)
	v_add_f32_e32 v19, v20, v21
	ds_write2_b32 v194, v18, v19 offset0:96 offset1:104
; #define LAS __attribute__((address_space(3)))
; #define ERN_EOFF(q, m) (eb + (unsigned)((((q) & 1) * HALF + (m) * 16) * DM + ERN_COL((q) >> 1)))
;     __device__ __forceinline__ void operator()(const f32x4 (&acc)[2][2][4][2], const Unit& u, int wr, int wc, int fr, int fq) const {
;     ...
;         ERN_LOADX(0);
; #pragma unroll
;         for (int g = 0; g < 8; ++g) { const int ai = g >> 2, m = g & 3;
;             if (g + 1 < 8) ERN_LOADX(g + 1);
;             float sq0 = 0.f, sq1 = 0.f; u32x2 hw[2][2];
; #pragma unroll
;             for (int bj = 0; bj < 2; ++bj) {
;                 *(LAS f32x4*)(st + wr_off) = acc[ai][bj][m][0]; *(LAS f32x4*)(st + wr_off + 64) = acc[ai][bj][m][1];
;                 const f32x4 a0 = *(const LAS f32x4*)(st + rd_off), a1 = *(const LAS f32x4*)(st + rd_off + 8 * 144);
;                 { const f32x4 xv = xb[g & 1][bj][0] + gv[bj] * a0; __builtin_nontemporal_store(xv, (f32x4*)((char*)xo + 4u * ERN_EOFF(g, bj, 0)));
;                   sq0 += (xv.x * xv.x + xv.y * xv.y) + (xv.z * xv.z + xv.w * xv.w);
;                   const f32x4 hv = xv * gsn[bj]; hw[bj][0].x = cvt_pk_bf16(hv.x, hv.y); hw[bj][0].y = cvt_pk_bf16(hv.z, hv.w); }
;                 { const f32x4 xv = xb[g & 1][bj][1] + gv[bj] * a1; __builtin_nontemporal_store(xv, (f32x4*)((char*)xo + 4u * ERN_EOFF(g, bj, 1)));
;                   sq1 += (xv.x * xv.x + xv.y * xv.y) + (xv.z * xv.z + xv.w * xv.w);
;                   const f32x4 hv = xv * gsn[bj]; hw[bj][1].x = cvt_pk_bf16(hv.x, hv.y); hw[bj][1].y = cvt_pk_bf16(hv.z, hv.w); }
;             }
;             if (!NOH && !PLAIN) {
; #pragma unroll
;                 for (int rh = 0; rh < 2; ++rh) { u32x2 rv; rv.x = __shfl_xor(hw[1][rh].x, 8); rv.y = __shfl_xor(hw[1][rh].y, 8);
;                     const unsigned e0 = ERN_EOFF(g, 0, rh);
;                     const unsigned ee = odd ? (e0 - DM + 32) : e0, eo2 = odd ? e0 : (e0 + DM + 32);
;                     *(u32x2*)((char*)ho + 2u * ee) = odd ? rv : hw[0][rh];
;                     *(u32x2*)((char*)ho + 2u * eo2) = odd ? hw[0][rh] : rv; }
;             }
;             if (!PLAIN) { sq0 += __shfl_xor(sq0, 1); sq0 += __shfl_xor(sq0, 2); sq0 += __shfl_xor(sq0, 4);
;             sq1 += __shfl_xor(sq1, 1); sq1 += __shfl_xor(sq1, 2); sq1 += __shfl_xor(sq1, 4); }
;             if (!PLAIN && pc == 0) { sst[g * 16 + rr] = sq0; sst[g * 16 + 8 + rr] = sq1; }
.LBB0_2839:
	s_or_b64 exec, exec, s[24:25]
	ds_write_b128 v200, v[14:17]
	ds_write_b128 v200, v[10:13] offset:64
	ds_read_b128 v[10:13], v201
	ds_read_b128 v[14:17], v201 offset:1152
	s_waitcnt lgkmcnt(5)
	v_lshl_add_u64 v[18:19], s[22:23], 0, v[162:163]
	v_mov_b32_e32 v79, v163
	v_lshl_add_u64 v[22:23], s[22:23], 0, v[78:79]
	s_waitcnt vmcnt(10) lgkmcnt(1)
	v_pk_fma_f32 v[12:13], v[56:57], v[12:13], v[48:49]
	v_pk_fma_f32 v[10:11], v[54:55], v[10:11], v[46:47]
	global_store_dwordx4 v[18:19], v[10:13], off nt
	v_pk_mul_f32 v[18:19], v[178:179], v[12:13]
	v_pk_mul_f32 v[20:21], v[180:181], v[10:11]
	s_waitcnt vmcnt(10) lgkmcnt(0)
	v_pk_fma_f32 v[14:15], v[54:55], v[14:15], v[42:43]
	v_cvt_pk_bf16_f32 v20, v20, v21
	v_cvt_pk_bf16_f32 v21, v18, v19
	v_pk_fma_f32 v[16:17], v[56:57], v[16:17], v[44:45]
	v_pk_mul_f32 v[18:19], v[180:181], v[14:15]
	global_store_dwordx4 v[22:23], v[14:17], off nt
	v_pk_mul_f32 v[22:23], v[178:179], v[16:17]
	v_cvt_pk_bf16_f32 v18, v18, v19
	v_mov_b32_e32 v77, v163
	v_cvt_pk_bf16_f32 v19, v22, v23
	ds_write_b128 v200, v[6:9]
	ds_write_b128 v200, v[2:5] offset:64
	ds_read_b128 v[2:5], v201
	ds_read_b128 v[6:9], v201 offset:1152
	v_lshl_add_u64 v[22:23], s[22:23], 0, v[76:77]
	v_mov_b32_e32 v75, v163
	v_lshl_add_u64 v[24:25], s[22:23], 0, v[74:75]
	s_waitcnt vmcnt(10) lgkmcnt(1)
	v_pk_fma_f32 v[4:5], v[52:53], v[4:5], v[40:41]
	v_pk_fma_f32 v[2:3], v[50:51], v[2:3], v[38:39]
	global_store_dwordx4 v[22:23], v[2:5], off nt
	v_pk_mul_f32 v[22:23], v[174:175], v[4:5]
	v_pk_mul_f32 v[26:27], v[176:177], v[2:3]
	s_waitcnt vmcnt(10) lgkmcnt(0)
	v_pk_fma_f32 v[8:9], v[52:53], v[8:9], v[36:37]
	v_cvt_pk_bf16_f32 v28, v26, v27
	v_cvt_pk_bf16_f32 v23, v22, v23
	ds_bpermute_b32 v22, v203, v28
	ds_bpermute_b32 v23, v203, v23
	v_pk_fma_f32 v[6:7], v[50:51], v[6:7], v[34:35]
	global_store_dwordx4 v[24:25], v[6:9], off nt
	v_pk_mul_f32 v[26:27], v[174:175], v[8:9]
	v_pk_mul_f32 v[24:25], v[176:177], v[6:7]
	s_nop 0
	v_cvt_pk_bf16_f32 v24, v24, v25
	v_cvt_pk_bf16_f32 v25, v26, v27
	v_add_u32_e32 v27, 0x58000, v202
	v_lshlrev_b32_e32 v26, 1, v27
	s_waitcnt lgkmcnt(0)
	v_add_u32_e32 v250, 0xfffff040, v26
	v_cndmask_b32_e64 v250, v26, v250, s[38:39]
	v_cndmask_b32_e64 v248, v20, v22, s[38:39]
	v_cndmask_b32_e64 v249, v21, v23, s[38:39]
	global_store_dwordx2 v250, v[248:249], s[20:21]
	v_cndmask_b32_e64 v246, v22, v20, s[38:39]
	v_cndmask_b32_e64 v247, v23, v21, s[38:39]
	s_waitcnt lgkmcnt(1)
	v_add_u32_e32 v22, 0x1040, v26
	v_cndmask_b32_e64 v22, v26, v22, s[36:37]
	global_store_dwordx2 v22, v[246:247], s[20:21]
	ds_bpermute_b32 v20, v203, v24
	ds_bpermute_b32 v21, v203, v25
	s_waitcnt lgkmcnt(2)
	v_add_u32_e32 v23, 0x5c000, v202
	v_lshlrev_b32_e32 v22, 1, v23
	s_waitcnt lgkmcnt(0)
	v_add_u32_e32 v250, 0xfffff040, v22
	v_cndmask_b32_e64 v250, v22, v250, s[38:39]
	v_cndmask_b32_e64 v248, v18, v20, s[38:39]
	v_cndmask_b32_e64 v249, v19, v21, s[38:39]
	global_store_dwordx2 v250, v[248:249], s[20:21]
	v_cndmask_b32_e64 v246, v20, v18, s[38:39]
	v_cndmask_b32_e64 v247, v21, v19, s[38:39]
	v_mul_f32_e32 v3, v3, v3
	v_fmac_f32_e32 v3, v2, v2
	v_mul_f32_e32 v2, v5, v5
	v_mul_f32_e32 v13, v13, v13
	v_fmac_f32_e32 v2, v4, v4
	v_mul_f32_e32 v11, v11, v11
	v_fmac_f32_e32 v13, v12, v12
	v_mul_f32_e32 v12, v15, v15
	v_mul_f32_e32 v15, v17, v17
	v_add_f32_e32 v2, v3, v2
	v_mul_f32_e32 v3, v7, v7
	v_mul_f32_e32 v4, v9, v9
	v_fmac_f32_e32 v15, v16, v16
	v_fmac_f32_e32 v3, v6, v6
	v_fmac_f32_e32 v4, v8, v8
	v_fmac_f32_e32 v11, v10, v10
	v_fmac_f32_e32 v12, v14, v14
	v_add_f32_e32 v3, v3, v4
	v_add_f32_e32 v4, v11, v13
	v_add_f32_e32 v5, v12, v15
	v_add_f32_e32 v2, v4, v2
	v_add_f32_e32 v3, v5, v3
	ds_bpermute_b32 v4, v190, v2
	ds_bpermute_b32 v5, v190, v3
	s_waitcnt lgkmcnt(1)
	v_add_f32_e32 v2, v2, v4
	s_waitcnt lgkmcnt(0)
	v_add_f32_e32 v5, v3, v5
	ds_bpermute_b32 v4, v191, v2
	ds_bpermute_b32 v6, v191, v5
	s_waitcnt lgkmcnt(1)
	v_add_f32_e32 v2, v2, v4
	s_waitcnt lgkmcnt(0)
	v_add_f32_e32 v4, v5, v6
	ds_bpermute_b32 v3, v204, v2
	ds_bpermute_b32 v5, v204, v4
	v_add_u32_e32 v6, 0x1040, v22
	v_cndmask_b32_e64 v6, v22, v6, s[36:37]
	global_store_dwordx2 v6, v[246:247], s[20:21]
	s_and_saveexec_b64 s[20:21], s[40:41]
	s_cbranch_execz .LBB0_2849
	s_waitcnt lgkmcnt(1)
	v_add_f32_e32 v2, v2, v3
	s_waitcnt lgkmcnt(0)
	v_add_f32_e32 v3, v4, v5
	ds_write2_b32 v194, v2, v3 offset0:112 offset1:120
